# attention inner tile loops (sel+window) rewritten by hand: software-pipelined QK/softmax/PV per 32-key block, in-place accumulators, causal/window edge tiles specialised per block; same bf16 MFMA + f3
# speedup vs baseline: 1.2388x; 1.2388x over previous
; template <int MODE>
; __device__ __forceinline__ void attn_tile(const LAS unsigned char* Kb, const LAS unsigned char* Vb, const bf16x8_t (&qf)[4], f32x16 (&oacc)[2], float& l_run,
;                                           int r, int h, int dlt0, int dlt1, bool hiw) {
;     ...
;     for (int mt = 0; mt < 4; ++mt) {
;         if (mt == 0) { if (hiw) __builtin_amdgcn_s_setprio(1); else __builtin_amdgcn_s_setprio(0); }
;         if (mt == 2) { if (hiw) __builtin_amdgcn_s_setprio(0); else __builtin_amdgcn_s_setprio(1); }
;         const int dl = mt < 2 ? dlt0 : dlt1;
;         f32x16 sacc = zero16();
; #pragma unroll
;         for (int ks = 0; ks < 4; ++ks) { const bf16x8_t ka = *(const LAS bf16x8_t*)(Kb + (32 * mt + r) * A_KSTR + 32 * ks + 16 * h); sacc = MFMA32(ka, qf[ks], sacc); }
; #pragma unroll
; __device__ __forceinline__ void phase4_attn(const Args& a, LAS unsigned char* lds) {
;     ...
; #pragma unroll 1
;                 for (int i = 0; i < n_all; ++i) {
;                     const int bufo = i & 1;
;                     if (i + 1 < n_all) A_ISSUE(i + 1);
;                     const LAS unsigned char* Kb = lds + A_KBUF + bufo * A_KT; const LAS unsigned char* Vb = lds + A_VBUF + bufo * A_VT;
;                     const bool issel = i < n_sel;
;                     const int st = issel ? i : wlo + (i - n_sel);
;                     const int dlt = 64 * t + ql - 128 * st - 4 * h;
;                     if (issel) {
;                         const bool b0 = (selw >> (2 * st)) & 1u, b1 = (selw >> (2 * st + 1)) & 1u;
;                         if (__ballot(b0 || b1) != 0ull) {
;                             if (2 * st + 1 < t) {
;                                 if (__ballot(b0 && b1) == ~0ull) attn_tile<2>(Kb, Vb, qf, oacc, l_run, r, h, dlt, dlt, (w & 4) != 0);
;                                 else attn_tile<3>(Kb, Vb, qf, oacc, l_run, r, h, __float_as_int(b0 ? 0.f : -1e30f), __float_as_int(b1 ? 0.f : -1e30f), (w & 4) != 0);
;                             } else attn_tile<0>(Kb, Vb, qf, oacc, l_run, r, h, b0 ? dlt : -1, b1 ? dlt : -1, (w & 4) != 0);
;                         }
;                     } else {
;                         if (2 * st > t - 8 && 2 * st + 1 < t) attn_tile<2>(Kb, Vb, qf, oacc, l_run, r, h, dlt, dlt, (w & 4) != 0);
;                         else attn_tile<1>(Kb, Vb, qf, oacc, l_run, r, h, dlt, dlt, (w & 4) != 0);
;                     }
.LBB0_727:
	v_add_u32_e32 v244, v118, v153
	v_add_u32_e32 v245, v156, v157
	v_add_u32_e32 v245, 0x9000, v245
	v_ashrrev_i32_e32 v239, 3, v152
	v_lshlrev_b32_e32 v240, 4, v152
	v_and_b32_e32 v240, 0x70, v240
	v_mul_u32_u24_e32 v246, 0x90, v239
	v_add_u32_e32 v246, v246, v240
	v_mul_u32_u24_e32 v247, 0x108, v239
	v_add_u32_e32 v247, v247, v240
	v_add_u32_e32 v247, 0x9000, v247
	v_lshlrev_b32_e32 v248, 4, v152
	v_add_u32_e32 v249, 0x2000, v248
	v_and_b32_e32 v250, 31, v152
	v_sub_u32_e32 v250, v250, v155
	v_readfirstlane_b32 s50, v152
	s_bfe_u32 s50, s50, 0x10006
	s_lshl_b32 s0, s38, 1
	s_add_i32 s50, s50, s0
.Lt1_head:
	s_add_i32 s6, s44, 1
	s_add_i32 s7, s91, s44
	s_cmp_lt_i32 s44, s90
	s_cselect_b32 s45, 1, 0
	s_cbranch_scc0 .Lt1_noissue
	s_cmp_lt_u32 s44, s89
	s_cselect_b32 s0, s71, s75
	s_cselect_b32 s1, s72, s76
	s_cselect_b32 s4, s73, s77
	s_cselect_b32 s5, s74, s78
	s_cselect_b32 s6, s6, s7
	s_ashr_i32 s7, s6, 31
	s_lshl_b64 s[6:7], s[6:7], 14
	s_add_u32 s6, s6, s58
	s_addc_u32 s7, s7, s59
	s_add_u32 s0, s0, s6
	s_addc_u32 s1, s1, s7
	s_add_u32 s4, s4, s6
	s_addc_u32 s5, s5, s7
	global_load_dwordx4 v[96:99], v248, s[0:1]
	global_load_dwordx4 v[100:103], v249, s[0:1]
	global_load_dwordx4 v[104:107], v248, s[4:5]
	global_load_dwordx4 v[108:111], v249, s[4:5]
.Lt1_noissue:
	s_and_b32 s46, s44, 1
	s_mul_i32 s0, s46, 0x4800
	s_mul_i32 s1, s46, 0x4200
	v_add_u32_e32 v72, s0, v244
	v_add_u32_e32 v73, s1, v245
	v_add_u32_e32 v74, 0x2000, v73
	s_cmp_gt_u32 s44, s89
	s_cbranch_scc1 .Lt1_win
	s_lshl_b32 s0, s44, 2
	s_sub_i32 s49, s50, s0
	s_lshl_b32 s4, s44, 1
	v_lshrrev_b32_e32 v238, s4, v158
	v_and_b32_e32 v238, 3, v238
	v_cmp_ne_u32_e32 vcc, 0, v238
	s_cmp_eq_u64 vcc, 0
	s_cbranch_scc1 .Lt1_join
	s_cmp_le_i32 s49, 3
	s_cbranch_scc1 .Lt1_diag
	v_cmp_eq_u32_e32 vcc, 3, v238
	s_cmp_eq_u64 vcc, -1
	s_cbranch_scc1 .Lt1_full
	s_mov_b32 s49, s4
	s_branch .Lt1_bias
.Lt1_win:
	s_add_i32 s0, s91, s44
	s_add_i32 s0, s0, -1
	s_lshl_b32 s0, s0, 2
	s_sub_i32 s49, s50, s0
	s_cmp_le_i32 s49, 3
	s_cbranch_scc1 .Lt1_diag
	s_cmp_ge_i32 s49, 16
	s_cbranch_scc0 .Lt1_full
	s_cmp_eq_u32 s49, 16
	s_cbranch_scc1 .Lt1_e0
	s_cmp_eq_u32 s49, 17
	s_cbranch_scc1 .Lt1_e1
	s_cmp_eq_u32 s49, 18
	s_cbranch_scc1 .Lt1_e2
	s_branch .Lt1_e3
.Lt1_diag:
	s_cmp_eq_u32 s49, 0
	s_cbranch_scc1 .Lt1_d0
	s_cmp_eq_u32 s49, 1
	s_cbranch_scc1 .Lt1_d1
	s_cmp_eq_u32 s49, 2
	s_cbranch_scc1 .Lt1_d2
	s_branch .Lt1_d3
.Lt1_full:
	ds_read_b128 v[200:203], v72 offset:0
	ds_read_b128 v[204:207], v72 offset:32
	ds_read_b128 v[208:211], v72 offset:64
	ds_read_b128 v[212:215], v72 offset:96
	ds_read2_b64 v[216:219], v73 offset0:0 offset1:2
	ds_read2_b64 v[220:223], v74 offset0:32 offset1:34
	ds_read2_b64 v[224:227], v73 offset0:4 offset1:6
	ds_read2_b64 v[228:231], v74 offset0:36 offset1:38
	s_waitcnt lgkmcnt(7)
	v_mfma_f32_32x32x16_bf16 v[32:47], v[200:203], v[80:83], 0
	ds_read_b128 v[200:203], v72 offset:4608
	s_waitcnt lgkmcnt(7)
	v_mfma_f32_32x32x16_bf16 v[32:47], v[204:207], v[84:87], v[32:47]
	ds_read_b128 v[204:207], v72 offset:4640
	s_waitcnt lgkmcnt(7)
	v_mfma_f32_32x32x16_bf16 v[32:47], v[208:211], v[88:91], v[32:47]
	ds_read_b128 v[208:211], v72 offset:4672
	s_waitcnt lgkmcnt(7)
	v_mfma_f32_32x32x16_bf16 v[32:47], v[212:215], v[92:95], v[32:47]
	ds_read_b128 v[212:215], v72 offset:4704
	s_nop 7
	s_nop 3
	s_waitcnt lgkmcnt(3)
	v_mfma_f32_32x32x16_bf16 v[48:63], v[200:203], v[80:83], 0
	ds_read_b128 v[200:203], v72 offset:9216
	v_exp_f32_e32 v32, v32
	v_exp_f32_e32 v33, v33
	s_waitcnt lgkmcnt(3)
	v_mfma_f32_32x32x16_bf16 v[48:63], v[204:207], v[84:87], v[48:63]
	ds_read_b128 v[204:207], v72 offset:9248
	v_exp_f32_e32 v34, v34
	v_exp_f32_e32 v35, v35
	v_mov_b32_e32 v232, v32
	v_mov_b32_e32 v233, v33
	v_cvt_pk_bf16_f32 v64, v32, v33
	v_exp_f32_e32 v36, v36
	v_exp_f32_e32 v37, v37
	v_add_f32_e32 v232, v232, v34
	v_add_f32_e32 v233, v233, v35
	v_cvt_pk_bf16_f32 v65, v34, v35
	v_exp_f32_e32 v38, v38
	v_exp_f32_e32 v39, v39
	v_add_f32_e32 v232, v232, v36
	v_add_f32_e32 v233, v233, v37
	v_cvt_pk_bf16_f32 v66, v36, v37
	v_add_f32_e32 v232, v232, v38
	v_add_f32_e32 v233, v233, v39
	v_cvt_pk_bf16_f32 v67, v38, v39
	s_waitcnt lgkmcnt(3)
	v_mfma_f32_32x32x16_bf16 v[48:63], v[208:211], v[88:91], v[48:63]
	ds_read_b128 v[208:211], v72 offset:9280
	v_exp_f32_e32 v40, v40
	v_exp_f32_e32 v41, v41
	s_waitcnt lgkmcnt(3)
	v_mfma_f32_32x32x16_bf16 v[48:63], v[212:215], v[92:95], v[48:63]
	ds_read_b128 v[212:215], v72 offset:9312
	v_exp_f32_e32 v42, v42
	v_exp_f32_e32 v43, v43
	v_add_f32_e32 v232, v232, v40
	v_add_f32_e32 v233, v233, v41
	v_cvt_pk_bf16_f32 v68, v40, v41
	s_waitcnt lgkmcnt(11)
	v_mfma_f32_32x32x16_bf16 v[0:15], v[216:219], v[64:67], v[0:15]
	ds_read2_b64 v[216:219], v73 offset0:8 offset1:10
	v_exp_f32_e32 v44, v44
	v_exp_f32_e32 v45, v45
	v_add_f32_e32 v232, v232, v42
	v_add_f32_e32 v233, v233, v43
	v_cvt_pk_bf16_f32 v69, v42, v43
	s_waitcnt lgkmcnt(11)
	v_mfma_f32_32x32x16_bf16 v[16:31], v[220:223], v[64:67], v[16:31]
	ds_read2_b64 v[220:223], v74 offset0:40 offset1:42
	v_exp_f32_e32 v46, v46
	v_exp_f32_e32 v47, v47
	v_add_f32_e32 v232, v232, v44
	v_add_f32_e32 v233, v233, v45
	v_cvt_pk_bf16_f32 v70, v44, v45
	v_add_f32_e32 v232, v232, v46
	v_add_f32_e32 v233, v233, v47
	v_cvt_pk_bf16_f32 v71, v46, v47
	s_waitcnt lgkmcnt(5)
	v_mfma_f32_32x32x16_bf16 v[32:47], v[200:203], v[80:83], 0
	ds_read_b128 v[200:203], v72 offset:13824
	v_exp_f32_e32 v48, v48
	v_exp_f32_e32 v49, v49
	s_waitcnt lgkmcnt(5)
	v_mfma_f32_32x32x16_bf16 v[32:47], v[204:207], v[84:87], v[32:47]
	ds_read_b128 v[204:207], v72 offset:13856
	v_exp_f32_e32 v50, v50
	v_exp_f32_e32 v51, v51
	v_add_f32_e32 v232, v232, v48
	v_add_f32_e32 v233, v233, v49
	v_cvt_pk_bf16_f32 v64, v48, v49
	s_waitcnt lgkmcnt(13)
; #define LAS __attribute__((address_space(3)))
; #define MFMA32(a, b, c) __builtin_amdgcn_mfma_f32_32x32x16_bf16((a), (b), (c), 0, 0, 0)
; __device__ __forceinline__ float ex2(float x) { return __builtin_amdgcn_exp2f(x); }
; template <int MODE>
; __device__ __forceinline__ void attn_tile(const LAS unsigned char* Kb, const LAS unsigned char* Vb, const bf16x8_t (&qf)[4], f32x16 (&oacc)[2], float& l_run,
;                                           int r, int h, int dlt0, int dlt1, bool hiw) {
;     ...
;     for (int mt = 0; mt < 4; ++mt) {
;         if (mt == 0) { if (hiw) __builtin_amdgcn_s_setprio(1); else __builtin_amdgcn_s_setprio(0); }
;         if (mt == 2) { if (hiw) __builtin_amdgcn_s_setprio(0); else __builtin_amdgcn_s_setprio(1); }
;         const int dl = mt < 2 ? dlt0 : dlt1;
;         f32x16 sacc = zero16();
; #pragma unroll
;         for (int ks = 0; ks < 4; ++ks) { const bf16x8_t ka = *(const LAS bf16x8_t*)(Kb + (32 * mt + r) * A_KSTR + 32 * ks + 16 * h); sacc = MFMA32(ka, qf[ks], sacc); }
; #pragma unroll
;         for (int i = 0; i < 16; ++i) {
;             float p;
;             if (MODE == 2) p = ex2(sacc[i]);
;             else if (MODE == 3) p = ex2(sacc[i] + __int_as_float(dl));
;             else { const int ci = 32 * mt + (i & 3) + 8 * (i >> 2); p = ((unsigned)(dl - ci) < ulim) ? ex2(sacc[i]) : 0.f; }
;             sacc[i] = p; ls += p;
;         }
; #pragma unroll
;         for (int s = 0; s < 2; ++s) {
;             const bf16x8_t pf = pack8(sacc, 8 * s);
; #pragma unroll
;             for (int dt = 0; dt < 2; ++dt) {
;                 const LAS unsigned char* vp = Vb + (32 * dt + r) * A_CVSTR + (32 * mt + 16 * s + 4 * h) * 2;
;                 const s16x4_t lo = *(const LAS s16x4_t*)vp, hi = *(const LAS s16x4_t*)(vp + 16);
;                 oacc[dt] = MFMA32(__builtin_shufflevector(lo, hi, 0, 1, 2, 3, 4, 5, 6, 7), pf, oacc[dt]);
;             }
;         }
;     }
;     l_run += ls;
	v_mfma_f32_32x32x16_bf16 v[0:15], v[224:227], v[68:71], v[0:15]
	ds_read2_b64 v[224:227], v73 offset0:12 offset1:14
	v_exp_f32_e32 v52, v52
	v_exp_f32_e32 v53, v53
	v_add_f32_e32 v232, v232, v50
	v_add_f32_e32 v233, v233, v51
	v_cvt_pk_bf16_f32 v65, v50, v51
	s_waitcnt lgkmcnt(13)
	v_mfma_f32_32x32x16_bf16 v[16:31], v[228:231], v[68:71], v[16:31]
	ds_read2_b64 v[228:231], v74 offset0:44 offset1:46
	v_exp_f32_e32 v54, v54
	v_exp_f32_e32 v55, v55
	v_add_f32_e32 v232, v232, v52
	v_add_f32_e32 v233, v233, v53
	v_cvt_pk_bf16_f32 v66, v52, v53
	v_add_f32_e32 v232, v232, v54
	v_add_f32_e32 v233, v233, v55
	v_cvt_pk_bf16_f32 v67, v54, v55
	s_waitcnt lgkmcnt(7)
	v_mfma_f32_32x32x16_bf16 v[32:47], v[208:211], v[88:91], v[32:47]
	ds_read_b128 v[208:211], v72 offset:13888
	v_exp_f32_e32 v56, v56
	v_exp_f32_e32 v57, v57
	s_waitcnt lgkmcnt(7)
	v_mfma_f32_32x32x16_bf16 v[32:47], v[212:215], v[92:95], v[32:47]
	ds_read_b128 v[212:215], v72 offset:13920
	v_exp_f32_e32 v58, v58
	v_exp_f32_e32 v59, v59
	v_add_f32_e32 v232, v232, v56
	v_add_f32_e32 v233, v233, v57
	v_cvt_pk_bf16_f32 v68, v56, v57
	s_waitcnt lgkmcnt(7)
	v_mfma_f32_32x32x16_bf16 v[0:15], v[216:219], v[64:67], v[0:15]
	ds_read2_b64 v[216:219], v73 offset0:16 offset1:18
	v_exp_f32_e32 v60, v60
	v_exp_f32_e32 v61, v61
	v_add_f32_e32 v232, v232, v58
	v_add_f32_e32 v233, v233, v59
	v_cvt_pk_bf16_f32 v69, v58, v59
	s_waitcnt lgkmcnt(7)
	v_mfma_f32_32x32x16_bf16 v[16:31], v[220:223], v[64:67], v[16:31]
	ds_read2_b64 v[220:223], v74 offset0:48 offset1:50
	v_exp_f32_e32 v62, v62
	v_exp_f32_e32 v63, v63
	v_add_f32_e32 v232, v232, v60
	v_add_f32_e32 v233, v233, v61
	v_cvt_pk_bf16_f32 v70, v60, v61
	v_add_f32_e32 v232, v232, v62
	v_add_f32_e32 v233, v233, v63
	v_cvt_pk_bf16_f32 v71, v62, v63
	s_waitcnt lgkmcnt(7)
	v_mfma_f32_32x32x16_bf16 v[48:63], v[200:203], v[80:83], 0
	v_exp_f32_e32 v32, v32
	v_exp_f32_e32 v33, v33
	s_waitcnt lgkmcnt(6)
	v_mfma_f32_32x32x16_bf16 v[48:63], v[204:207], v[84:87], v[48:63]
	v_exp_f32_e32 v34, v34
	v_exp_f32_e32 v35, v35
	v_add_f32_e32 v232, v232, v32
	v_add_f32_e32 v233, v233, v33
	v_cvt_pk_bf16_f32 v64, v32, v33
	s_waitcnt lgkmcnt(5)
	v_mfma_f32_32x32x16_bf16 v[0:15], v[224:227], v[68:71], v[0:15]
	ds_read2_b64 v[224:227], v73 offset0:20 offset1:22
	v_exp_f32_e32 v36, v36
	v_exp_f32_e32 v37, v37
	v_add_f32_e32 v232, v232, v34
	v_add_f32_e32 v233, v233, v35
	v_cvt_pk_bf16_f32 v65, v34, v35
	s_waitcnt lgkmcnt(5)
	v_mfma_f32_32x32x16_bf16 v[16:31], v[228:231], v[68:71], v[16:31]
	ds_read2_b64 v[228:231], v74 offset0:52 offset1:54
	v_exp_f32_e32 v38, v38
	v_exp_f32_e32 v39, v39
	v_add_f32_e32 v232, v232, v36
	v_add_f32_e32 v233, v233, v37
	v_cvt_pk_bf16_f32 v66, v36, v37
	v_add_f32_e32 v232, v232, v38
	v_add_f32_e32 v233, v233, v39
	v_cvt_pk_bf16_f32 v67, v38, v39
	s_waitcnt lgkmcnt(5)
	v_mfma_f32_32x32x16_bf16 v[48:63], v[208:211], v[88:91], v[48:63]
	v_exp_f32_e32 v40, v40
	v_exp_f32_e32 v41, v41
	s_waitcnt lgkmcnt(4)
	v_mfma_f32_32x32x16_bf16 v[48:63], v[212:215], v[92:95], v[48:63]
	v_exp_f32_e32 v42, v42
	v_exp_f32_e32 v43, v43
	v_add_f32_e32 v232, v232, v40
	v_add_f32_e32 v233, v233, v41
	v_cvt_pk_bf16_f32 v68, v40, v41
	s_waitcnt lgkmcnt(3)
	v_mfma_f32_32x32x16_bf16 v[0:15], v[216:219], v[64:67], v[0:15]
	ds_read2_b64 v[216:219], v73 offset0:24 offset1:26
	v_exp_f32_e32 v44, v44
	v_exp_f32_e32 v45, v45
	v_add_f32_e32 v232, v232, v42
	v_add_f32_e32 v233, v233, v43
	v_cvt_pk_bf16_f32 v69, v42, v43
	s_waitcnt lgkmcnt(3)
	v_mfma_f32_32x32x16_bf16 v[16:31], v[220:223], v[64:67], v[16:31]
	ds_read2_b64 v[220:223], v74 offset0:56 offset1:58
	v_exp_f32_e32 v46, v46
	v_exp_f32_e32 v47, v47
	v_add_f32_e32 v232, v232, v44
	v_add_f32_e32 v233, v233, v45
	v_cvt_pk_bf16_f32 v70, v44, v45
	v_add_f32_e32 v232, v232, v46
	v_add_f32_e32 v233, v233, v47
	v_cvt_pk_bf16_f32 v71, v46, v47
	v_exp_f32_e32 v48, v48
	v_exp_f32_e32 v49, v49
	v_exp_f32_e32 v50, v50
	v_exp_f32_e32 v51, v51
	v_add_f32_e32 v232, v232, v48
	v_add_f32_e32 v233, v233, v49
	v_cvt_pk_bf16_f32 v64, v48, v49
	s_waitcnt lgkmcnt(3)
	v_mfma_f32_32x32x16_bf16 v[0:15], v[224:227], v[68:71], v[0:15]
	ds_read2_b64 v[224:227], v73 offset0:28 offset1:30
	v_exp_f32_e32 v52, v52
	v_exp_f32_e32 v53, v53
	v_add_f32_e32 v232, v232, v50
	v_add_f32_e32 v233, v233, v51
	v_cvt_pk_bf16_f32 v65, v50, v51
	s_waitcnt lgkmcnt(3)
	v_mfma_f32_32x32x16_bf16 v[16:31], v[228:231], v[68:71], v[16:31]
	ds_read2_b64 v[228:231], v74 offset0:60 offset1:62
	v_exp_f32_e32 v54, v54
	v_exp_f32_e32 v55, v55
	v_add_f32_e32 v232, v232, v52
	v_add_f32_e32 v233, v233, v53
	v_cvt_pk_bf16_f32 v66, v52, v53
	v_add_f32_e32 v232, v232, v54
	v_add_f32_e32 v233, v233, v55
	v_cvt_pk_bf16_f32 v67, v54, v55
	v_exp_f32_e32 v56, v56
	v_exp_f32_e32 v57, v57
	v_exp_f32_e32 v58, v58
	v_exp_f32_e32 v59, v59
	v_add_f32_e32 v232, v232, v56
	v_add_f32_e32 v233, v233, v57
	v_cvt_pk_bf16_f32 v68, v56, v57
	s_waitcnt lgkmcnt(3)
	v_mfma_f32_32x32x16_bf16 v[0:15], v[216:219], v[64:67], v[0:15]
	v_exp_f32_e32 v60, v60
	v_exp_f32_e32 v61, v61
	v_add_f32_e32 v232, v232, v58
	v_add_f32_e32 v233, v233, v59
	v_cvt_pk_bf16_f32 v69, v58, v59
	s_waitcnt lgkmcnt(2)
	v_mfma_f32_32x32x16_bf16 v[16:31], v[220:223], v[64:67], v[16:31]
	v_exp_f32_e32 v62, v62
	v_exp_f32_e32 v63, v63
	v_add_f32_e32 v232, v232, v60
	v_add_f32_e32 v233, v233, v61
	v_cvt_pk_bf16_f32 v70, v60, v61
	v_add_f32_e32 v232, v232, v62
	v_add_f32_e32 v233, v233, v63
	v_cvt_pk_bf16_f32 v71, v62, v63
	s_nop 1
	s_waitcnt lgkmcnt(1)
	v_mfma_f32_32x32x16_bf16 v[0:15], v[224:227], v[68:71], v[0:15]
	s_waitcnt lgkmcnt(0)
	v_mfma_f32_32x32x16_bf16 v[16:31], v[228:231], v[68:71], v[16:31]
	v_add_f32_e32 v232, v232, v233
	v_add_f32_e32 v112, v112, v232
	s_branch .Lt1_join
; #define LAS __attribute__((address_space(3)))
; #define MFMA32(a, b, c) __builtin_amdgcn_mfma_f32_32x32x16_bf16((a), (b), (c), 0, 0, 0)
; __device__ __forceinline__ float ex2(float x) { return __builtin_amdgcn_exp2f(x); }
; template <int MODE>
; __device__ __forceinline__ void attn_tile(const LAS unsigned char* Kb, const LAS unsigned char* Vb, const bf16x8_t (&qf)[4], f32x16 (&oacc)[2], float& l_run,
;                                           int r, int h, int dlt0, int dlt1, bool hiw) {
;     ...
;     for (int mt = 0; mt < 4; ++mt) {
;         if (mt == 0) { if (hiw) __builtin_amdgcn_s_setprio(1); else __builtin_amdgcn_s_setprio(0); }
;         if (mt == 2) { if (hiw) __builtin_amdgcn_s_setprio(0); else __builtin_amdgcn_s_setprio(1); }
;         const int dl = mt < 2 ? dlt0 : dlt1;
;         f32x16 sacc = zero16();
; #pragma unroll
;         for (int ks = 0; ks < 4; ++ks) { const bf16x8_t ka = *(const LAS bf16x8_t*)(Kb + (32 * mt + r) * A_KSTR + 32 * ks + 16 * h); sacc = MFMA32(ka, qf[ks], sacc); }
; #pragma unroll
;         for (int i = 0; i < 16; ++i) {
;             float p;
;             if (MODE == 2) p = ex2(sacc[i]);
;             else if (MODE == 3) p = ex2(sacc[i] + __int_as_float(dl));
;             else { const int ci = 32 * mt + (i & 3) + 8 * (i >> 2); p = ((unsigned)(dl - ci) < ulim) ? ex2(sacc[i]) : 0.f; }
;             sacc[i] = p; ls += p;
;         }
; #pragma unroll
;         for (int s = 0; s < 2; ++s) {
;             const bf16x8_t pf = pack8(sacc, 8 * s);
; #pragma unroll
;             for (int dt = 0; dt < 2; ++dt) {
;                 const LAS unsigned char* vp = Vb + (32 * dt + r) * A_CVSTR + (32 * mt + 16 * s + 4 * h) * 2;
;                 const s16x4_t lo = *(const LAS s16x4_t*)vp, hi = *(const LAS s16x4_t*)(vp + 16);
;                 oacc[dt] = MFMA32(__builtin_shufflevector(lo, hi, 0, 1, 2, 3, 4, 5, 6, 7), pf, oacc[dt]);
;             }
;         }
;     }
;     l_run += ls;
; __device__ __forceinline__ void phase4_attn(const Args& a, LAS unsigned char* lds) {
;     ...
;                                 else attn_tile<3>(Kb, Vb, qf, oacc, l_run, r, h, __float_as_int(b0 ? 0.f : -1e30f), __float_as_int(b1 ? 0.f : -1e30f), (w & 4) != 0);
.Lt1_bias:
	ds_read_b128 v[200:203], v72 offset:0
	ds_read_b128 v[204:207], v72 offset:32
	ds_read_b128 v[208:211], v72 offset:64
	ds_read_b128 v[212:215], v72 offset:96
	ds_read2_b64 v[216:219], v73 offset0:0 offset1:2
	ds_read2_b64 v[220:223], v74 offset0:32 offset1:34
	ds_read2_b64 v[224:227], v73 offset0:4 offset1:6
	ds_read2_b64 v[228:231], v74 offset0:36 offset1:38
	v_bfe_i32 v236, v158, s49, 1
	s_add_i32 s49, s49, 1
	v_bfe_i32 v237, v158, s49, 1
	s_waitcnt lgkmcnt(7)
	v_mfma_f32_32x32x16_bf16 v[32:47], v[200:203], v[80:83], 0
	ds_read_b128 v[200:203], v72 offset:4608
	s_waitcnt lgkmcnt(7)
	v_mfma_f32_32x32x16_bf16 v[32:47], v[204:207], v[84:87], v[32:47]
	ds_read_b128 v[204:207], v72 offset:4640
	s_waitcnt lgkmcnt(7)
	v_mfma_f32_32x32x16_bf16 v[32:47], v[208:211], v[88:91], v[32:47]
	ds_read_b128 v[208:211], v72 offset:4672
	s_waitcnt lgkmcnt(7)
	v_mfma_f32_32x32x16_bf16 v[32:47], v[212:215], v[92:95], v[32:47]
	ds_read_b128 v[212:215], v72 offset:4704
	s_nop 7
	s_nop 3
	s_waitcnt lgkmcnt(3)
	v_mfma_f32_32x32x16_bf16 v[48:63], v[200:203], v[80:83], 0
	ds_read_b128 v[200:203], v72 offset:9216
	v_exp_f32_e32 v32, v32
	v_exp_f32_e32 v33, v33
	s_waitcnt lgkmcnt(3)
	v_mfma_f32_32x32x16_bf16 v[48:63], v[204:207], v[84:87], v[48:63]
	ds_read_b128 v[204:207], v72 offset:9248
	v_exp_f32_e32 v34, v34
	v_exp_f32_e32 v35, v35
	v_mov_b32_e32 v232, v32
	v_mov_b32_e32 v233, v33
	v_cvt_pk_bf16_f32 v64, v32, v33
	v_and_b32_e32 v64, v236, v64
	v_exp_f32_e32 v36, v36
	v_exp_f32_e32 v37, v37
	v_add_f32_e32 v232, v232, v34
	v_add_f32_e32 v233, v233, v35
	v_cvt_pk_bf16_f32 v65, v34, v35
	v_and_b32_e32 v65, v236, v65
	v_exp_f32_e32 v38, v38
	v_exp_f32_e32 v39, v39
	v_add_f32_e32 v232, v232, v36
	v_add_f32_e32 v233, v233, v37
	v_cvt_pk_bf16_f32 v66, v36, v37
	v_and_b32_e32 v66, v236, v66
	v_add_f32_e32 v232, v232, v38
	v_add_f32_e32 v233, v233, v39
	v_cvt_pk_bf16_f32 v67, v38, v39
	v_and_b32_e32 v67, v236, v67
	s_waitcnt lgkmcnt(3)
	v_mfma_f32_32x32x16_bf16 v[48:63], v[208:211], v[88:91], v[48:63]
	ds_read_b128 v[208:211], v72 offset:9280
	v_exp_f32_e32 v40, v40
	v_exp_f32_e32 v41, v41
	s_waitcnt lgkmcnt(3)
	v_mfma_f32_32x32x16_bf16 v[48:63], v[212:215], v[92:95], v[48:63]
	ds_read_b128 v[212:215], v72 offset:9312
	v_exp_f32_e32 v42, v42
	v_exp_f32_e32 v43, v43
	v_add_f32_e32 v232, v232, v40
	v_add_f32_e32 v233, v233, v41
	v_cvt_pk_bf16_f32 v68, v40, v41
	v_and_b32_e32 v68, v236, v68
	s_waitcnt lgkmcnt(11)
	v_mfma_f32_32x32x16_bf16 v[0:15], v[216:219], v[64:67], v[0:15]
	ds_read2_b64 v[216:219], v73 offset0:8 offset1:10
	v_exp_f32_e32 v44, v44
	v_exp_f32_e32 v45, v45
	v_add_f32_e32 v232, v232, v42
	v_add_f32_e32 v233, v233, v43
	v_cvt_pk_bf16_f32 v69, v42, v43
	v_and_b32_e32 v69, v236, v69
	s_waitcnt lgkmcnt(11)
	v_mfma_f32_32x32x16_bf16 v[16:31], v[220:223], v[64:67], v[16:31]
	ds_read2_b64 v[220:223], v74 offset0:40 offset1:42
	v_exp_f32_e32 v46, v46
	v_exp_f32_e32 v47, v47
	v_add_f32_e32 v232, v232, v44
	v_add_f32_e32 v233, v233, v45
	v_cvt_pk_bf16_f32 v70, v44, v45
	v_and_b32_e32 v70, v236, v70
	v_add_f32_e32 v232, v232, v46
	v_add_f32_e32 v233, v233, v47
	v_cvt_pk_bf16_f32 v71, v46, v47
	v_and_b32_e32 v71, v236, v71
	s_waitcnt lgkmcnt(5)
	v_mfma_f32_32x32x16_bf16 v[32:47], v[200:203], v[80:83], 0
	ds_read_b128 v[200:203], v72 offset:13824
	v_exp_f32_e32 v48, v48
	v_exp_f32_e32 v49, v49
	s_waitcnt lgkmcnt(5)
	v_mfma_f32_32x32x16_bf16 v[32:47], v[204:207], v[84:87], v[32:47]
	ds_read_b128 v[204:207], v72 offset:13856
	v_exp_f32_e32 v50, v50
	v_exp_f32_e32 v51, v51
	v_add_f32_e32 v232, v232, v48
	v_add_f32_e32 v233, v233, v49
	v_cvt_pk_bf16_f32 v64, v48, v49
	v_and_b32_e32 v64, v236, v64
	s_waitcnt lgkmcnt(13)
	v_mfma_f32_32x32x16_bf16 v[0:15], v[224:227], v[68:71], v[0:15]
	ds_read2_b64 v[224:227], v73 offset0:12 offset1:14
	v_exp_f32_e32 v52, v52
	v_exp_f32_e32 v53, v53
	v_add_f32_e32 v232, v232, v50
	v_add_f32_e32 v233, v233, v51
	v_cvt_pk_bf16_f32 v65, v50, v51
	v_and_b32_e32 v65, v236, v65
	s_waitcnt lgkmcnt(13)
	v_mfma_f32_32x32x16_bf16 v[16:31], v[228:231], v[68:71], v[16:31]
	ds_read2_b64 v[228:231], v74 offset0:44 offset1:46
	v_exp_f32_e32 v54, v54
	v_exp_f32_e32 v55, v55
	v_add_f32_e32 v232, v232, v52
	v_add_f32_e32 v233, v233, v53
	v_cvt_pk_bf16_f32 v66, v52, v53
	v_and_b32_e32 v66, v236, v66
	v_add_f32_e32 v232, v232, v54
	v_add_f32_e32 v233, v233, v55
	v_cvt_pk_bf16_f32 v67, v54, v55
	v_and_b32_e32 v67, v236, v67
	s_waitcnt lgkmcnt(7)
	v_mfma_f32_32x32x16_bf16 v[32:47], v[208:211], v[88:91], v[32:47]
	ds_read_b128 v[208:211], v72 offset:13888
	v_exp_f32_e32 v56, v56
	v_exp_f32_e32 v57, v57
	s_waitcnt lgkmcnt(7)
	v_mfma_f32_32x32x16_bf16 v[32:47], v[212:215], v[92:95], v[32:47]
	ds_read_b128 v[212:215], v72 offset:13920
	v_exp_f32_e32 v58, v58
	v_exp_f32_e32 v59, v59
	v_add_f32_e32 v232, v232, v56
	v_add_f32_e32 v233, v233, v57
	v_cvt_pk_bf16_f32 v68, v56, v57
	v_and_b32_e32 v68, v236, v68
	s_waitcnt lgkmcnt(7)
	v_mfma_f32_32x32x16_bf16 v[0:15], v[216:219], v[64:67], v[0:15]
	ds_read2_b64 v[216:219], v73 offset0:16 offset1:18
	v_exp_f32_e32 v60, v60
	v_exp_f32_e32 v61, v61
	v_add_f32_e32 v232, v232, v58
	v_add_f32_e32 v233, v233, v59
	v_cvt_pk_bf16_f32 v69, v58, v59
	v_and_b32_e32 v69, v236, v69
	s_waitcnt lgkmcnt(7)
	v_mfma_f32_32x32x16_bf16 v[16:31], v[220:223], v[64:67], v[16:31]
	ds_read2_b64 v[220:223], v74 offset0:48 offset1:50
	v_exp_f32_e32 v62, v62
	v_exp_f32_e32 v63, v63
	v_add_f32_e32 v232, v232, v60
	v_add_f32_e32 v233, v233, v61
	v_cvt_pk_bf16_f32 v70, v60, v61
	v_and_b32_e32 v70, v236, v70
	v_add_f32_e32 v232, v232, v62
	v_add_f32_e32 v233, v233, v63
	v_cvt_pk_bf16_f32 v71, v62, v63
	v_and_b32_e32 v71, v236, v71
	s_waitcnt lgkmcnt(7)
; #define LAS __attribute__((address_space(3)))
; #define MFMA32(a, b, c) __builtin_amdgcn_mfma_f32_32x32x16_bf16((a), (b), (c), 0, 0, 0)
; __device__ __forceinline__ float ex2(float x) { return __builtin_amdgcn_exp2f(x); }
; template <int MODE>
; __device__ __forceinline__ void attn_tile(const LAS unsigned char* Kb, const LAS unsigned char* Vb, const bf16x8_t (&qf)[4], f32x16 (&oacc)[2], float& l_run,
;                                           int r, int h, int dlt0, int dlt1, bool hiw) {
;     ...
;     for (int mt = 0; mt < 4; ++mt) {
;         if (mt == 0) { if (hiw) __builtin_amdgcn_s_setprio(1); else __builtin_amdgcn_s_setprio(0); }
;         if (mt == 2) { if (hiw) __builtin_amdgcn_s_setprio(0); else __builtin_amdgcn_s_setprio(1); }
;         const int dl = mt < 2 ? dlt0 : dlt1;
;         f32x16 sacc = zero16();
; #pragma unroll
;         for (int ks = 0; ks < 4; ++ks) { const bf16x8_t ka = *(const LAS bf16x8_t*)(Kb + (32 * mt + r) * A_KSTR + 32 * ks + 16 * h); sacc = MFMA32(ka, qf[ks], sacc); }
; #pragma unroll
;         for (int i = 0; i < 16; ++i) {
;             float p;
;             if (MODE == 2) p = ex2(sacc[i]);
;             else if (MODE == 3) p = ex2(sacc[i] + __int_as_float(dl));
;             else { const int ci = 32 * mt + (i & 3) + 8 * (i >> 2); p = ((unsigned)(dl - ci) < ulim) ? ex2(sacc[i]) : 0.f; }
;             sacc[i] = p; ls += p;
;         }
; #pragma unroll
;         for (int s = 0; s < 2; ++s) {
;             const bf16x8_t pf = pack8(sacc, 8 * s);
; #pragma unroll
;             for (int dt = 0; dt < 2; ++dt) {
;                 const LAS unsigned char* vp = Vb + (32 * dt + r) * A_CVSTR + (32 * mt + 16 * s + 4 * h) * 2;
;                 const s16x4_t lo = *(const LAS s16x4_t*)vp, hi = *(const LAS s16x4_t*)(vp + 16);
;                 oacc[dt] = MFMA32(__builtin_shufflevector(lo, hi, 0, 1, 2, 3, 4, 5, 6, 7), pf, oacc[dt]);
;             }
;         }
;     }
;     l_run += ls;
	v_mfma_f32_32x32x16_bf16 v[48:63], v[200:203], v[80:83], 0
	v_exp_f32_e32 v32, v32
	v_exp_f32_e32 v33, v33
	s_waitcnt lgkmcnt(6)
	v_mfma_f32_32x32x16_bf16 v[48:63], v[204:207], v[84:87], v[48:63]
	v_exp_f32_e32 v34, v34
	v_exp_f32_e32 v35, v35
	v_mov_b32_e32 v234, v32
	v_mov_b32_e32 v235, v33
	v_cvt_pk_bf16_f32 v64, v32, v33
	v_and_b32_e32 v64, v237, v64
	s_waitcnt lgkmcnt(5)
	v_mfma_f32_32x32x16_bf16 v[0:15], v[224:227], v[68:71], v[0:15]
	ds_read2_b64 v[224:227], v73 offset0:20 offset1:22
	v_exp_f32_e32 v36, v36
	v_exp_f32_e32 v37, v37
	v_add_f32_e32 v234, v234, v34
	v_add_f32_e32 v235, v235, v35
	v_cvt_pk_bf16_f32 v65, v34, v35
	v_and_b32_e32 v65, v237, v65
	s_waitcnt lgkmcnt(5)
	v_mfma_f32_32x32x16_bf16 v[16:31], v[228:231], v[68:71], v[16:31]
	ds_read2_b64 v[228:231], v74 offset0:52 offset1:54
	v_exp_f32_e32 v38, v38
	v_exp_f32_e32 v39, v39
	v_add_f32_e32 v234, v234, v36
	v_add_f32_e32 v235, v235, v37
	v_cvt_pk_bf16_f32 v66, v36, v37
	v_and_b32_e32 v66, v237, v66
	v_add_f32_e32 v234, v234, v38
	v_add_f32_e32 v235, v235, v39
	v_cvt_pk_bf16_f32 v67, v38, v39
	v_and_b32_e32 v67, v237, v67
	s_waitcnt lgkmcnt(5)
	v_mfma_f32_32x32x16_bf16 v[48:63], v[208:211], v[88:91], v[48:63]
	v_exp_f32_e32 v40, v40
	v_exp_f32_e32 v41, v41
	s_waitcnt lgkmcnt(4)
	v_mfma_f32_32x32x16_bf16 v[48:63], v[212:215], v[92:95], v[48:63]
	v_exp_f32_e32 v42, v42
	v_exp_f32_e32 v43, v43
	v_add_f32_e32 v234, v234, v40
	v_add_f32_e32 v235, v235, v41
	v_cvt_pk_bf16_f32 v68, v40, v41
	v_and_b32_e32 v68, v237, v68
	s_waitcnt lgkmcnt(3)
	v_mfma_f32_32x32x16_bf16 v[0:15], v[216:219], v[64:67], v[0:15]
	ds_read2_b64 v[216:219], v73 offset0:24 offset1:26
	v_exp_f32_e32 v44, v44
	v_exp_f32_e32 v45, v45
	v_add_f32_e32 v234, v234, v42
	v_add_f32_e32 v235, v235, v43
	v_cvt_pk_bf16_f32 v69, v42, v43
	v_and_b32_e32 v69, v237, v69
	s_waitcnt lgkmcnt(3)
	v_mfma_f32_32x32x16_bf16 v[16:31], v[220:223], v[64:67], v[16:31]
	ds_read2_b64 v[220:223], v74 offset0:56 offset1:58
	v_exp_f32_e32 v46, v46
	v_exp_f32_e32 v47, v47
	v_add_f32_e32 v234, v234, v44
	v_add_f32_e32 v235, v235, v45
	v_cvt_pk_bf16_f32 v70, v44, v45
	v_and_b32_e32 v70, v237, v70
	v_add_f32_e32 v234, v234, v46
	v_add_f32_e32 v235, v235, v47
	v_cvt_pk_bf16_f32 v71, v46, v47
	v_and_b32_e32 v71, v237, v71
	v_exp_f32_e32 v48, v48
	v_exp_f32_e32 v49, v49
	v_exp_f32_e32 v50, v50
	v_exp_f32_e32 v51, v51
	v_add_f32_e32 v234, v234, v48
	v_add_f32_e32 v235, v235, v49
	v_cvt_pk_bf16_f32 v64, v48, v49
	v_and_b32_e32 v64, v237, v64
	s_waitcnt lgkmcnt(3)
	v_mfma_f32_32x32x16_bf16 v[0:15], v[224:227], v[68:71], v[0:15]
	ds_read2_b64 v[224:227], v73 offset0:28 offset1:30
	v_exp_f32_e32 v52, v52
	v_exp_f32_e32 v53, v53
	v_add_f32_e32 v234, v234, v50
	v_add_f32_e32 v235, v235, v51
	v_cvt_pk_bf16_f32 v65, v50, v51
	v_and_b32_e32 v65, v237, v65
	s_waitcnt lgkmcnt(3)
	v_mfma_f32_32x32x16_bf16 v[16:31], v[228:231], v[68:71], v[16:31]
	ds_read2_b64 v[228:231], v74 offset0:60 offset1:62
	v_exp_f32_e32 v54, v54
	v_exp_f32_e32 v55, v55
	v_add_f32_e32 v234, v234, v52
	v_add_f32_e32 v235, v235, v53
	v_cvt_pk_bf16_f32 v66, v52, v53
	v_and_b32_e32 v66, v237, v66
	v_add_f32_e32 v234, v234, v54
	v_add_f32_e32 v235, v235, v55
	v_cvt_pk_bf16_f32 v67, v54, v55
	v_and_b32_e32 v67, v237, v67
	v_exp_f32_e32 v56, v56
	v_exp_f32_e32 v57, v57
	v_exp_f32_e32 v58, v58
	v_exp_f32_e32 v59, v59
	v_add_f32_e32 v234, v234, v56
	v_add_f32_e32 v235, v235, v57
	v_cvt_pk_bf16_f32 v68, v56, v57
	v_and_b32_e32 v68, v237, v68
	s_waitcnt lgkmcnt(3)
	v_mfma_f32_32x32x16_bf16 v[0:15], v[216:219], v[64:67], v[0:15]
	v_exp_f32_e32 v60, v60
	v_exp_f32_e32 v61, v61
	v_add_f32_e32 v234, v234, v58
	v_add_f32_e32 v235, v235, v59
	v_cvt_pk_bf16_f32 v69, v58, v59
	v_and_b32_e32 v69, v237, v69
	s_waitcnt lgkmcnt(2)
	v_mfma_f32_32x32x16_bf16 v[16:31], v[220:223], v[64:67], v[16:31]
	v_exp_f32_e32 v62, v62
	v_exp_f32_e32 v63, v63
	v_add_f32_e32 v234, v234, v60
	v_add_f32_e32 v235, v235, v61
	v_cvt_pk_bf16_f32 v70, v60, v61
	v_and_b32_e32 v70, v237, v70
	v_add_f32_e32 v234, v234, v62
	v_add_f32_e32 v235, v235, v63
	v_cvt_pk_bf16_f32 v71, v62, v63
	v_and_b32_e32 v71, v237, v71
	s_nop 1
	s_waitcnt lgkmcnt(1)
	v_mfma_f32_32x32x16_bf16 v[0:15], v[224:227], v[68:71], v[0:15]
	s_waitcnt lgkmcnt(0)
	v_mfma_f32_32x32x16_bf16 v[16:31], v[228:231], v[68:71], v[16:31]
	v_add_f32_e32 v232, v232, v233
	v_add_f32_e32 v234, v234, v235
	v_and_b32_e32 v239, 1.0, v236
	v_and_b32_e32 v240, 1.0, v237
	v_fmac_f32_e32 v112, v232, v239
	v_fmac_f32_e32 v112, v234, v240
	s_branch .Lt1_join
; #define LAS __attribute__((address_space(3)))
; #define MFMA32(a, b, c) __builtin_amdgcn_mfma_f32_32x32x16_bf16((a), (b), (c), 0, 0, 0)
; __device__ __forceinline__ float ex2(float x) { return __builtin_amdgcn_exp2f(x); }
; template <int MODE>
; __device__ __forceinline__ void attn_tile(const LAS unsigned char* Kb, const LAS unsigned char* Vb, const bf16x8_t (&qf)[4], f32x16 (&oacc)[2], float& l_run,
;                                           int r, int h, int dlt0, int dlt1, bool hiw) {
;     ...
;     for (int mt = 0; mt < 4; ++mt) {
;         if (mt == 0) { if (hiw) __builtin_amdgcn_s_setprio(1); else __builtin_amdgcn_s_setprio(0); }
;         if (mt == 2) { if (hiw) __builtin_amdgcn_s_setprio(0); else __builtin_amdgcn_s_setprio(1); }
;         const int dl = mt < 2 ? dlt0 : dlt1;
;         f32x16 sacc = zero16();
; #pragma unroll
;         for (int ks = 0; ks < 4; ++ks) { const bf16x8_t ka = *(const LAS bf16x8_t*)(Kb + (32 * mt + r) * A_KSTR + 32 * ks + 16 * h); sacc = MFMA32(ka, qf[ks], sacc); }
; #pragma unroll
;         for (int i = 0; i < 16; ++i) {
;             float p;
;             if (MODE == 2) p = ex2(sacc[i]);
;             else if (MODE == 3) p = ex2(sacc[i] + __int_as_float(dl));
;             else { const int ci = 32 * mt + (i & 3) + 8 * (i >> 2); p = ((unsigned)(dl - ci) < ulim) ? ex2(sacc[i]) : 0.f; }
;             sacc[i] = p; ls += p;
;         }
; #pragma unroll
;         for (int s = 0; s < 2; ++s) {
;             const bf16x8_t pf = pack8(sacc, 8 * s);
; #pragma unroll
;             for (int dt = 0; dt < 2; ++dt) {
;                 const LAS unsigned char* vp = Vb + (32 * dt + r) * A_CVSTR + (32 * mt + 16 * s + 4 * h) * 2;
;                 const s16x4_t lo = *(const LAS s16x4_t*)vp, hi = *(const LAS s16x4_t*)(vp + 16);
;                 oacc[dt] = MFMA32(__builtin_shufflevector(lo, hi, 0, 1, 2, 3, 4, 5, 6, 7), pf, oacc[dt]);
;             }
;         }
;     }
;     l_run += ls;
.Lt1_d0:
	ds_read_b128 v[200:203], v72 offset:0
	ds_read_b128 v[204:207], v72 offset:32
	ds_read_b128 v[208:211], v72 offset:64
	ds_read_b128 v[212:215], v72 offset:96
	ds_read2_b64 v[216:219], v73 offset0:0 offset1:2
	ds_read2_b64 v[220:223], v74 offset0:32 offset1:34
	ds_read2_b64 v[224:227], v73 offset0:4 offset1:6
	ds_read2_b64 v[228:231], v74 offset0:36 offset1:38
	s_waitcnt lgkmcnt(7)
	v_mfma_f32_32x32x16_bf16 v[32:47], v[200:203], v[80:83], 0
	s_waitcnt lgkmcnt(6)
	v_mfma_f32_32x32x16_bf16 v[32:47], v[204:207], v[84:87], v[32:47]
	s_waitcnt lgkmcnt(5)
	v_mfma_f32_32x32x16_bf16 v[32:47], v[208:211], v[88:91], v[32:47]
	s_waitcnt lgkmcnt(4)
	v_mfma_f32_32x32x16_bf16 v[32:47], v[212:215], v[92:95], v[32:47]
	s_nop 7
	s_nop 3
	v_cmp_le_i32_e64 s[0:1], 0, v250
	v_cmp_le_i32_e64 s[4:5], 1, v250
	v_exp_f32_e32 v32, v32
	v_exp_f32_e32 v33, v33
	v_cmp_le_i32_e64 s[6:7], 2, v250
	v_cmp_le_i32_e64 s[48:49], 3, v250
	v_exp_f32_e32 v34, v34
	v_exp_f32_e32 v35, v35
	v_cndmask_b32_e64 v32, 0, v32, s[0:1]
	v_cndmask_b32_e64 v33, 0, v33, s[4:5]
	v_mov_b32_e32 v232, v32
	v_mov_b32_e32 v233, v33
	v_cvt_pk_bf16_f32 v64, v32, v33
	v_cmp_le_i32_e64 s[0:1], 8, v250
	v_cmp_le_i32_e64 s[4:5], 9, v250
	v_exp_f32_e32 v36, v36
	v_exp_f32_e32 v37, v37
	v_cndmask_b32_e64 v34, 0, v34, s[6:7]
	v_cndmask_b32_e64 v35, 0, v35, s[48:49]
	v_add_f32_e32 v232, v232, v34
	v_add_f32_e32 v233, v233, v35
	v_cvt_pk_bf16_f32 v65, v34, v35
	v_cmp_le_i32_e64 s[6:7], 10, v250
	v_cmp_le_i32_e64 s[48:49], 11, v250
	v_exp_f32_e32 v38, v38
	v_exp_f32_e32 v39, v39
	v_cndmask_b32_e64 v36, 0, v36, s[0:1]
	v_cndmask_b32_e64 v37, 0, v37, s[4:5]
	v_add_f32_e32 v232, v232, v36
	v_add_f32_e32 v233, v233, v37
	v_cvt_pk_bf16_f32 v66, v36, v37
	v_cndmask_b32_e64 v38, 0, v38, s[6:7]
	v_cndmask_b32_e64 v39, 0, v39, s[48:49]
	v_add_f32_e32 v232, v232, v38
	v_add_f32_e32 v233, v233, v39
	v_cvt_pk_bf16_f32 v67, v38, v39
	v_cmp_le_i32_e64 s[0:1], 16, v250
	v_cmp_le_i32_e64 s[4:5], 17, v250
	v_exp_f32_e32 v40, v40
	v_exp_f32_e32 v41, v41
	v_cmp_le_i32_e64 s[6:7], 18, v250
	v_cmp_le_i32_e64 s[48:49], 19, v250
	v_exp_f32_e32 v42, v42
	v_exp_f32_e32 v43, v43
	v_cndmask_b32_e64 v40, 0, v40, s[0:1]
	v_cndmask_b32_e64 v41, 0, v41, s[4:5]
	v_add_f32_e32 v232, v232, v40
	v_add_f32_e32 v233, v233, v41
	v_cvt_pk_bf16_f32 v68, v40, v41
	s_waitcnt lgkmcnt(3)
	v_mfma_f32_32x32x16_bf16 v[0:15], v[216:219], v[64:67], v[0:15]
	v_cmp_le_i32_e64 s[0:1], 24, v250
	v_cmp_le_i32_e64 s[4:5], 25, v250
	v_exp_f32_e32 v44, v44
	v_exp_f32_e32 v45, v45
	v_cndmask_b32_e64 v42, 0, v42, s[6:7]
	v_cndmask_b32_e64 v43, 0, v43, s[48:49]
	v_add_f32_e32 v232, v232, v42
	v_add_f32_e32 v233, v233, v43
	v_cvt_pk_bf16_f32 v69, v42, v43
	s_waitcnt lgkmcnt(2)
	v_mfma_f32_32x32x16_bf16 v[16:31], v[220:223], v[64:67], v[16:31]
	v_cmp_le_i32_e64 s[6:7], 26, v250
	v_cmp_le_i32_e64 s[48:49], 27, v250
	v_exp_f32_e32 v46, v46
	v_exp_f32_e32 v47, v47
	v_cndmask_b32_e64 v44, 0, v44, s[0:1]
	v_cndmask_b32_e64 v45, 0, v45, s[4:5]
	v_add_f32_e32 v232, v232, v44
	v_add_f32_e32 v233, v233, v45
	v_cvt_pk_bf16_f32 v70, v44, v45
	v_cndmask_b32_e64 v46, 0, v46, s[6:7]
	v_cndmask_b32_e64 v47, 0, v47, s[48:49]
	v_add_f32_e32 v232, v232, v46
	v_add_f32_e32 v233, v233, v47
	v_cvt_pk_bf16_f32 v71, v46, v47
	s_nop 1
	s_waitcnt lgkmcnt(1)
	v_mfma_f32_32x32x16_bf16 v[0:15], v[224:227], v[68:71], v[0:15]
	s_waitcnt lgkmcnt(0)
	v_mfma_f32_32x32x16_bf16 v[16:31], v[228:231], v[68:71], v[16:31]
	v_add_f32_e32 v232, v232, v233
	v_add_f32_e32 v112, v112, v232
	s_branch .Lt1_join
.Lt1_d1:
	ds_read_b128 v[200:203], v72 offset:0
	ds_read_b128 v[204:207], v72 offset:32
	ds_read_b128 v[208:211], v72 offset:64
	ds_read_b128 v[212:215], v72 offset:96
	ds_read2_b64 v[216:219], v73 offset0:0 offset1:2
	ds_read2_b64 v[220:223], v74 offset0:32 offset1:34
	ds_read2_b64 v[224:227], v73 offset0:4 offset1:6
	ds_read2_b64 v[228:231], v74 offset0:36 offset1:38
	s_waitcnt lgkmcnt(7)
	v_mfma_f32_32x32x16_bf16 v[32:47], v[200:203], v[80:83], 0
	ds_read_b128 v[200:203], v72 offset:4608
	s_waitcnt lgkmcnt(7)
	v_mfma_f32_32x32x16_bf16 v[32:47], v[204:207], v[84:87], v[32:47]
	ds_read_b128 v[204:207], v72 offset:4640
	s_waitcnt lgkmcnt(7)
	v_mfma_f32_32x32x16_bf16 v[32:47], v[208:211], v[88:91], v[32:47]
	ds_read_b128 v[208:211], v72 offset:4672
	s_waitcnt lgkmcnt(7)
	v_mfma_f32_32x32x16_bf16 v[32:47], v[212:215], v[92:95], v[32:47]
	ds_read_b128 v[212:215], v72 offset:4704
	s_nop 7
	s_nop 3
	s_waitcnt lgkmcnt(3)
	v_mfma_f32_32x32x16_bf16 v[48:63], v[200:203], v[80:83], 0
	v_exp_f32_e32 v32, v32
	v_exp_f32_e32 v33, v33
	s_waitcnt lgkmcnt(2)
	v_mfma_f32_32x32x16_bf16 v[48:63], v[204:207], v[84:87], v[48:63]
	v_exp_f32_e32 v34, v34
	v_exp_f32_e32 v35, v35
	v_mov_b32_e32 v232, v32
	v_mov_b32_e32 v233, v33
	v_cvt_pk_bf16_f32 v64, v32, v33
	v_exp_f32_e32 v36, v36
	v_exp_f32_e32 v37, v37
	v_add_f32_e32 v232, v232, v34
	v_add_f32_e32 v233, v233, v35
	v_cvt_pk_bf16_f32 v65, v34, v35
	v_exp_f32_e32 v38, v38
	v_exp_f32_e32 v39, v39
	v_add_f32_e32 v232, v232, v36
	v_add_f32_e32 v233, v233, v37
	v_cvt_pk_bf16_f32 v66, v36, v37
	v_add_f32_e32 v232, v232, v38
	v_add_f32_e32 v233, v233, v39
	v_cvt_pk_bf16_f32 v67, v38, v39
	s_waitcnt lgkmcnt(1)
	v_mfma_f32_32x32x16_bf16 v[48:63], v[208:211], v[88:91], v[48:63]
	v_exp_f32_e32 v40, v40
	v_exp_f32_e32 v41, v41
	s_waitcnt lgkmcnt(0)
	v_mfma_f32_32x32x16_bf16 v[48:63], v[212:215], v[92:95], v[48:63]
	v_exp_f32_e32 v42, v42
	v_exp_f32_e32 v43, v43
	v_add_f32_e32 v232, v232, v40
	v_add_f32_e32 v233, v233, v41
	v_cvt_pk_bf16_f32 v68, v40, v41
	s_waitcnt lgkmcnt(7)
; #define LAS __attribute__((address_space(3)))
; #define MFMA32(a, b, c) __builtin_amdgcn_mfma_f32_32x32x16_bf16((a), (b), (c), 0, 0, 0)
; __device__ __forceinline__ float ex2(float x) { return __builtin_amdgcn_exp2f(x); }
; template <int MODE>
; __device__ __forceinline__ void attn_tile(const LAS unsigned char* Kb, const LAS unsigned char* Vb, const bf16x8_t (&qf)[4], f32x16 (&oacc)[2], float& l_run,
;                                           int r, int h, int dlt0, int dlt1, bool hiw) {
;     ...
;     for (int mt = 0; mt < 4; ++mt) {
;         if (mt == 0) { if (hiw) __builtin_amdgcn_s_setprio(1); else __builtin_amdgcn_s_setprio(0); }
;         if (mt == 2) { if (hiw) __builtin_amdgcn_s_setprio(0); else __builtin_amdgcn_s_setprio(1); }
;         const int dl = mt < 2 ? dlt0 : dlt1;
;         f32x16 sacc = zero16();
; #pragma unroll
;         for (int ks = 0; ks < 4; ++ks) { const bf16x8_t ka = *(const LAS bf16x8_t*)(Kb + (32 * mt + r) * A_KSTR + 32 * ks + 16 * h); sacc = MFMA32(ka, qf[ks], sacc); }
; #pragma unroll
;         for (int i = 0; i < 16; ++i) {
;             float p;
;             if (MODE == 2) p = ex2(sacc[i]);
;             else if (MODE == 3) p = ex2(sacc[i] + __int_as_float(dl));
;             else { const int ci = 32 * mt + (i & 3) + 8 * (i >> 2); p = ((unsigned)(dl - ci) < ulim) ? ex2(sacc[i]) : 0.f; }
;             sacc[i] = p; ls += p;
;         }
; #pragma unroll
;         for (int s = 0; s < 2; ++s) {
;             const bf16x8_t pf = pack8(sacc, 8 * s);
; #pragma unroll
;             for (int dt = 0; dt < 2; ++dt) {
;                 const LAS unsigned char* vp = Vb + (32 * dt + r) * A_CVSTR + (32 * mt + 16 * s + 4 * h) * 2;
;                 const s16x4_t lo = *(const LAS s16x4_t*)vp, hi = *(const LAS s16x4_t*)(vp + 16);
;                 oacc[dt] = MFMA32(__builtin_shufflevector(lo, hi, 0, 1, 2, 3, 4, 5, 6, 7), pf, oacc[dt]);
;             }
;         }
;     }
;     l_run += ls;
	v_mfma_f32_32x32x16_bf16 v[0:15], v[216:219], v[64:67], v[0:15]
	ds_read2_b64 v[216:219], v73 offset0:8 offset1:10
	v_exp_f32_e32 v44, v44
	v_exp_f32_e32 v45, v45
	v_add_f32_e32 v232, v232, v42
	v_add_f32_e32 v233, v233, v43
	v_cvt_pk_bf16_f32 v69, v42, v43
	s_waitcnt lgkmcnt(7)
	v_mfma_f32_32x32x16_bf16 v[16:31], v[220:223], v[64:67], v[16:31]
	ds_read2_b64 v[220:223], v74 offset0:40 offset1:42
	v_exp_f32_e32 v46, v46
	v_exp_f32_e32 v47, v47
	v_add_f32_e32 v232, v232, v44
	v_add_f32_e32 v233, v233, v45
	v_cvt_pk_bf16_f32 v70, v44, v45
	v_add_f32_e32 v232, v232, v46
	v_add_f32_e32 v233, v233, v47
	v_cvt_pk_bf16_f32 v71, v46, v47
	v_cmp_le_i32_e64 s[0:1], 0, v250
	v_cmp_le_i32_e64 s[4:5], 1, v250
	v_exp_f32_e32 v48, v48
	v_exp_f32_e32 v49, v49
	v_cmp_le_i32_e64 s[6:7], 2, v250
	v_cmp_le_i32_e64 s[48:49], 3, v250
	v_exp_f32_e32 v50, v50
	v_exp_f32_e32 v51, v51
	v_cndmask_b32_e64 v48, 0, v48, s[0:1]
	v_cndmask_b32_e64 v49, 0, v49, s[4:5]
	v_add_f32_e32 v232, v232, v48
	v_add_f32_e32 v233, v233, v49
	v_cvt_pk_bf16_f32 v64, v48, v49
	s_waitcnt lgkmcnt(7)
	v_mfma_f32_32x32x16_bf16 v[0:15], v[224:227], v[68:71], v[0:15]
	ds_read2_b64 v[224:227], v73 offset0:12 offset1:14
	v_cmp_le_i32_e64 s[0:1], 8, v250
	v_cmp_le_i32_e64 s[4:5], 9, v250
	v_exp_f32_e32 v52, v52
	v_exp_f32_e32 v53, v53
	v_cndmask_b32_e64 v50, 0, v50, s[6:7]
	v_cndmask_b32_e64 v51, 0, v51, s[48:49]
	v_add_f32_e32 v232, v232, v50
	v_add_f32_e32 v233, v233, v51
	v_cvt_pk_bf16_f32 v65, v50, v51
	s_waitcnt lgkmcnt(7)
	v_mfma_f32_32x32x16_bf16 v[16:31], v[228:231], v[68:71], v[16:31]
	ds_read2_b64 v[228:231], v74 offset0:44 offset1:46
	v_cmp_le_i32_e64 s[6:7], 10, v250
	v_cmp_le_i32_e64 s[48:49], 11, v250
	v_exp_f32_e32 v54, v54
	v_exp_f32_e32 v55, v55
	v_cndmask_b32_e64 v52, 0, v52, s[0:1]
	v_cndmask_b32_e64 v53, 0, v53, s[4:5]
	v_add_f32_e32 v232, v232, v52
	v_add_f32_e32 v233, v233, v53
	v_cvt_pk_bf16_f32 v66, v52, v53
	v_cndmask_b32_e64 v54, 0, v54, s[6:7]
	v_cndmask_b32_e64 v55, 0, v55, s[48:49]
	v_add_f32_e32 v232, v232, v54
	v_add_f32_e32 v233, v233, v55
	v_cvt_pk_bf16_f32 v67, v54, v55
	v_cmp_le_i32_e64 s[0:1], 16, v250
	v_cmp_le_i32_e64 s[4:5], 17, v250
	v_exp_f32_e32 v56, v56
	v_exp_f32_e32 v57, v57
	v_cmp_le_i32_e64 s[6:7], 18, v250
	v_cmp_le_i32_e64 s[48:49], 19, v250
	v_exp_f32_e32 v58, v58
	v_exp_f32_e32 v59, v59
	v_cndmask_b32_e64 v56, 0, v56, s[0:1]
	v_cndmask_b32_e64 v57, 0, v57, s[4:5]
	v_add_f32_e32 v232, v232, v56
	v_add_f32_e32 v233, v233, v57
	v_cvt_pk_bf16_f32 v68, v56, v57
	s_waitcnt lgkmcnt(3)
	v_mfma_f32_32x32x16_bf16 v[0:15], v[216:219], v[64:67], v[0:15]
	v_cmp_le_i32_e64 s[0:1], 24, v250
	v_cmp_le_i32_e64 s[4:5], 25, v250
	v_exp_f32_e32 v60, v60
	v_exp_f32_e32 v61, v61
	v_cndmask_b32_e64 v58, 0, v58, s[6:7]
	v_cndmask_b32_e64 v59, 0, v59, s[48:49]
	v_add_f32_e32 v232, v232, v58
	v_add_f32_e32 v233, v233, v59
	v_cvt_pk_bf16_f32 v69, v58, v59
	s_waitcnt lgkmcnt(2)
	v_mfma_f32_32x32x16_bf16 v[16:31], v[220:223], v[64:67], v[16:31]
	v_cmp_le_i32_e64 s[6:7], 26, v250
	v_cmp_le_i32_e64 s[48:49], 27, v250
	v_exp_f32_e32 v62, v62
	v_exp_f32_e32 v63, v63
	v_cndmask_b32_e64 v60, 0, v60, s[0:1]
	v_cndmask_b32_e64 v61, 0, v61, s[4:5]
	v_add_f32_e32 v232, v232, v60
	v_add_f32_e32 v233, v233, v61
	v_cvt_pk_bf16_f32 v70, v60, v61
	v_cndmask_b32_e64 v62, 0, v62, s[6:7]
	v_cndmask_b32_e64 v63, 0, v63, s[48:49]
	v_add_f32_e32 v232, v232, v62
	v_add_f32_e32 v233, v233, v63
	v_cvt_pk_bf16_f32 v71, v62, v63
	s_nop 1
	s_waitcnt lgkmcnt(1)
	v_mfma_f32_32x32x16_bf16 v[0:15], v[224:227], v[68:71], v[0:15]
	s_waitcnt lgkmcnt(0)
	v_mfma_f32_32x32x16_bf16 v[16:31], v[228:231], v[68:71], v[16:31]
	v_add_f32_e32 v232, v232, v233
	v_add_f32_e32 v112, v112, v232
	s_branch .Lt1_join
.Lt1_d2:
	ds_read_b128 v[200:203], v72 offset:0
	ds_read_b128 v[204:207], v72 offset:32
	ds_read_b128 v[208:211], v72 offset:64
	ds_read_b128 v[212:215], v72 offset:96
	ds_read2_b64 v[216:219], v73 offset0:0 offset1:2
	ds_read2_b64 v[220:223], v74 offset0:32 offset1:34
	ds_read2_b64 v[224:227], v73 offset0:4 offset1:6
	ds_read2_b64 v[228:231], v74 offset0:36 offset1:38
	s_waitcnt lgkmcnt(7)
	v_mfma_f32_32x32x16_bf16 v[32:47], v[200:203], v[80:83], 0
	ds_read_b128 v[200:203], v72 offset:4608
	s_waitcnt lgkmcnt(7)
	v_mfma_f32_32x32x16_bf16 v[32:47], v[204:207], v[84:87], v[32:47]
	ds_read_b128 v[204:207], v72 offset:4640
	s_waitcnt lgkmcnt(7)
	v_mfma_f32_32x32x16_bf16 v[32:47], v[208:211], v[88:91], v[32:47]
	ds_read_b128 v[208:211], v72 offset:4672
	s_waitcnt lgkmcnt(7)
	v_mfma_f32_32x32x16_bf16 v[32:47], v[212:215], v[92:95], v[32:47]
	ds_read_b128 v[212:215], v72 offset:4704
	s_nop 7
	s_nop 3
	s_waitcnt lgkmcnt(3)
	v_mfma_f32_32x32x16_bf16 v[48:63], v[200:203], v[80:83], 0
	ds_read_b128 v[200:203], v72 offset:9216
	v_exp_f32_e32 v32, v32
	v_exp_f32_e32 v33, v33
	s_waitcnt lgkmcnt(3)
	v_mfma_f32_32x32x16_bf16 v[48:63], v[204:207], v[84:87], v[48:63]
	ds_read_b128 v[204:207], v72 offset:9248
	v_exp_f32_e32 v34, v34
	v_exp_f32_e32 v35, v35
	v_mov_b32_e32 v232, v32
	v_mov_b32_e32 v233, v33
	v_cvt_pk_bf16_f32 v64, v32, v33
	v_exp_f32_e32 v36, v36
	v_exp_f32_e32 v37, v37
	v_add_f32_e32 v232, v232, v34
	v_add_f32_e32 v233, v233, v35
	v_cvt_pk_bf16_f32 v65, v34, v35
	v_exp_f32_e32 v38, v38
	v_exp_f32_e32 v39, v39
	v_add_f32_e32 v232, v232, v36
	v_add_f32_e32 v233, v233, v37
	v_cvt_pk_bf16_f32 v66, v36, v37
	v_add_f32_e32 v232, v232, v38
	v_add_f32_e32 v233, v233, v39
	v_cvt_pk_bf16_f32 v67, v38, v39
	s_waitcnt lgkmcnt(3)
	v_mfma_f32_32x32x16_bf16 v[48:63], v[208:211], v[88:91], v[48:63]
	ds_read_b128 v[208:211], v72 offset:9280
	v_exp_f32_e32 v40, v40
	v_exp_f32_e32 v41, v41
	s_waitcnt lgkmcnt(3)
; #define LAS __attribute__((address_space(3)))
; #define MFMA32(a, b, c) __builtin_amdgcn_mfma_f32_32x32x16_bf16((a), (b), (c), 0, 0, 0)
; __device__ __forceinline__ float ex2(float x) { return __builtin_amdgcn_exp2f(x); }
; template <int MODE>
; __device__ __forceinline__ void attn_tile(const LAS unsigned char* Kb, const LAS unsigned char* Vb, const bf16x8_t (&qf)[4], f32x16 (&oacc)[2], float& l_run,
;                                           int r, int h, int dlt0, int dlt1, bool hiw) {
;     ...
;     for (int mt = 0; mt < 4; ++mt) {
;         if (mt == 0) { if (hiw) __builtin_amdgcn_s_setprio(1); else __builtin_amdgcn_s_setprio(0); }
;         if (mt == 2) { if (hiw) __builtin_amdgcn_s_setprio(0); else __builtin_amdgcn_s_setprio(1); }
;         const int dl = mt < 2 ? dlt0 : dlt1;
;         f32x16 sacc = zero16();
; #pragma unroll
;         for (int ks = 0; ks < 4; ++ks) { const bf16x8_t ka = *(const LAS bf16x8_t*)(Kb + (32 * mt + r) * A_KSTR + 32 * ks + 16 * h); sacc = MFMA32(ka, qf[ks], sacc); }
; #pragma unroll
;         for (int i = 0; i < 16; ++i) {
;             float p;
;             if (MODE == 2) p = ex2(sacc[i]);
;             else if (MODE == 3) p = ex2(sacc[i] + __int_as_float(dl));
;             else { const int ci = 32 * mt + (i & 3) + 8 * (i >> 2); p = ((unsigned)(dl - ci) < ulim) ? ex2(sacc[i]) : 0.f; }
;             sacc[i] = p; ls += p;
;         }
; #pragma unroll
;         for (int s = 0; s < 2; ++s) {
;             const bf16x8_t pf = pack8(sacc, 8 * s);
; #pragma unroll
;             for (int dt = 0; dt < 2; ++dt) {
;                 const LAS unsigned char* vp = Vb + (32 * dt + r) * A_CVSTR + (32 * mt + 16 * s + 4 * h) * 2;
;                 const s16x4_t lo = *(const LAS s16x4_t*)vp, hi = *(const LAS s16x4_t*)(vp + 16);
;                 oacc[dt] = MFMA32(__builtin_shufflevector(lo, hi, 0, 1, 2, 3, 4, 5, 6, 7), pf, oacc[dt]);
;             }
;         }
;     }
;     l_run += ls;
	v_mfma_f32_32x32x16_bf16 v[48:63], v[212:215], v[92:95], v[48:63]
	ds_read_b128 v[212:215], v72 offset:9312
	v_exp_f32_e32 v42, v42
	v_exp_f32_e32 v43, v43
	v_add_f32_e32 v232, v232, v40
	v_add_f32_e32 v233, v233, v41
	v_cvt_pk_bf16_f32 v68, v40, v41
	s_waitcnt lgkmcnt(11)
	v_mfma_f32_32x32x16_bf16 v[0:15], v[216:219], v[64:67], v[0:15]
	ds_read2_b64 v[216:219], v73 offset0:8 offset1:10
	v_exp_f32_e32 v44, v44
	v_exp_f32_e32 v45, v45
	v_add_f32_e32 v232, v232, v42
	v_add_f32_e32 v233, v233, v43
	v_cvt_pk_bf16_f32 v69, v42, v43
	s_waitcnt lgkmcnt(11)
	v_mfma_f32_32x32x16_bf16 v[16:31], v[220:223], v[64:67], v[16:31]
	ds_read2_b64 v[220:223], v74 offset0:40 offset1:42
	v_exp_f32_e32 v46, v46
	v_exp_f32_e32 v47, v47
	v_add_f32_e32 v232, v232, v44
	v_add_f32_e32 v233, v233, v45
	v_cvt_pk_bf16_f32 v70, v44, v45
	v_add_f32_e32 v232, v232, v46
	v_add_f32_e32 v233, v233, v47
	v_cvt_pk_bf16_f32 v71, v46, v47
	s_waitcnt lgkmcnt(5)
	v_mfma_f32_32x32x16_bf16 v[32:47], v[200:203], v[80:83], 0
	v_exp_f32_e32 v48, v48
	v_exp_f32_e32 v49, v49
	s_waitcnt lgkmcnt(4)
	v_mfma_f32_32x32x16_bf16 v[32:47], v[204:207], v[84:87], v[32:47]
	v_exp_f32_e32 v50, v50
	v_exp_f32_e32 v51, v51
	v_add_f32_e32 v232, v232, v48
	v_add_f32_e32 v233, v233, v49
	v_cvt_pk_bf16_f32 v64, v48, v49
	s_waitcnt lgkmcnt(11)
	v_mfma_f32_32x32x16_bf16 v[0:15], v[224:227], v[68:71], v[0:15]
	ds_read2_b64 v[224:227], v73 offset0:12 offset1:14
	v_exp_f32_e32 v52, v52
	v_exp_f32_e32 v53, v53
	v_add_f32_e32 v232, v232, v50
	v_add_f32_e32 v233, v233, v51
	v_cvt_pk_bf16_f32 v65, v50, v51
	s_waitcnt lgkmcnt(11)
	v_mfma_f32_32x32x16_bf16 v[16:31], v[228:231], v[68:71], v[16:31]
	ds_read2_b64 v[228:231], v74 offset0:44 offset1:46
	v_exp_f32_e32 v54, v54
	v_exp_f32_e32 v55, v55
	v_add_f32_e32 v232, v232, v52
	v_add_f32_e32 v233, v233, v53
	v_cvt_pk_bf16_f32 v66, v52, v53
	v_add_f32_e32 v232, v232, v54
	v_add_f32_e32 v233, v233, v55
	v_cvt_pk_bf16_f32 v67, v54, v55
	s_waitcnt lgkmcnt(5)
	v_mfma_f32_32x32x16_bf16 v[32:47], v[208:211], v[88:91], v[32:47]
	v_exp_f32_e32 v56, v56
	v_exp_f32_e32 v57, v57
	s_waitcnt lgkmcnt(4)
	v_mfma_f32_32x32x16_bf16 v[32:47], v[212:215], v[92:95], v[32:47]
	v_exp_f32_e32 v58, v58
	v_exp_f32_e32 v59, v59
	v_add_f32_e32 v232, v232, v56
	v_add_f32_e32 v233, v233, v57
	v_cvt_pk_bf16_f32 v68, v56, v57
	s_waitcnt lgkmcnt(3)
	v_mfma_f32_32x32x16_bf16 v[0:15], v[216:219], v[64:67], v[0:15]
	ds_read2_b64 v[216:219], v73 offset0:16 offset1:18
	v_exp_f32_e32 v60, v60
	v_exp_f32_e32 v61, v61
	v_add_f32_e32 v232, v232, v58
	v_add_f32_e32 v233, v233, v59
	v_cvt_pk_bf16_f32 v69, v58, v59
	s_waitcnt lgkmcnt(3)
	v_mfma_f32_32x32x16_bf16 v[16:31], v[220:223], v[64:67], v[16:31]
	ds_read2_b64 v[220:223], v74 offset0:48 offset1:50
	v_exp_f32_e32 v62, v62
	v_exp_f32_e32 v63, v63
	v_add_f32_e32 v232, v232, v60
	v_add_f32_e32 v233, v233, v61
	v_cvt_pk_bf16_f32 v70, v60, v61
	v_add_f32_e32 v232, v232, v62
	v_add_f32_e32 v233, v233, v63
	v_cvt_pk_bf16_f32 v71, v62, v63
	v_cmp_le_i32_e64 s[0:1], 0, v250
	v_cmp_le_i32_e64 s[4:5], 1, v250
	v_exp_f32_e32 v32, v32
	v_exp_f32_e32 v33, v33
	v_cmp_le_i32_e64 s[6:7], 2, v250
	v_cmp_le_i32_e64 s[48:49], 3, v250
	v_exp_f32_e32 v34, v34
	v_exp_f32_e32 v35, v35
	v_cndmask_b32_e64 v32, 0, v32, s[0:1]
	v_cndmask_b32_e64 v33, 0, v33, s[4:5]
	v_add_f32_e32 v232, v232, v32
	v_add_f32_e32 v233, v233, v33
	v_cvt_pk_bf16_f32 v64, v32, v33
	s_waitcnt lgkmcnt(3)
	v_mfma_f32_32x32x16_bf16 v[0:15], v[224:227], v[68:71], v[0:15]
	ds_read2_b64 v[224:227], v73 offset0:20 offset1:22
	v_cmp_le_i32_e64 s[0:1], 8, v250
	v_cmp_le_i32_e64 s[4:5], 9, v250
	v_exp_f32_e32 v36, v36
	v_exp_f32_e32 v37, v37
	v_cndmask_b32_e64 v34, 0, v34, s[6:7]
	v_cndmask_b32_e64 v35, 0, v35, s[48:49]
	v_add_f32_e32 v232, v232, v34
	v_add_f32_e32 v233, v233, v35
	v_cvt_pk_bf16_f32 v65, v34, v35
	s_waitcnt lgkmcnt(3)
	v_mfma_f32_32x32x16_bf16 v[16:31], v[228:231], v[68:71], v[16:31]
	ds_read2_b64 v[228:231], v74 offset0:52 offset1:54
	v_cmp_le_i32_e64 s[6:7], 10, v250
	v_cmp_le_i32_e64 s[48:49], 11, v250
	v_exp_f32_e32 v38, v38
	v_exp_f32_e32 v39, v39
	v_cndmask_b32_e64 v36, 0, v36, s[0:1]
	v_cndmask_b32_e64 v37, 0, v37, s[4:5]
	v_add_f32_e32 v232, v232, v36
	v_add_f32_e32 v233, v233, v37
	v_cvt_pk_bf16_f32 v66, v36, v37
	v_cndmask_b32_e64 v38, 0, v38, s[6:7]
	v_cndmask_b32_e64 v39, 0, v39, s[48:49]
	v_add_f32_e32 v232, v232, v38
	v_add_f32_e32 v233, v233, v39
	v_cvt_pk_bf16_f32 v67, v38, v39
	v_cmp_le_i32_e64 s[0:1], 16, v250
	v_cmp_le_i32_e64 s[4:5], 17, v250
	v_exp_f32_e32 v40, v40
	v_exp_f32_e32 v41, v41
	v_cmp_le_i32_e64 s[6:7], 18, v250
	v_cmp_le_i32_e64 s[48:49], 19, v250
	v_exp_f32_e32 v42, v42
	v_exp_f32_e32 v43, v43
	v_cndmask_b32_e64 v40, 0, v40, s[0:1]
	v_cndmask_b32_e64 v41, 0, v41, s[4:5]
	v_add_f32_e32 v232, v232, v40
	v_add_f32_e32 v233, v233, v41
	v_cvt_pk_bf16_f32 v68, v40, v41
	s_waitcnt lgkmcnt(3)
	v_mfma_f32_32x32x16_bf16 v[0:15], v[216:219], v[64:67], v[0:15]
	v_cmp_le_i32_e64 s[0:1], 24, v250
	v_cmp_le_i32_e64 s[4:5], 25, v250
	v_exp_f32_e32 v44, v44
	v_exp_f32_e32 v45, v45
	v_cndmask_b32_e64 v42, 0, v42, s[6:7]
	v_cndmask_b32_e64 v43, 0, v43, s[48:49]
	v_add_f32_e32 v232, v232, v42
	v_add_f32_e32 v233, v233, v43
	v_cvt_pk_bf16_f32 v69, v42, v43
	s_waitcnt lgkmcnt(2)
	v_mfma_f32_32x32x16_bf16 v[16:31], v[220:223], v[64:67], v[16:31]
	v_cmp_le_i32_e64 s[6:7], 26, v250
	v_cmp_le_i32_e64 s[48:49], 27, v250
	v_exp_f32_e32 v46, v46
	v_exp_f32_e32 v47, v47
	v_cndmask_b32_e64 v44, 0, v44, s[0:1]
	v_cndmask_b32_e64 v45, 0, v45, s[4:5]
	v_add_f32_e32 v232, v232, v44
	v_add_f32_e32 v233, v233, v45
	v_cvt_pk_bf16_f32 v70, v44, v45
	v_cndmask_b32_e64 v46, 0, v46, s[6:7]
	v_cndmask_b32_e64 v47, 0, v47, s[48:49]
	v_add_f32_e32 v232, v232, v46
	v_add_f32_e32 v233, v233, v47
	v_cvt_pk_bf16_f32 v71, v46, v47
	s_nop 1
	s_waitcnt lgkmcnt(1)
	v_mfma_f32_32x32x16_bf16 v[0:15], v[224:227], v[68:71], v[0:15]
	s_waitcnt lgkmcnt(0)
	v_mfma_f32_32x32x16_bf16 v[16:31], v[228:231], v[68:71], v[16:31]
	v_add_f32_e32 v232, v232, v233
	v_add_f32_e32 v112, v112, v232
	s_branch .Lt1_join
; #define LAS __attribute__((address_space(3)))
; #define MFMA32(a, b, c) __builtin_amdgcn_mfma_f32_32x32x16_bf16((a), (b), (c), 0, 0, 0)
; __device__ __forceinline__ float ex2(float x) { return __builtin_amdgcn_exp2f(x); }
; template <int MODE>
; __device__ __forceinline__ void attn_tile(const LAS unsigned char* Kb, const LAS unsigned char* Vb, const bf16x8_t (&qf)[4], f32x16 (&oacc)[2], float& l_run,
;                                           int r, int h, int dlt0, int dlt1, bool hiw) {
;     ...
;     for (int mt = 0; mt < 4; ++mt) {
;         if (mt == 0) { if (hiw) __builtin_amdgcn_s_setprio(1); else __builtin_amdgcn_s_setprio(0); }
;         if (mt == 2) { if (hiw) __builtin_amdgcn_s_setprio(0); else __builtin_amdgcn_s_setprio(1); }
;         const int dl = mt < 2 ? dlt0 : dlt1;
;         f32x16 sacc = zero16();
; #pragma unroll
;         for (int ks = 0; ks < 4; ++ks) { const bf16x8_t ka = *(const LAS bf16x8_t*)(Kb + (32 * mt + r) * A_KSTR + 32 * ks + 16 * h); sacc = MFMA32(ka, qf[ks], sacc); }
; #pragma unroll
;         for (int i = 0; i < 16; ++i) {
;             float p;
;             if (MODE == 2) p = ex2(sacc[i]);
;             else if (MODE == 3) p = ex2(sacc[i] + __int_as_float(dl));
;             else { const int ci = 32 * mt + (i & 3) + 8 * (i >> 2); p = ((unsigned)(dl - ci) < ulim) ? ex2(sacc[i]) : 0.f; }
;             sacc[i] = p; ls += p;
;         }
; #pragma unroll
;         for (int s = 0; s < 2; ++s) {
;             const bf16x8_t pf = pack8(sacc, 8 * s);
; #pragma unroll
;             for (int dt = 0; dt < 2; ++dt) {
;                 const LAS unsigned char* vp = Vb + (32 * dt + r) * A_CVSTR + (32 * mt + 16 * s + 4 * h) * 2;
;                 const s16x4_t lo = *(const LAS s16x4_t*)vp, hi = *(const LAS s16x4_t*)(vp + 16);
;                 oacc[dt] = MFMA32(__builtin_shufflevector(lo, hi, 0, 1, 2, 3, 4, 5, 6, 7), pf, oacc[dt]);
;             }
;         }
;     }
;     l_run += ls;
.Lt1_d3:
	ds_read_b128 v[200:203], v72 offset:0
	ds_read_b128 v[204:207], v72 offset:32
	ds_read_b128 v[208:211], v72 offset:64
	ds_read_b128 v[212:215], v72 offset:96
	ds_read2_b64 v[216:219], v73 offset0:0 offset1:2
	ds_read2_b64 v[220:223], v74 offset0:32 offset1:34
	ds_read2_b64 v[224:227], v73 offset0:4 offset1:6
	ds_read2_b64 v[228:231], v74 offset0:36 offset1:38
	s_waitcnt lgkmcnt(7)
	v_mfma_f32_32x32x16_bf16 v[32:47], v[200:203], v[80:83], 0
	ds_read_b128 v[200:203], v72 offset:4608
	s_waitcnt lgkmcnt(7)
	v_mfma_f32_32x32x16_bf16 v[32:47], v[204:207], v[84:87], v[32:47]
	ds_read_b128 v[204:207], v72 offset:4640
	s_waitcnt lgkmcnt(7)
	v_mfma_f32_32x32x16_bf16 v[32:47], v[208:211], v[88:91], v[32:47]
	ds_read_b128 v[208:211], v72 offset:4672
	s_waitcnt lgkmcnt(7)
	v_mfma_f32_32x32x16_bf16 v[32:47], v[212:215], v[92:95], v[32:47]
	ds_read_b128 v[212:215], v72 offset:4704
	s_nop 7
	s_nop 3
	s_waitcnt lgkmcnt(3)
	v_mfma_f32_32x32x16_bf16 v[48:63], v[200:203], v[80:83], 0
	ds_read_b128 v[200:203], v72 offset:9216
	v_exp_f32_e32 v32, v32
	v_exp_f32_e32 v33, v33
	s_waitcnt lgkmcnt(3)
	v_mfma_f32_32x32x16_bf16 v[48:63], v[204:207], v[84:87], v[48:63]
	ds_read_b128 v[204:207], v72 offset:9248
	v_exp_f32_e32 v34, v34
	v_exp_f32_e32 v35, v35
	v_mov_b32_e32 v232, v32
	v_mov_b32_e32 v233, v33
	v_cvt_pk_bf16_f32 v64, v32, v33
	v_exp_f32_e32 v36, v36
	v_exp_f32_e32 v37, v37
	v_add_f32_e32 v232, v232, v34
	v_add_f32_e32 v233, v233, v35
	v_cvt_pk_bf16_f32 v65, v34, v35
	v_exp_f32_e32 v38, v38
	v_exp_f32_e32 v39, v39
	v_add_f32_e32 v232, v232, v36
	v_add_f32_e32 v233, v233, v37
	v_cvt_pk_bf16_f32 v66, v36, v37
	v_add_f32_e32 v232, v232, v38
	v_add_f32_e32 v233, v233, v39
	v_cvt_pk_bf16_f32 v67, v38, v39
	s_waitcnt lgkmcnt(3)
	v_mfma_f32_32x32x16_bf16 v[48:63], v[208:211], v[88:91], v[48:63]
	ds_read_b128 v[208:211], v72 offset:9280
	v_exp_f32_e32 v40, v40
	v_exp_f32_e32 v41, v41
	s_waitcnt lgkmcnt(3)
	v_mfma_f32_32x32x16_bf16 v[48:63], v[212:215], v[92:95], v[48:63]
	ds_read_b128 v[212:215], v72 offset:9312
	v_exp_f32_e32 v42, v42
	v_exp_f32_e32 v43, v43
	v_add_f32_e32 v232, v232, v40
	v_add_f32_e32 v233, v233, v41
	v_cvt_pk_bf16_f32 v68, v40, v41
	s_waitcnt lgkmcnt(11)
	v_mfma_f32_32x32x16_bf16 v[0:15], v[216:219], v[64:67], v[0:15]
	ds_read2_b64 v[216:219], v73 offset0:8 offset1:10
	v_exp_f32_e32 v44, v44
	v_exp_f32_e32 v45, v45
	v_add_f32_e32 v232, v232, v42
	v_add_f32_e32 v233, v233, v43
	v_cvt_pk_bf16_f32 v69, v42, v43
	s_waitcnt lgkmcnt(11)
	v_mfma_f32_32x32x16_bf16 v[16:31], v[220:223], v[64:67], v[16:31]
	ds_read2_b64 v[220:223], v74 offset0:40 offset1:42
	v_exp_f32_e32 v46, v46
	v_exp_f32_e32 v47, v47
	v_add_f32_e32 v232, v232, v44
	v_add_f32_e32 v233, v233, v45
	v_cvt_pk_bf16_f32 v70, v44, v45
	v_add_f32_e32 v232, v232, v46
	v_add_f32_e32 v233, v233, v47
	v_cvt_pk_bf16_f32 v71, v46, v47
	s_waitcnt lgkmcnt(5)
	v_mfma_f32_32x32x16_bf16 v[32:47], v[200:203], v[80:83], 0
	ds_read_b128 v[200:203], v72 offset:13824
	v_exp_f32_e32 v48, v48
	v_exp_f32_e32 v49, v49
	s_waitcnt lgkmcnt(5)
	v_mfma_f32_32x32x16_bf16 v[32:47], v[204:207], v[84:87], v[32:47]
	ds_read_b128 v[204:207], v72 offset:13856
	v_exp_f32_e32 v50, v50
	v_exp_f32_e32 v51, v51
	v_add_f32_e32 v232, v232, v48
	v_add_f32_e32 v233, v233, v49
	v_cvt_pk_bf16_f32 v64, v48, v49
	s_waitcnt lgkmcnt(13)
	v_mfma_f32_32x32x16_bf16 v[0:15], v[224:227], v[68:71], v[0:15]
	ds_read2_b64 v[224:227], v73 offset0:12 offset1:14
	v_exp_f32_e32 v52, v52
	v_exp_f32_e32 v53, v53
	v_add_f32_e32 v232, v232, v50
	v_add_f32_e32 v233, v233, v51
	v_cvt_pk_bf16_f32 v65, v50, v51
	s_waitcnt lgkmcnt(13)
	v_mfma_f32_32x32x16_bf16 v[16:31], v[228:231], v[68:71], v[16:31]
	ds_read2_b64 v[228:231], v74 offset0:44 offset1:46
	v_exp_f32_e32 v54, v54
	v_exp_f32_e32 v55, v55
	v_add_f32_e32 v232, v232, v52
	v_add_f32_e32 v233, v233, v53
	v_cvt_pk_bf16_f32 v66, v52, v53
	v_add_f32_e32 v232, v232, v54
	v_add_f32_e32 v233, v233, v55
	v_cvt_pk_bf16_f32 v67, v54, v55
	s_waitcnt lgkmcnt(7)
	v_mfma_f32_32x32x16_bf16 v[32:47], v[208:211], v[88:91], v[32:47]
	ds_read_b128 v[208:211], v72 offset:13888
	v_exp_f32_e32 v56, v56
	v_exp_f32_e32 v57, v57
	s_waitcnt lgkmcnt(7)
	v_mfma_f32_32x32x16_bf16 v[32:47], v[212:215], v[92:95], v[32:47]
	ds_read_b128 v[212:215], v72 offset:13920
	v_exp_f32_e32 v58, v58
	v_exp_f32_e32 v59, v59
	v_add_f32_e32 v232, v232, v56
	v_add_f32_e32 v233, v233, v57
	v_cvt_pk_bf16_f32 v68, v56, v57
	s_waitcnt lgkmcnt(7)
	v_mfma_f32_32x32x16_bf16 v[0:15], v[216:219], v[64:67], v[0:15]
	ds_read2_b64 v[216:219], v73 offset0:16 offset1:18
	v_exp_f32_e32 v60, v60
	v_exp_f32_e32 v61, v61
	v_add_f32_e32 v232, v232, v58
	v_add_f32_e32 v233, v233, v59
	v_cvt_pk_bf16_f32 v69, v58, v59
	s_waitcnt lgkmcnt(7)
	v_mfma_f32_32x32x16_bf16 v[16:31], v[220:223], v[64:67], v[16:31]
	ds_read2_b64 v[220:223], v74 offset0:48 offset1:50
	v_exp_f32_e32 v62, v62
	v_exp_f32_e32 v63, v63
	v_add_f32_e32 v232, v232, v60
	v_add_f32_e32 v233, v233, v61
	v_cvt_pk_bf16_f32 v70, v60, v61
	v_add_f32_e32 v232, v232, v62
	v_add_f32_e32 v233, v233, v63
	v_cvt_pk_bf16_f32 v71, v62, v63
	s_waitcnt lgkmcnt(7)
	v_mfma_f32_32x32x16_bf16 v[48:63], v[200:203], v[80:83], 0
	v_exp_f32_e32 v32, v32
	v_exp_f32_e32 v33, v33
	s_waitcnt lgkmcnt(6)
	v_mfma_f32_32x32x16_bf16 v[48:63], v[204:207], v[84:87], v[48:63]
	v_exp_f32_e32 v34, v34
	v_exp_f32_e32 v35, v35
	v_add_f32_e32 v232, v232, v32
	v_add_f32_e32 v233, v233, v33
	v_cvt_pk_bf16_f32 v64, v32, v33
	s_waitcnt lgkmcnt(5)
	v_mfma_f32_32x32x16_bf16 v[0:15], v[224:227], v[68:71], v[0:15]
	ds_read2_b64 v[224:227], v73 offset0:20 offset1:22
	v_exp_f32_e32 v36, v36
	v_exp_f32_e32 v37, v37
	v_add_f32_e32 v232, v232, v34
	v_add_f32_e32 v233, v233, v35
	v_cvt_pk_bf16_f32 v65, v34, v35
	s_waitcnt lgkmcnt(5)
; #define LAS __attribute__((address_space(3)))
; #define MFMA32(a, b, c) __builtin_amdgcn_mfma_f32_32x32x16_bf16((a), (b), (c), 0, 0, 0)
; __device__ __forceinline__ float ex2(float x) { return __builtin_amdgcn_exp2f(x); }
; template <int MODE>
; __device__ __forceinline__ void attn_tile(const LAS unsigned char* Kb, const LAS unsigned char* Vb, const bf16x8_t (&qf)[4], f32x16 (&oacc)[2], float& l_run,
;                                           int r, int h, int dlt0, int dlt1, bool hiw) {
;     ...
;     for (int mt = 0; mt < 4; ++mt) {
;         if (mt == 0) { if (hiw) __builtin_amdgcn_s_setprio(1); else __builtin_amdgcn_s_setprio(0); }
;         if (mt == 2) { if (hiw) __builtin_amdgcn_s_setprio(0); else __builtin_amdgcn_s_setprio(1); }
;         const int dl = mt < 2 ? dlt0 : dlt1;
;         f32x16 sacc = zero16();
; #pragma unroll
;         for (int ks = 0; ks < 4; ++ks) { const bf16x8_t ka = *(const LAS bf16x8_t*)(Kb + (32 * mt + r) * A_KSTR + 32 * ks + 16 * h); sacc = MFMA32(ka, qf[ks], sacc); }
; #pragma unroll
;         for (int i = 0; i < 16; ++i) {
;             float p;
;             if (MODE == 2) p = ex2(sacc[i]);
;             else if (MODE == 3) p = ex2(sacc[i] + __int_as_float(dl));
;             else { const int ci = 32 * mt + (i & 3) + 8 * (i >> 2); p = ((unsigned)(dl - ci) < ulim) ? ex2(sacc[i]) : 0.f; }
;             sacc[i] = p; ls += p;
;         }
; #pragma unroll
;         for (int s = 0; s < 2; ++s) {
;             const bf16x8_t pf = pack8(sacc, 8 * s);
; #pragma unroll
;             for (int dt = 0; dt < 2; ++dt) {
;                 const LAS unsigned char* vp = Vb + (32 * dt + r) * A_CVSTR + (32 * mt + 16 * s + 4 * h) * 2;
;                 const s16x4_t lo = *(const LAS s16x4_t*)vp, hi = *(const LAS s16x4_t*)(vp + 16);
;                 oacc[dt] = MFMA32(__builtin_shufflevector(lo, hi, 0, 1, 2, 3, 4, 5, 6, 7), pf, oacc[dt]);
;             }
;         }
;     }
;     l_run += ls;
	v_mfma_f32_32x32x16_bf16 v[16:31], v[228:231], v[68:71], v[16:31]
	ds_read2_b64 v[228:231], v74 offset0:52 offset1:54
	v_exp_f32_e32 v38, v38
	v_exp_f32_e32 v39, v39
	v_add_f32_e32 v232, v232, v36
	v_add_f32_e32 v233, v233, v37
	v_cvt_pk_bf16_f32 v66, v36, v37
	v_add_f32_e32 v232, v232, v38
	v_add_f32_e32 v233, v233, v39
	v_cvt_pk_bf16_f32 v67, v38, v39
	s_waitcnt lgkmcnt(5)
	v_mfma_f32_32x32x16_bf16 v[48:63], v[208:211], v[88:91], v[48:63]
	v_exp_f32_e32 v40, v40
	v_exp_f32_e32 v41, v41
	s_waitcnt lgkmcnt(4)
	v_mfma_f32_32x32x16_bf16 v[48:63], v[212:215], v[92:95], v[48:63]
	v_exp_f32_e32 v42, v42
	v_exp_f32_e32 v43, v43
	v_add_f32_e32 v232, v232, v40
	v_add_f32_e32 v233, v233, v41
	v_cvt_pk_bf16_f32 v68, v40, v41
	s_waitcnt lgkmcnt(3)
	v_mfma_f32_32x32x16_bf16 v[0:15], v[216:219], v[64:67], v[0:15]
	ds_read2_b64 v[216:219], v73 offset0:24 offset1:26
	v_exp_f32_e32 v44, v44
	v_exp_f32_e32 v45, v45
	v_add_f32_e32 v232, v232, v42
	v_add_f32_e32 v233, v233, v43
	v_cvt_pk_bf16_f32 v69, v42, v43
	s_waitcnt lgkmcnt(3)
	v_mfma_f32_32x32x16_bf16 v[16:31], v[220:223], v[64:67], v[16:31]
	ds_read2_b64 v[220:223], v74 offset0:56 offset1:58
	v_exp_f32_e32 v46, v46
	v_exp_f32_e32 v47, v47
	v_add_f32_e32 v232, v232, v44
	v_add_f32_e32 v233, v233, v45
	v_cvt_pk_bf16_f32 v70, v44, v45
	v_add_f32_e32 v232, v232, v46
	v_add_f32_e32 v233, v233, v47
	v_cvt_pk_bf16_f32 v71, v46, v47
	v_cmp_le_i32_e64 s[0:1], 0, v250
	v_cmp_le_i32_e64 s[4:5], 1, v250
	v_exp_f32_e32 v48, v48
	v_exp_f32_e32 v49, v49
	v_cmp_le_i32_e64 s[6:7], 2, v250
	v_cmp_le_i32_e64 s[48:49], 3, v250
	v_exp_f32_e32 v50, v50
	v_exp_f32_e32 v51, v51
	v_cndmask_b32_e64 v48, 0, v48, s[0:1]
	v_cndmask_b32_e64 v49, 0, v49, s[4:5]
	v_add_f32_e32 v232, v232, v48
	v_add_f32_e32 v233, v233, v49
	v_cvt_pk_bf16_f32 v64, v48, v49
	s_waitcnt lgkmcnt(3)
	v_mfma_f32_32x32x16_bf16 v[0:15], v[224:227], v[68:71], v[0:15]
	ds_read2_b64 v[224:227], v73 offset0:28 offset1:30
	v_cmp_le_i32_e64 s[0:1], 8, v250
	v_cmp_le_i32_e64 s[4:5], 9, v250
	v_exp_f32_e32 v52, v52
	v_exp_f32_e32 v53, v53
	v_cndmask_b32_e64 v50, 0, v50, s[6:7]
	v_cndmask_b32_e64 v51, 0, v51, s[48:49]
	v_add_f32_e32 v232, v232, v50
	v_add_f32_e32 v233, v233, v51
	v_cvt_pk_bf16_f32 v65, v50, v51
	s_waitcnt lgkmcnt(3)
	v_mfma_f32_32x32x16_bf16 v[16:31], v[228:231], v[68:71], v[16:31]
	ds_read2_b64 v[228:231], v74 offset0:60 offset1:62
	v_cmp_le_i32_e64 s[6:7], 10, v250
	v_cmp_le_i32_e64 s[48:49], 11, v250
	v_exp_f32_e32 v54, v54
	v_exp_f32_e32 v55, v55
	v_cndmask_b32_e64 v52, 0, v52, s[0:1]
	v_cndmask_b32_e64 v53, 0, v53, s[4:5]
	v_add_f32_e32 v232, v232, v52
	v_add_f32_e32 v233, v233, v53
	v_cvt_pk_bf16_f32 v66, v52, v53
	v_cndmask_b32_e64 v54, 0, v54, s[6:7]
	v_cndmask_b32_e64 v55, 0, v55, s[48:49]
	v_add_f32_e32 v232, v232, v54
	v_add_f32_e32 v233, v233, v55
	v_cvt_pk_bf16_f32 v67, v54, v55
	v_cmp_le_i32_e64 s[0:1], 16, v250
	v_cmp_le_i32_e64 s[4:5], 17, v250
	v_exp_f32_e32 v56, v56
	v_exp_f32_e32 v57, v57
	v_cmp_le_i32_e64 s[6:7], 18, v250
	v_cmp_le_i32_e64 s[48:49], 19, v250
	v_exp_f32_e32 v58, v58
	v_exp_f32_e32 v59, v59
	v_cndmask_b32_e64 v56, 0, v56, s[0:1]
	v_cndmask_b32_e64 v57, 0, v57, s[4:5]
	v_add_f32_e32 v232, v232, v56
	v_add_f32_e32 v233, v233, v57
	v_cvt_pk_bf16_f32 v68, v56, v57
	s_waitcnt lgkmcnt(3)
	v_mfma_f32_32x32x16_bf16 v[0:15], v[216:219], v[64:67], v[0:15]
	v_cmp_le_i32_e64 s[0:1], 24, v250
	v_cmp_le_i32_e64 s[4:5], 25, v250
	v_exp_f32_e32 v60, v60
	v_exp_f32_e32 v61, v61
	v_cndmask_b32_e64 v58, 0, v58, s[6:7]
	v_cndmask_b32_e64 v59, 0, v59, s[48:49]
	v_add_f32_e32 v232, v232, v58
	v_add_f32_e32 v233, v233, v59
	v_cvt_pk_bf16_f32 v69, v58, v59
	s_waitcnt lgkmcnt(2)
	v_mfma_f32_32x32x16_bf16 v[16:31], v[220:223], v[64:67], v[16:31]
	v_cmp_le_i32_e64 s[6:7], 26, v250
	v_cmp_le_i32_e64 s[48:49], 27, v250
	v_exp_f32_e32 v62, v62
	v_exp_f32_e32 v63, v63
	v_cndmask_b32_e64 v60, 0, v60, s[0:1]
	v_cndmask_b32_e64 v61, 0, v61, s[4:5]
	v_add_f32_e32 v232, v232, v60
	v_add_f32_e32 v233, v233, v61
	v_cvt_pk_bf16_f32 v70, v60, v61
	v_cndmask_b32_e64 v62, 0, v62, s[6:7]
	v_cndmask_b32_e64 v63, 0, v63, s[48:49]
	v_add_f32_e32 v232, v232, v62
	v_add_f32_e32 v233, v233, v63
	v_cvt_pk_bf16_f32 v71, v62, v63
	s_nop 1
	s_waitcnt lgkmcnt(1)
	v_mfma_f32_32x32x16_bf16 v[0:15], v[224:227], v[68:71], v[0:15]
	s_waitcnt lgkmcnt(0)
	v_mfma_f32_32x32x16_bf16 v[16:31], v[228:231], v[68:71], v[16:31]
	v_add_f32_e32 v232, v232, v233
	v_add_f32_e32 v112, v112, v232
	s_branch .Lt1_join
; #define LAS __attribute__((address_space(3)))
; #define MFMA32(a, b, c) __builtin_amdgcn_mfma_f32_32x32x16_bf16((a), (b), (c), 0, 0, 0)
; __device__ __forceinline__ float ex2(float x) { return __builtin_amdgcn_exp2f(x); }
; template <int MODE>
; __device__ __forceinline__ void attn_tile(const LAS unsigned char* Kb, const LAS unsigned char* Vb, const bf16x8_t (&qf)[4], f32x16 (&oacc)[2], float& l_run,
;                                           int r, int h, int dlt0, int dlt1, bool hiw) {
;     ...
;     for (int mt = 0; mt < 4; ++mt) {
;         if (mt == 0) { if (hiw) __builtin_amdgcn_s_setprio(1); else __builtin_amdgcn_s_setprio(0); }
;         if (mt == 2) { if (hiw) __builtin_amdgcn_s_setprio(0); else __builtin_amdgcn_s_setprio(1); }
;         const int dl = mt < 2 ? dlt0 : dlt1;
;         f32x16 sacc = zero16();
; #pragma unroll
;         for (int ks = 0; ks < 4; ++ks) { const bf16x8_t ka = *(const LAS bf16x8_t*)(Kb + (32 * mt + r) * A_KSTR + 32 * ks + 16 * h); sacc = MFMA32(ka, qf[ks], sacc); }
; #pragma unroll
;         for (int i = 0; i < 16; ++i) {
;             float p;
;             if (MODE == 2) p = ex2(sacc[i]);
;             else if (MODE == 3) p = ex2(sacc[i] + __int_as_float(dl));
;             else { const int ci = 32 * mt + (i & 3) + 8 * (i >> 2); p = ((unsigned)(dl - ci) < ulim) ? ex2(sacc[i]) : 0.f; }
;             sacc[i] = p; ls += p;
;         }
; #pragma unroll
;         for (int s = 0; s < 2; ++s) {
;             const bf16x8_t pf = pack8(sacc, 8 * s);
; #pragma unroll
;             for (int dt = 0; dt < 2; ++dt) {
;                 const LAS unsigned char* vp = Vb + (32 * dt + r) * A_CVSTR + (32 * mt + 16 * s + 4 * h) * 2;
;                 const s16x4_t lo = *(const LAS s16x4_t*)vp, hi = *(const LAS s16x4_t*)(vp + 16);
;                 oacc[dt] = MFMA32(__builtin_shufflevector(lo, hi, 0, 1, 2, 3, 4, 5, 6, 7), pf, oacc[dt]);
;             }
;         }
;     }
;     l_run += ls;
.Lt1_e0:
	ds_read_b128 v[200:203], v72 offset:0
	ds_read_b128 v[204:207], v72 offset:32
	ds_read_b128 v[208:211], v72 offset:64
	ds_read_b128 v[212:215], v72 offset:96
	ds_read2_b64 v[216:219], v73 offset0:0 offset1:2
	ds_read2_b64 v[220:223], v74 offset0:32 offset1:34
	ds_read2_b64 v[224:227], v73 offset0:4 offset1:6
	ds_read2_b64 v[228:231], v74 offset0:36 offset1:38
	s_waitcnt lgkmcnt(7)
	v_mfma_f32_32x32x16_bf16 v[32:47], v[200:203], v[80:83], 0
	ds_read_b128 v[200:203], v72 offset:4608
	s_waitcnt lgkmcnt(7)
	v_mfma_f32_32x32x16_bf16 v[32:47], v[204:207], v[84:87], v[32:47]
	ds_read_b128 v[204:207], v72 offset:4640
	s_waitcnt lgkmcnt(7)
	v_mfma_f32_32x32x16_bf16 v[32:47], v[208:211], v[88:91], v[32:47]
	ds_read_b128 v[208:211], v72 offset:4672
	s_waitcnt lgkmcnt(7)
	v_mfma_f32_32x32x16_bf16 v[32:47], v[212:215], v[92:95], v[32:47]
	ds_read_b128 v[212:215], v72 offset:4704
	s_nop 7
	s_nop 3
	s_waitcnt lgkmcnt(3)
	v_mfma_f32_32x32x16_bf16 v[48:63], v[200:203], v[80:83], 0
	ds_read_b128 v[200:203], v72 offset:9216
	v_cmp_le_i32_e64 s[0:1], 0, v250
	v_cmp_le_i32_e64 s[4:5], 1, v250
	v_exp_f32_e32 v32, v32
	v_exp_f32_e32 v33, v33
	s_waitcnt lgkmcnt(3)
	v_mfma_f32_32x32x16_bf16 v[48:63], v[204:207], v[84:87], v[48:63]
	ds_read_b128 v[204:207], v72 offset:9248
	v_cmp_le_i32_e64 s[6:7], 2, v250
	v_cmp_le_i32_e64 s[48:49], 3, v250
	v_exp_f32_e32 v34, v34
	v_exp_f32_e32 v35, v35
	v_cndmask_b32_e64 v32, v32, 0, s[0:1]
	v_cndmask_b32_e64 v33, v33, 0, s[4:5]
	v_mov_b32_e32 v232, v32
	v_mov_b32_e32 v233, v33
	v_cvt_pk_bf16_f32 v64, v32, v33
	v_cmp_le_i32_e64 s[0:1], 8, v250
	v_cmp_le_i32_e64 s[4:5], 9, v250
	v_exp_f32_e32 v36, v36
	v_exp_f32_e32 v37, v37
	v_cndmask_b32_e64 v34, v34, 0, s[6:7]
	v_cndmask_b32_e64 v35, v35, 0, s[48:49]
	v_add_f32_e32 v232, v232, v34
	v_add_f32_e32 v233, v233, v35
	v_cvt_pk_bf16_f32 v65, v34, v35
	v_cmp_le_i32_e64 s[6:7], 10, v250
	v_cmp_le_i32_e64 s[48:49], 11, v250
	v_exp_f32_e32 v38, v38
	v_exp_f32_e32 v39, v39
	v_cndmask_b32_e64 v36, v36, 0, s[0:1]
	v_cndmask_b32_e64 v37, v37, 0, s[4:5]
	v_add_f32_e32 v232, v232, v36
	v_add_f32_e32 v233, v233, v37
	v_cvt_pk_bf16_f32 v66, v36, v37
	v_cndmask_b32_e64 v38, v38, 0, s[6:7]
	v_cndmask_b32_e64 v39, v39, 0, s[48:49]
	v_add_f32_e32 v232, v232, v38
	v_add_f32_e32 v233, v233, v39
	v_cvt_pk_bf16_f32 v67, v38, v39
	s_waitcnt lgkmcnt(3)
	v_mfma_f32_32x32x16_bf16 v[48:63], v[208:211], v[88:91], v[48:63]
	ds_read_b128 v[208:211], v72 offset:9280
	v_cmp_le_i32_e64 s[0:1], 16, v250
	v_cmp_le_i32_e64 s[4:5], 17, v250
	v_exp_f32_e32 v40, v40
	v_exp_f32_e32 v41, v41
	s_waitcnt lgkmcnt(3)
	v_mfma_f32_32x32x16_bf16 v[48:63], v[212:215], v[92:95], v[48:63]
	ds_read_b128 v[212:215], v72 offset:9312
	v_cmp_le_i32_e64 s[6:7], 18, v250
	v_cmp_le_i32_e64 s[48:49], 19, v250
	v_exp_f32_e32 v42, v42
	v_exp_f32_e32 v43, v43
	v_cndmask_b32_e64 v40, v40, 0, s[0:1]
	v_cndmask_b32_e64 v41, v41, 0, s[4:5]
	v_add_f32_e32 v232, v232, v40
	v_add_f32_e32 v233, v233, v41
	v_cvt_pk_bf16_f32 v68, v40, v41
	s_waitcnt lgkmcnt(11)
	v_mfma_f32_32x32x16_bf16 v[0:15], v[216:219], v[64:67], v[0:15]
	ds_read2_b64 v[216:219], v73 offset0:8 offset1:10
	v_cmp_le_i32_e64 s[0:1], 24, v250
	v_cmp_le_i32_e64 s[4:5], 25, v250
	v_exp_f32_e32 v44, v44
	v_exp_f32_e32 v45, v45
	v_cndmask_b32_e64 v42, v42, 0, s[6:7]
	v_cndmask_b32_e64 v43, v43, 0, s[48:49]
	v_add_f32_e32 v232, v232, v42
	v_add_f32_e32 v233, v233, v43
	v_cvt_pk_bf16_f32 v69, v42, v43
	s_waitcnt lgkmcnt(11)
	v_mfma_f32_32x32x16_bf16 v[16:31], v[220:223], v[64:67], v[16:31]
	ds_read2_b64 v[220:223], v74 offset0:40 offset1:42
	v_cmp_le_i32_e64 s[6:7], 26, v250
	v_cmp_le_i32_e64 s[48:49], 27, v250
	v_exp_f32_e32 v46, v46
	v_exp_f32_e32 v47, v47
	v_cndmask_b32_e64 v44, v44, 0, s[0:1]
	v_cndmask_b32_e64 v45, v45, 0, s[4:5]
	v_add_f32_e32 v232, v232, v44
	v_add_f32_e32 v233, v233, v45
	v_cvt_pk_bf16_f32 v70, v44, v45
	v_cndmask_b32_e64 v46, v46, 0, s[6:7]
	v_cndmask_b32_e64 v47, v47, 0, s[48:49]
	v_add_f32_e32 v232, v232, v46
	v_add_f32_e32 v233, v233, v47
	v_cvt_pk_bf16_f32 v71, v46, v47
	s_waitcnt lgkmcnt(5)
	v_mfma_f32_32x32x16_bf16 v[32:47], v[200:203], v[80:83], 0
	ds_read_b128 v[200:203], v72 offset:13824
	v_exp_f32_e32 v48, v48
	v_exp_f32_e32 v49, v49
	s_waitcnt lgkmcnt(5)
	v_mfma_f32_32x32x16_bf16 v[32:47], v[204:207], v[84:87], v[32:47]
	ds_read_b128 v[204:207], v72 offset:13856
	v_exp_f32_e32 v50, v50
	v_exp_f32_e32 v51, v51
	v_add_f32_e32 v232, v232, v48
	v_add_f32_e32 v233, v233, v49
	v_cvt_pk_bf16_f32 v64, v48, v49
	s_waitcnt lgkmcnt(13)
	v_mfma_f32_32x32x16_bf16 v[0:15], v[224:227], v[68:71], v[0:15]
	ds_read2_b64 v[224:227], v73 offset0:12 offset1:14
	v_exp_f32_e32 v52, v52
	v_exp_f32_e32 v53, v53
	v_add_f32_e32 v232, v232, v50
	v_add_f32_e32 v233, v233, v51
	v_cvt_pk_bf16_f32 v65, v50, v51
	s_waitcnt lgkmcnt(13)
	v_mfma_f32_32x32x16_bf16 v[16:31], v[228:231], v[68:71], v[16:31]
	ds_read2_b64 v[228:231], v74 offset0:44 offset1:46
	v_exp_f32_e32 v54, v54
	v_exp_f32_e32 v55, v55
	v_add_f32_e32 v232, v232, v52
	v_add_f32_e32 v233, v233, v53
	v_cvt_pk_bf16_f32 v66, v52, v53
	v_add_f32_e32 v232, v232, v54
	v_add_f32_e32 v233, v233, v55
	v_cvt_pk_bf16_f32 v67, v54, v55
	s_waitcnt lgkmcnt(7)
	v_mfma_f32_32x32x16_bf16 v[32:47], v[208:211], v[88:91], v[32:47]
	ds_read_b128 v[208:211], v72 offset:13888
	v_exp_f32_e32 v56, v56
	v_exp_f32_e32 v57, v57
	s_waitcnt lgkmcnt(7)
	v_mfma_f32_32x32x16_bf16 v[32:47], v[212:215], v[92:95], v[32:47]
	ds_read_b128 v[212:215], v72 offset:13920
	v_exp_f32_e32 v58, v58
	v_exp_f32_e32 v59, v59
	v_add_f32_e32 v232, v232, v56
	v_add_f32_e32 v233, v233, v57
	v_cvt_pk_bf16_f32 v68, v56, v57
	s_waitcnt lgkmcnt(7)
; #define LAS __attribute__((address_space(3)))
; #define MFMA32(a, b, c) __builtin_amdgcn_mfma_f32_32x32x16_bf16((a), (b), (c), 0, 0, 0)
; __device__ __forceinline__ float ex2(float x) { return __builtin_amdgcn_exp2f(x); }
; template <int MODE>
; __device__ __forceinline__ void attn_tile(const LAS unsigned char* Kb, const LAS unsigned char* Vb, const bf16x8_t (&qf)[4], f32x16 (&oacc)[2], float& l_run,
;                                           int r, int h, int dlt0, int dlt1, bool hiw) {
;     ...
;     for (int mt = 0; mt < 4; ++mt) {
;         if (mt == 0) { if (hiw) __builtin_amdgcn_s_setprio(1); else __builtin_amdgcn_s_setprio(0); }
;         if (mt == 2) { if (hiw) __builtin_amdgcn_s_setprio(0); else __builtin_amdgcn_s_setprio(1); }
;         const int dl = mt < 2 ? dlt0 : dlt1;
;         f32x16 sacc = zero16();
; #pragma unroll
;         for (int ks = 0; ks < 4; ++ks) { const bf16x8_t ka = *(const LAS bf16x8_t*)(Kb + (32 * mt + r) * A_KSTR + 32 * ks + 16 * h); sacc = MFMA32(ka, qf[ks], sacc); }
; #pragma unroll
;         for (int i = 0; i < 16; ++i) {
;             float p;
;             if (MODE == 2) p = ex2(sacc[i]);
;             else if (MODE == 3) p = ex2(sacc[i] + __int_as_float(dl));
;             else { const int ci = 32 * mt + (i & 3) + 8 * (i >> 2); p = ((unsigned)(dl - ci) < ulim) ? ex2(sacc[i]) : 0.f; }
;             sacc[i] = p; ls += p;
;         }
; #pragma unroll
;         for (int s = 0; s < 2; ++s) {
;             const bf16x8_t pf = pack8(sacc, 8 * s);
; #pragma unroll
;             for (int dt = 0; dt < 2; ++dt) {
;                 const LAS unsigned char* vp = Vb + (32 * dt + r) * A_CVSTR + (32 * mt + 16 * s + 4 * h) * 2;
;                 const s16x4_t lo = *(const LAS s16x4_t*)vp, hi = *(const LAS s16x4_t*)(vp + 16);
;                 oacc[dt] = MFMA32(__builtin_shufflevector(lo, hi, 0, 1, 2, 3, 4, 5, 6, 7), pf, oacc[dt]);
;             }
;         }
;     }
;     l_run += ls;
	v_mfma_f32_32x32x16_bf16 v[0:15], v[216:219], v[64:67], v[0:15]
	ds_read2_b64 v[216:219], v73 offset0:16 offset1:18
	v_exp_f32_e32 v60, v60
	v_exp_f32_e32 v61, v61
	v_add_f32_e32 v232, v232, v58
	v_add_f32_e32 v233, v233, v59
	v_cvt_pk_bf16_f32 v69, v58, v59
	s_waitcnt lgkmcnt(7)
	v_mfma_f32_32x32x16_bf16 v[16:31], v[220:223], v[64:67], v[16:31]
	ds_read2_b64 v[220:223], v74 offset0:48 offset1:50
	v_exp_f32_e32 v62, v62
	v_exp_f32_e32 v63, v63
	v_add_f32_e32 v232, v232, v60
	v_add_f32_e32 v233, v233, v61
	v_cvt_pk_bf16_f32 v70, v60, v61
	v_add_f32_e32 v232, v232, v62
	v_add_f32_e32 v233, v233, v63
	v_cvt_pk_bf16_f32 v71, v62, v63
	s_waitcnt lgkmcnt(7)
	v_mfma_f32_32x32x16_bf16 v[48:63], v[200:203], v[80:83], 0
	v_exp_f32_e32 v32, v32
	v_exp_f32_e32 v33, v33
	s_waitcnt lgkmcnt(6)
	v_mfma_f32_32x32x16_bf16 v[48:63], v[204:207], v[84:87], v[48:63]
	v_exp_f32_e32 v34, v34
	v_exp_f32_e32 v35, v35
	v_add_f32_e32 v232, v232, v32
	v_add_f32_e32 v233, v233, v33
	v_cvt_pk_bf16_f32 v64, v32, v33
	s_waitcnt lgkmcnt(5)
	v_mfma_f32_32x32x16_bf16 v[0:15], v[224:227], v[68:71], v[0:15]
	ds_read2_b64 v[224:227], v73 offset0:20 offset1:22
	v_exp_f32_e32 v36, v36
	v_exp_f32_e32 v37, v37
	v_add_f32_e32 v232, v232, v34
	v_add_f32_e32 v233, v233, v35
	v_cvt_pk_bf16_f32 v65, v34, v35
	s_waitcnt lgkmcnt(5)
	v_mfma_f32_32x32x16_bf16 v[16:31], v[228:231], v[68:71], v[16:31]
	ds_read2_b64 v[228:231], v74 offset0:52 offset1:54
	v_exp_f32_e32 v38, v38
	v_exp_f32_e32 v39, v39
	v_add_f32_e32 v232, v232, v36
	v_add_f32_e32 v233, v233, v37
	v_cvt_pk_bf16_f32 v66, v36, v37
	v_add_f32_e32 v232, v232, v38
	v_add_f32_e32 v233, v233, v39
	v_cvt_pk_bf16_f32 v67, v38, v39
	s_waitcnt lgkmcnt(5)
	v_mfma_f32_32x32x16_bf16 v[48:63], v[208:211], v[88:91], v[48:63]
	v_exp_f32_e32 v40, v40
	v_exp_f32_e32 v41, v41
	s_waitcnt lgkmcnt(4)
	v_mfma_f32_32x32x16_bf16 v[48:63], v[212:215], v[92:95], v[48:63]
	v_exp_f32_e32 v42, v42
	v_exp_f32_e32 v43, v43
	v_add_f32_e32 v232, v232, v40
	v_add_f32_e32 v233, v233, v41
	v_cvt_pk_bf16_f32 v68, v40, v41
	s_waitcnt lgkmcnt(3)
	v_mfma_f32_32x32x16_bf16 v[0:15], v[216:219], v[64:67], v[0:15]
	ds_read2_b64 v[216:219], v73 offset0:24 offset1:26
	v_exp_f32_e32 v44, v44
	v_exp_f32_e32 v45, v45
	v_add_f32_e32 v232, v232, v42
	v_add_f32_e32 v233, v233, v43
	v_cvt_pk_bf16_f32 v69, v42, v43
	s_waitcnt lgkmcnt(3)
	v_mfma_f32_32x32x16_bf16 v[16:31], v[220:223], v[64:67], v[16:31]
	ds_read2_b64 v[220:223], v74 offset0:56 offset1:58
	v_exp_f32_e32 v46, v46
	v_exp_f32_e32 v47, v47
	v_add_f32_e32 v232, v232, v44
	v_add_f32_e32 v233, v233, v45
	v_cvt_pk_bf16_f32 v70, v44, v45
	v_add_f32_e32 v232, v232, v46
	v_add_f32_e32 v233, v233, v47
	v_cvt_pk_bf16_f32 v71, v46, v47
	v_exp_f32_e32 v48, v48
	v_exp_f32_e32 v49, v49
	v_exp_f32_e32 v50, v50
	v_exp_f32_e32 v51, v51
	v_add_f32_e32 v232, v232, v48
	v_add_f32_e32 v233, v233, v49
	v_cvt_pk_bf16_f32 v64, v48, v49
	s_waitcnt lgkmcnt(3)
	v_mfma_f32_32x32x16_bf16 v[0:15], v[224:227], v[68:71], v[0:15]
	ds_read2_b64 v[224:227], v73 offset0:28 offset1:30
	v_exp_f32_e32 v52, v52
	v_exp_f32_e32 v53, v53
	v_add_f32_e32 v232, v232, v50
	v_add_f32_e32 v233, v233, v51
	v_cvt_pk_bf16_f32 v65, v50, v51
	s_waitcnt lgkmcnt(3)
	v_mfma_f32_32x32x16_bf16 v[16:31], v[228:231], v[68:71], v[16:31]
	ds_read2_b64 v[228:231], v74 offset0:60 offset1:62
	v_exp_f32_e32 v54, v54
	v_exp_f32_e32 v55, v55
	v_add_f32_e32 v232, v232, v52
	v_add_f32_e32 v233, v233, v53
	v_cvt_pk_bf16_f32 v66, v52, v53
	v_add_f32_e32 v232, v232, v54
	v_add_f32_e32 v233, v233, v55
	v_cvt_pk_bf16_f32 v67, v54, v55
	v_exp_f32_e32 v56, v56
	v_exp_f32_e32 v57, v57
	v_exp_f32_e32 v58, v58
	v_exp_f32_e32 v59, v59
	v_add_f32_e32 v232, v232, v56
	v_add_f32_e32 v233, v233, v57
	v_cvt_pk_bf16_f32 v68, v56, v57
	s_waitcnt lgkmcnt(3)
	v_mfma_f32_32x32x16_bf16 v[0:15], v[216:219], v[64:67], v[0:15]
	v_exp_f32_e32 v60, v60
	v_exp_f32_e32 v61, v61
	v_add_f32_e32 v232, v232, v58
	v_add_f32_e32 v233, v233, v59
	v_cvt_pk_bf16_f32 v69, v58, v59
	s_waitcnt lgkmcnt(2)
	v_mfma_f32_32x32x16_bf16 v[16:31], v[220:223], v[64:67], v[16:31]
	v_exp_f32_e32 v62, v62
	v_exp_f32_e32 v63, v63
	v_add_f32_e32 v232, v232, v60
	v_add_f32_e32 v233, v233, v61
	v_cvt_pk_bf16_f32 v70, v60, v61
	v_add_f32_e32 v232, v232, v62
	v_add_f32_e32 v233, v233, v63
	v_cvt_pk_bf16_f32 v71, v62, v63
	s_nop 1
	s_waitcnt lgkmcnt(1)
	v_mfma_f32_32x32x16_bf16 v[0:15], v[224:227], v[68:71], v[0:15]
	s_waitcnt lgkmcnt(0)
	v_mfma_f32_32x32x16_bf16 v[16:31], v[228:231], v[68:71], v[16:31]
	v_add_f32_e32 v232, v232, v233
	v_add_f32_e32 v112, v112, v232
	s_branch .Lt1_join
; #define LAS __attribute__((address_space(3)))
; #define MFMA32(a, b, c) __builtin_amdgcn_mfma_f32_32x32x16_bf16((a), (b), (c), 0, 0, 0)
; __device__ __forceinline__ float ex2(float x) { return __builtin_amdgcn_exp2f(x); }
; template <int MODE>
; __device__ __forceinline__ void attn_tile(const LAS unsigned char* Kb, const LAS unsigned char* Vb, const bf16x8_t (&qf)[4], f32x16 (&oacc)[2], float& l_run,
;                                           int r, int h, int dlt0, int dlt1, bool hiw) {
;     ...
;     for (int mt = 0; mt < 4; ++mt) {
;         if (mt == 0) { if (hiw) __builtin_amdgcn_s_setprio(1); else __builtin_amdgcn_s_setprio(0); }
;         if (mt == 2) { if (hiw) __builtin_amdgcn_s_setprio(0); else __builtin_amdgcn_s_setprio(1); }
;         const int dl = mt < 2 ? dlt0 : dlt1;
;         f32x16 sacc = zero16();
; #pragma unroll
;         for (int ks = 0; ks < 4; ++ks) { const bf16x8_t ka = *(const LAS bf16x8_t*)(Kb + (32 * mt + r) * A_KSTR + 32 * ks + 16 * h); sacc = MFMA32(ka, qf[ks], sacc); }
; #pragma unroll
;         for (int i = 0; i < 16; ++i) {
;             float p;
;             if (MODE == 2) p = ex2(sacc[i]);
;             else if (MODE == 3) p = ex2(sacc[i] + __int_as_float(dl));
;             else { const int ci = 32 * mt + (i & 3) + 8 * (i >> 2); p = ((unsigned)(dl - ci) < ulim) ? ex2(sacc[i]) : 0.f; }
;             sacc[i] = p; ls += p;
;         }
; #pragma unroll
;         for (int s = 0; s < 2; ++s) {
;             const bf16x8_t pf = pack8(sacc, 8 * s);
; #pragma unroll
;             for (int dt = 0; dt < 2; ++dt) {
;                 const LAS unsigned char* vp = Vb + (32 * dt + r) * A_CVSTR + (32 * mt + 16 * s + 4 * h) * 2;
;                 const s16x4_t lo = *(const LAS s16x4_t*)vp, hi = *(const LAS s16x4_t*)(vp + 16);
;                 oacc[dt] = MFMA32(__builtin_shufflevector(lo, hi, 0, 1, 2, 3, 4, 5, 6, 7), pf, oacc[dt]);
;             }
;         }
;     }
;     l_run += ls;
.Lt1_e1:
	ds_read_b128 v[200:203], v72 offset:4608
	ds_read_b128 v[204:207], v72 offset:4640
	ds_read_b128 v[208:211], v72 offset:4672
	ds_read_b128 v[212:215], v72 offset:4704
	ds_read2_b64 v[216:219], v73 offset0:8 offset1:10
	ds_read2_b64 v[220:223], v74 offset0:40 offset1:42
	ds_read2_b64 v[224:227], v73 offset0:12 offset1:14
	ds_read2_b64 v[228:231], v74 offset0:44 offset1:46
	s_waitcnt lgkmcnt(7)
	v_mfma_f32_32x32x16_bf16 v[32:47], v[200:203], v[80:83], 0
	ds_read_b128 v[200:203], v72 offset:9216
	s_waitcnt lgkmcnt(7)
	v_mfma_f32_32x32x16_bf16 v[32:47], v[204:207], v[84:87], v[32:47]
	ds_read_b128 v[204:207], v72 offset:9248
	s_waitcnt lgkmcnt(7)
	v_mfma_f32_32x32x16_bf16 v[32:47], v[208:211], v[88:91], v[32:47]
	ds_read_b128 v[208:211], v72 offset:9280
	s_waitcnt lgkmcnt(7)
	v_mfma_f32_32x32x16_bf16 v[32:47], v[212:215], v[92:95], v[32:47]
	ds_read_b128 v[212:215], v72 offset:9312
	s_nop 7
	s_nop 3
	s_waitcnt lgkmcnt(3)
	v_mfma_f32_32x32x16_bf16 v[48:63], v[200:203], v[80:83], 0
	ds_read_b128 v[200:203], v72 offset:13824
	v_cmp_le_i32_e64 s[0:1], 0, v250
	v_cmp_le_i32_e64 s[4:5], 1, v250
	v_exp_f32_e32 v32, v32
	v_exp_f32_e32 v33, v33
	s_waitcnt lgkmcnt(3)
	v_mfma_f32_32x32x16_bf16 v[48:63], v[204:207], v[84:87], v[48:63]
	ds_read_b128 v[204:207], v72 offset:13856
	v_cmp_le_i32_e64 s[6:7], 2, v250
	v_cmp_le_i32_e64 s[48:49], 3, v250
	v_exp_f32_e32 v34, v34
	v_exp_f32_e32 v35, v35
	v_cndmask_b32_e64 v32, v32, 0, s[0:1]
	v_cndmask_b32_e64 v33, v33, 0, s[4:5]
	v_mov_b32_e32 v232, v32
	v_mov_b32_e32 v233, v33
	v_cvt_pk_bf16_f32 v64, v32, v33
	v_cmp_le_i32_e64 s[0:1], 8, v250
	v_cmp_le_i32_e64 s[4:5], 9, v250
	v_exp_f32_e32 v36, v36
	v_exp_f32_e32 v37, v37
	v_cndmask_b32_e64 v34, v34, 0, s[6:7]
	v_cndmask_b32_e64 v35, v35, 0, s[48:49]
	v_add_f32_e32 v232, v232, v34
	v_add_f32_e32 v233, v233, v35
	v_cvt_pk_bf16_f32 v65, v34, v35
	v_cmp_le_i32_e64 s[6:7], 10, v250
	v_cmp_le_i32_e64 s[48:49], 11, v250
	v_exp_f32_e32 v38, v38
	v_exp_f32_e32 v39, v39
	v_cndmask_b32_e64 v36, v36, 0, s[0:1]
	v_cndmask_b32_e64 v37, v37, 0, s[4:5]
	v_add_f32_e32 v232, v232, v36
	v_add_f32_e32 v233, v233, v37
	v_cvt_pk_bf16_f32 v66, v36, v37
	v_cndmask_b32_e64 v38, v38, 0, s[6:7]
	v_cndmask_b32_e64 v39, v39, 0, s[48:49]
	v_add_f32_e32 v232, v232, v38
	v_add_f32_e32 v233, v233, v39
	v_cvt_pk_bf16_f32 v67, v38, v39
	s_waitcnt lgkmcnt(3)
	v_mfma_f32_32x32x16_bf16 v[48:63], v[208:211], v[88:91], v[48:63]
	ds_read_b128 v[208:211], v72 offset:13888
	v_cmp_le_i32_e64 s[0:1], 16, v250
	v_cmp_le_i32_e64 s[4:5], 17, v250
	v_exp_f32_e32 v40, v40
	v_exp_f32_e32 v41, v41
	s_waitcnt lgkmcnt(3)
	v_mfma_f32_32x32x16_bf16 v[48:63], v[212:215], v[92:95], v[48:63]
	ds_read_b128 v[212:215], v72 offset:13920
	v_cmp_le_i32_e64 s[6:7], 18, v250
	v_cmp_le_i32_e64 s[48:49], 19, v250
	v_exp_f32_e32 v42, v42
	v_exp_f32_e32 v43, v43
	v_cndmask_b32_e64 v40, v40, 0, s[0:1]
	v_cndmask_b32_e64 v41, v41, 0, s[4:5]
	v_add_f32_e32 v232, v232, v40
	v_add_f32_e32 v233, v233, v41
	v_cvt_pk_bf16_f32 v68, v40, v41
	s_waitcnt lgkmcnt(11)
	v_mfma_f32_32x32x16_bf16 v[0:15], v[216:219], v[64:67], v[0:15]
	ds_read2_b64 v[216:219], v73 offset0:16 offset1:18
	v_cmp_le_i32_e64 s[0:1], 24, v250
	v_cmp_le_i32_e64 s[4:5], 25, v250
	v_exp_f32_e32 v44, v44
	v_exp_f32_e32 v45, v45
	v_cndmask_b32_e64 v42, v42, 0, s[6:7]
	v_cndmask_b32_e64 v43, v43, 0, s[48:49]
	v_add_f32_e32 v232, v232, v42
	v_add_f32_e32 v233, v233, v43
	v_cvt_pk_bf16_f32 v69, v42, v43
	s_waitcnt lgkmcnt(11)
	v_mfma_f32_32x32x16_bf16 v[16:31], v[220:223], v[64:67], v[16:31]
	ds_read2_b64 v[220:223], v74 offset0:48 offset1:50
	v_cmp_le_i32_e64 s[6:7], 26, v250
	v_cmp_le_i32_e64 s[48:49], 27, v250
	v_exp_f32_e32 v46, v46
	v_exp_f32_e32 v47, v47
	v_cndmask_b32_e64 v44, v44, 0, s[0:1]
	v_cndmask_b32_e64 v45, v45, 0, s[4:5]
	v_add_f32_e32 v232, v232, v44
	v_add_f32_e32 v233, v233, v45
	v_cvt_pk_bf16_f32 v70, v44, v45
	v_cndmask_b32_e64 v46, v46, 0, s[6:7]
	v_cndmask_b32_e64 v47, v47, 0, s[48:49]
	v_add_f32_e32 v232, v232, v46
	v_add_f32_e32 v233, v233, v47
	v_cvt_pk_bf16_f32 v71, v46, v47
	s_waitcnt lgkmcnt(5)
	v_mfma_f32_32x32x16_bf16 v[32:47], v[200:203], v[80:83], 0
	v_exp_f32_e32 v48, v48
	v_exp_f32_e32 v49, v49
	s_waitcnt lgkmcnt(4)
	v_mfma_f32_32x32x16_bf16 v[32:47], v[204:207], v[84:87], v[32:47]
	v_exp_f32_e32 v50, v50
	v_exp_f32_e32 v51, v51
	v_add_f32_e32 v232, v232, v48
	v_add_f32_e32 v233, v233, v49
	v_cvt_pk_bf16_f32 v64, v48, v49
	s_waitcnt lgkmcnt(11)
	v_mfma_f32_32x32x16_bf16 v[0:15], v[224:227], v[68:71], v[0:15]
	ds_read2_b64 v[224:227], v73 offset0:20 offset1:22
	v_exp_f32_e32 v52, v52
	v_exp_f32_e32 v53, v53
	v_add_f32_e32 v232, v232, v50
	v_add_f32_e32 v233, v233, v51
	v_cvt_pk_bf16_f32 v65, v50, v51
	s_waitcnt lgkmcnt(11)
	v_mfma_f32_32x32x16_bf16 v[16:31], v[228:231], v[68:71], v[16:31]
	ds_read2_b64 v[228:231], v74 offset0:52 offset1:54
	v_exp_f32_e32 v54, v54
	v_exp_f32_e32 v55, v55
	v_add_f32_e32 v232, v232, v52
	v_add_f32_e32 v233, v233, v53
	v_cvt_pk_bf16_f32 v66, v52, v53
	v_add_f32_e32 v232, v232, v54
	v_add_f32_e32 v233, v233, v55
	v_cvt_pk_bf16_f32 v67, v54, v55
	s_waitcnt lgkmcnt(5)
	v_mfma_f32_32x32x16_bf16 v[32:47], v[208:211], v[88:91], v[32:47]
	v_exp_f32_e32 v56, v56
	v_exp_f32_e32 v57, v57
	s_waitcnt lgkmcnt(4)
	v_mfma_f32_32x32x16_bf16 v[32:47], v[212:215], v[92:95], v[32:47]
	v_exp_f32_e32 v58, v58
	v_exp_f32_e32 v59, v59
	v_add_f32_e32 v232, v232, v56
	v_add_f32_e32 v233, v233, v57
	v_cvt_pk_bf16_f32 v68, v56, v57
	s_waitcnt lgkmcnt(3)
	v_mfma_f32_32x32x16_bf16 v[0:15], v[216:219], v[64:67], v[0:15]
	ds_read2_b64 v[216:219], v73 offset0:24 offset1:26
	v_exp_f32_e32 v60, v60
	v_exp_f32_e32 v61, v61
	v_add_f32_e32 v232, v232, v58
	v_add_f32_e32 v233, v233, v59
	v_cvt_pk_bf16_f32 v69, v58, v59
	s_waitcnt lgkmcnt(3)
; #define LAS __attribute__((address_space(3)))
; #define MFMA32(a, b, c) __builtin_amdgcn_mfma_f32_32x32x16_bf16((a), (b), (c), 0, 0, 0)
; __device__ __forceinline__ float ex2(float x) { return __builtin_amdgcn_exp2f(x); }
; template <int MODE>
; __device__ __forceinline__ void attn_tile(const LAS unsigned char* Kb, const LAS unsigned char* Vb, const bf16x8_t (&qf)[4], f32x16 (&oacc)[2], float& l_run,
;                                           int r, int h, int dlt0, int dlt1, bool hiw) {
;     ...
;     for (int mt = 0; mt < 4; ++mt) {
;         if (mt == 0) { if (hiw) __builtin_amdgcn_s_setprio(1); else __builtin_amdgcn_s_setprio(0); }
;         if (mt == 2) { if (hiw) __builtin_amdgcn_s_setprio(0); else __builtin_amdgcn_s_setprio(1); }
;         const int dl = mt < 2 ? dlt0 : dlt1;
;         f32x16 sacc = zero16();
; #pragma unroll
;         for (int ks = 0; ks < 4; ++ks) { const bf16x8_t ka = *(const LAS bf16x8_t*)(Kb + (32 * mt + r) * A_KSTR + 32 * ks + 16 * h); sacc = MFMA32(ka, qf[ks], sacc); }
; #pragma unroll
;         for (int i = 0; i < 16; ++i) {
;             float p;
;             if (MODE == 2) p = ex2(sacc[i]);
;             else if (MODE == 3) p = ex2(sacc[i] + __int_as_float(dl));
;             else { const int ci = 32 * mt + (i & 3) + 8 * (i >> 2); p = ((unsigned)(dl - ci) < ulim) ? ex2(sacc[i]) : 0.f; }
;             sacc[i] = p; ls += p;
;         }
; #pragma unroll
;         for (int s = 0; s < 2; ++s) {
;             const bf16x8_t pf = pack8(sacc, 8 * s);
; #pragma unroll
;             for (int dt = 0; dt < 2; ++dt) {
;                 const LAS unsigned char* vp = Vb + (32 * dt + r) * A_CVSTR + (32 * mt + 16 * s + 4 * h) * 2;
;                 const s16x4_t lo = *(const LAS s16x4_t*)vp, hi = *(const LAS s16x4_t*)(vp + 16);
;                 oacc[dt] = MFMA32(__builtin_shufflevector(lo, hi, 0, 1, 2, 3, 4, 5, 6, 7), pf, oacc[dt]);
;             }
;         }
;     }
;     l_run += ls;
	v_mfma_f32_32x32x16_bf16 v[16:31], v[220:223], v[64:67], v[16:31]
	ds_read2_b64 v[220:223], v74 offset0:56 offset1:58
	v_exp_f32_e32 v62, v62
	v_exp_f32_e32 v63, v63
	v_add_f32_e32 v232, v232, v60
	v_add_f32_e32 v233, v233, v61
	v_cvt_pk_bf16_f32 v70, v60, v61
	v_add_f32_e32 v232, v232, v62
	v_add_f32_e32 v233, v233, v63
	v_cvt_pk_bf16_f32 v71, v62, v63
	v_exp_f32_e32 v32, v32
	v_exp_f32_e32 v33, v33
	v_exp_f32_e32 v34, v34
	v_exp_f32_e32 v35, v35
	v_add_f32_e32 v232, v232, v32
	v_add_f32_e32 v233, v233, v33
	v_cvt_pk_bf16_f32 v64, v32, v33
	s_waitcnt lgkmcnt(3)
	v_mfma_f32_32x32x16_bf16 v[0:15], v[224:227], v[68:71], v[0:15]
	ds_read2_b64 v[224:227], v73 offset0:28 offset1:30
	v_exp_f32_e32 v36, v36
	v_exp_f32_e32 v37, v37
	v_add_f32_e32 v232, v232, v34
	v_add_f32_e32 v233, v233, v35
	v_cvt_pk_bf16_f32 v65, v34, v35
	s_waitcnt lgkmcnt(3)
	v_mfma_f32_32x32x16_bf16 v[16:31], v[228:231], v[68:71], v[16:31]
	ds_read2_b64 v[228:231], v74 offset0:60 offset1:62
	v_exp_f32_e32 v38, v38
	v_exp_f32_e32 v39, v39
	v_add_f32_e32 v232, v232, v36
	v_add_f32_e32 v233, v233, v37
	v_cvt_pk_bf16_f32 v66, v36, v37
	v_add_f32_e32 v232, v232, v38
	v_add_f32_e32 v233, v233, v39
	v_cvt_pk_bf16_f32 v67, v38, v39
	v_exp_f32_e32 v40, v40
	v_exp_f32_e32 v41, v41
	v_exp_f32_e32 v42, v42
	v_exp_f32_e32 v43, v43
	v_add_f32_e32 v232, v232, v40
	v_add_f32_e32 v233, v233, v41
	v_cvt_pk_bf16_f32 v68, v40, v41
	s_waitcnt lgkmcnt(3)
	v_mfma_f32_32x32x16_bf16 v[0:15], v[216:219], v[64:67], v[0:15]
	v_exp_f32_e32 v44, v44
	v_exp_f32_e32 v45, v45
	v_add_f32_e32 v232, v232, v42
	v_add_f32_e32 v233, v233, v43
	v_cvt_pk_bf16_f32 v69, v42, v43
	s_waitcnt lgkmcnt(2)
	v_mfma_f32_32x32x16_bf16 v[16:31], v[220:223], v[64:67], v[16:31]
	v_exp_f32_e32 v46, v46
	v_exp_f32_e32 v47, v47
	v_add_f32_e32 v232, v232, v44
	v_add_f32_e32 v233, v233, v45
	v_cvt_pk_bf16_f32 v70, v44, v45
	v_add_f32_e32 v232, v232, v46
	v_add_f32_e32 v233, v233, v47
	v_cvt_pk_bf16_f32 v71, v46, v47
	s_nop 1
	s_waitcnt lgkmcnt(1)
	v_mfma_f32_32x32x16_bf16 v[0:15], v[224:227], v[68:71], v[0:15]
	s_waitcnt lgkmcnt(0)
	v_mfma_f32_32x32x16_bf16 v[16:31], v[228:231], v[68:71], v[16:31]
	v_add_f32_e32 v232, v232, v233
	v_add_f32_e32 v112, v112, v232
	s_branch .Lt1_join
.Lt1_e2:
	ds_read_b128 v[200:203], v72 offset:9216
	ds_read_b128 v[204:207], v72 offset:9248
	ds_read_b128 v[208:211], v72 offset:9280
	ds_read_b128 v[212:215], v72 offset:9312
	ds_read2_b64 v[216:219], v73 offset0:16 offset1:18
	ds_read2_b64 v[220:223], v74 offset0:48 offset1:50
	ds_read2_b64 v[224:227], v73 offset0:20 offset1:22
	ds_read2_b64 v[228:231], v74 offset0:52 offset1:54
	s_waitcnt lgkmcnt(7)
	v_mfma_f32_32x32x16_bf16 v[32:47], v[200:203], v[80:83], 0
	ds_read_b128 v[200:203], v72 offset:13824
	s_waitcnt lgkmcnt(7)
	v_mfma_f32_32x32x16_bf16 v[32:47], v[204:207], v[84:87], v[32:47]
	ds_read_b128 v[204:207], v72 offset:13856
	s_waitcnt lgkmcnt(7)
	v_mfma_f32_32x32x16_bf16 v[32:47], v[208:211], v[88:91], v[32:47]
	ds_read_b128 v[208:211], v72 offset:13888
	s_waitcnt lgkmcnt(7)
	v_mfma_f32_32x32x16_bf16 v[32:47], v[212:215], v[92:95], v[32:47]
	ds_read_b128 v[212:215], v72 offset:13920
	s_nop 7
	s_nop 3
	s_waitcnt lgkmcnt(3)
	v_mfma_f32_32x32x16_bf16 v[48:63], v[200:203], v[80:83], 0
	v_cmp_le_i32_e64 s[0:1], 0, v250
	v_cmp_le_i32_e64 s[4:5], 1, v250
	v_exp_f32_e32 v32, v32
	v_exp_f32_e32 v33, v33
	s_waitcnt lgkmcnt(2)
	v_mfma_f32_32x32x16_bf16 v[48:63], v[204:207], v[84:87], v[48:63]
	v_cmp_le_i32_e64 s[6:7], 2, v250
	v_cmp_le_i32_e64 s[48:49], 3, v250
	v_exp_f32_e32 v34, v34
	v_exp_f32_e32 v35, v35
	v_cndmask_b32_e64 v32, v32, 0, s[0:1]
	v_cndmask_b32_e64 v33, v33, 0, s[4:5]
	v_mov_b32_e32 v232, v32
	v_mov_b32_e32 v233, v33
	v_cvt_pk_bf16_f32 v64, v32, v33
	v_cmp_le_i32_e64 s[0:1], 8, v250
	v_cmp_le_i32_e64 s[4:5], 9, v250
	v_exp_f32_e32 v36, v36
	v_exp_f32_e32 v37, v37
	v_cndmask_b32_e64 v34, v34, 0, s[6:7]
	v_cndmask_b32_e64 v35, v35, 0, s[48:49]
	v_add_f32_e32 v232, v232, v34
	v_add_f32_e32 v233, v233, v35
	v_cvt_pk_bf16_f32 v65, v34, v35
	v_cmp_le_i32_e64 s[6:7], 10, v250
	v_cmp_le_i32_e64 s[48:49], 11, v250
	v_exp_f32_e32 v38, v38
	v_exp_f32_e32 v39, v39
	v_cndmask_b32_e64 v36, v36, 0, s[0:1]
	v_cndmask_b32_e64 v37, v37, 0, s[4:5]
	v_add_f32_e32 v232, v232, v36
	v_add_f32_e32 v233, v233, v37
	v_cvt_pk_bf16_f32 v66, v36, v37
	v_cndmask_b32_e64 v38, v38, 0, s[6:7]
	v_cndmask_b32_e64 v39, v39, 0, s[48:49]
	v_add_f32_e32 v232, v232, v38
	v_add_f32_e32 v233, v233, v39
	v_cvt_pk_bf16_f32 v67, v38, v39
	s_waitcnt lgkmcnt(1)
	v_mfma_f32_32x32x16_bf16 v[48:63], v[208:211], v[88:91], v[48:63]
	v_cmp_le_i32_e64 s[0:1], 16, v250
	v_cmp_le_i32_e64 s[4:5], 17, v250
	v_exp_f32_e32 v40, v40
	v_exp_f32_e32 v41, v41
	s_waitcnt lgkmcnt(0)
	v_mfma_f32_32x32x16_bf16 v[48:63], v[212:215], v[92:95], v[48:63]
	v_cmp_le_i32_e64 s[6:7], 18, v250
	v_cmp_le_i32_e64 s[48:49], 19, v250
	v_exp_f32_e32 v42, v42
	v_exp_f32_e32 v43, v43
	v_cndmask_b32_e64 v40, v40, 0, s[0:1]
	v_cndmask_b32_e64 v41, v41, 0, s[4:5]
	v_add_f32_e32 v232, v232, v40
	v_add_f32_e32 v233, v233, v41
	v_cvt_pk_bf16_f32 v68, v40, v41
	s_waitcnt lgkmcnt(7)
	v_mfma_f32_32x32x16_bf16 v[0:15], v[216:219], v[64:67], v[0:15]
	ds_read2_b64 v[216:219], v73 offset0:24 offset1:26
	v_cmp_le_i32_e64 s[0:1], 24, v250
	v_cmp_le_i32_e64 s[4:5], 25, v250
	v_exp_f32_e32 v44, v44
	v_exp_f32_e32 v45, v45
	v_cndmask_b32_e64 v42, v42, 0, s[6:7]
	v_cndmask_b32_e64 v43, v43, 0, s[48:49]
	v_add_f32_e32 v232, v232, v42
	v_add_f32_e32 v233, v233, v43
	v_cvt_pk_bf16_f32 v69, v42, v43
	s_waitcnt lgkmcnt(7)
; #define LAS __attribute__((address_space(3)))
; #define MFMA32(a, b, c) __builtin_amdgcn_mfma_f32_32x32x16_bf16((a), (b), (c), 0, 0, 0)
; __device__ __forceinline__ float ex2(float x) { return __builtin_amdgcn_exp2f(x); }
; template <int MODE>
; __device__ __forceinline__ void attn_tile(const LAS unsigned char* Kb, const LAS unsigned char* Vb, const bf16x8_t (&qf)[4], f32x16 (&oacc)[2], float& l_run,
;                                           int r, int h, int dlt0, int dlt1, bool hiw) {
;     ...
;     for (int mt = 0; mt < 4; ++mt) {
;         if (mt == 0) { if (hiw) __builtin_amdgcn_s_setprio(1); else __builtin_amdgcn_s_setprio(0); }
;         if (mt == 2) { if (hiw) __builtin_amdgcn_s_setprio(0); else __builtin_amdgcn_s_setprio(1); }
;         const int dl = mt < 2 ? dlt0 : dlt1;
;         f32x16 sacc = zero16();
; #pragma unroll
;         for (int ks = 0; ks < 4; ++ks) { const bf16x8_t ka = *(const LAS bf16x8_t*)(Kb + (32 * mt + r) * A_KSTR + 32 * ks + 16 * h); sacc = MFMA32(ka, qf[ks], sacc); }
; #pragma unroll
;         for (int i = 0; i < 16; ++i) {
;             float p;
;             if (MODE == 2) p = ex2(sacc[i]);
;             else if (MODE == 3) p = ex2(sacc[i] + __int_as_float(dl));
;             else { const int ci = 32 * mt + (i & 3) + 8 * (i >> 2); p = ((unsigned)(dl - ci) < ulim) ? ex2(sacc[i]) : 0.f; }
;             sacc[i] = p; ls += p;
;         }
; #pragma unroll
;         for (int s = 0; s < 2; ++s) {
;             const bf16x8_t pf = pack8(sacc, 8 * s);
; #pragma unroll
;             for (int dt = 0; dt < 2; ++dt) {
;                 const LAS unsigned char* vp = Vb + (32 * dt + r) * A_CVSTR + (32 * mt + 16 * s + 4 * h) * 2;
;                 const s16x4_t lo = *(const LAS s16x4_t*)vp, hi = *(const LAS s16x4_t*)(vp + 16);
;                 oacc[dt] = MFMA32(__builtin_shufflevector(lo, hi, 0, 1, 2, 3, 4, 5, 6, 7), pf, oacc[dt]);
;             }
;         }
;     }
;     l_run += ls;
	v_mfma_f32_32x32x16_bf16 v[16:31], v[220:223], v[64:67], v[16:31]
	ds_read2_b64 v[220:223], v74 offset0:56 offset1:58
	v_cmp_le_i32_e64 s[6:7], 26, v250
	v_cmp_le_i32_e64 s[48:49], 27, v250
	v_exp_f32_e32 v46, v46
	v_exp_f32_e32 v47, v47
	v_cndmask_b32_e64 v44, v44, 0, s[0:1]
	v_cndmask_b32_e64 v45, v45, 0, s[4:5]
	v_add_f32_e32 v232, v232, v44
	v_add_f32_e32 v233, v233, v45
	v_cvt_pk_bf16_f32 v70, v44, v45
	v_cndmask_b32_e64 v46, v46, 0, s[6:7]
	v_cndmask_b32_e64 v47, v47, 0, s[48:49]
	v_add_f32_e32 v232, v232, v46
	v_add_f32_e32 v233, v233, v47
	v_cvt_pk_bf16_f32 v71, v46, v47
	v_exp_f32_e32 v48, v48
	v_exp_f32_e32 v49, v49
	v_exp_f32_e32 v50, v50
	v_exp_f32_e32 v51, v51
	v_add_f32_e32 v232, v232, v48
	v_add_f32_e32 v233, v233, v49
	v_cvt_pk_bf16_f32 v64, v48, v49
	s_waitcnt lgkmcnt(7)
	v_mfma_f32_32x32x16_bf16 v[0:15], v[224:227], v[68:71], v[0:15]
	ds_read2_b64 v[224:227], v73 offset0:28 offset1:30
	v_exp_f32_e32 v52, v52
	v_exp_f32_e32 v53, v53
	v_add_f32_e32 v232, v232, v50
	v_add_f32_e32 v233, v233, v51
	v_cvt_pk_bf16_f32 v65, v50, v51
	s_waitcnt lgkmcnt(7)
	v_mfma_f32_32x32x16_bf16 v[16:31], v[228:231], v[68:71], v[16:31]
	ds_read2_b64 v[228:231], v74 offset0:60 offset1:62
	v_exp_f32_e32 v54, v54
	v_exp_f32_e32 v55, v55
	v_add_f32_e32 v232, v232, v52
	v_add_f32_e32 v233, v233, v53
	v_cvt_pk_bf16_f32 v66, v52, v53
	v_add_f32_e32 v232, v232, v54
	v_add_f32_e32 v233, v233, v55
	v_cvt_pk_bf16_f32 v67, v54, v55
	v_exp_f32_e32 v56, v56
	v_exp_f32_e32 v57, v57
	v_exp_f32_e32 v58, v58
	v_exp_f32_e32 v59, v59
	v_add_f32_e32 v232, v232, v56
	v_add_f32_e32 v233, v233, v57
	v_cvt_pk_bf16_f32 v68, v56, v57
	s_waitcnt lgkmcnt(3)
	v_mfma_f32_32x32x16_bf16 v[0:15], v[216:219], v[64:67], v[0:15]
	v_exp_f32_e32 v60, v60
	v_exp_f32_e32 v61, v61
	v_add_f32_e32 v232, v232, v58
	v_add_f32_e32 v233, v233, v59
	v_cvt_pk_bf16_f32 v69, v58, v59
	s_waitcnt lgkmcnt(2)
	v_mfma_f32_32x32x16_bf16 v[16:31], v[220:223], v[64:67], v[16:31]
	v_exp_f32_e32 v62, v62
	v_exp_f32_e32 v63, v63
	v_add_f32_e32 v232, v232, v60
	v_add_f32_e32 v233, v233, v61
	v_cvt_pk_bf16_f32 v70, v60, v61
	v_add_f32_e32 v232, v232, v62
	v_add_f32_e32 v233, v233, v63
	v_cvt_pk_bf16_f32 v71, v62, v63
	s_nop 1
	s_waitcnt lgkmcnt(1)
	v_mfma_f32_32x32x16_bf16 v[0:15], v[224:227], v[68:71], v[0:15]
	s_waitcnt lgkmcnt(0)
	v_mfma_f32_32x32x16_bf16 v[16:31], v[228:231], v[68:71], v[16:31]
	v_add_f32_e32 v232, v232, v233
	v_add_f32_e32 v112, v112, v232
	s_branch .Lt1_join
.Lt1_e3:
	ds_read_b128 v[200:203], v72 offset:13824
	ds_read_b128 v[204:207], v72 offset:13856
	ds_read_b128 v[208:211], v72 offset:13888
	ds_read_b128 v[212:215], v72 offset:13920
	ds_read2_b64 v[216:219], v73 offset0:24 offset1:26
	ds_read2_b64 v[220:223], v74 offset0:56 offset1:58
	ds_read2_b64 v[224:227], v73 offset0:28 offset1:30
	ds_read2_b64 v[228:231], v74 offset0:60 offset1:62
	s_waitcnt lgkmcnt(7)
	v_mfma_f32_32x32x16_bf16 v[32:47], v[200:203], v[80:83], 0
	s_waitcnt lgkmcnt(6)
	v_mfma_f32_32x32x16_bf16 v[32:47], v[204:207], v[84:87], v[32:47]
	s_waitcnt lgkmcnt(5)
	v_mfma_f32_32x32x16_bf16 v[32:47], v[208:211], v[88:91], v[32:47]
	s_waitcnt lgkmcnt(4)
	v_mfma_f32_32x32x16_bf16 v[32:47], v[212:215], v[92:95], v[32:47]
	s_nop 7
	s_nop 3
	v_cmp_le_i32_e64 s[0:1], 0, v250
	v_cmp_le_i32_e64 s[4:5], 1, v250
	v_exp_f32_e32 v32, v32
	v_exp_f32_e32 v33, v33
	v_cmp_le_i32_e64 s[6:7], 2, v250
	v_cmp_le_i32_e64 s[48:49], 3, v250
	v_exp_f32_e32 v34, v34
	v_exp_f32_e32 v35, v35
	v_cndmask_b32_e64 v32, v32, 0, s[0:1]
	v_cndmask_b32_e64 v33, v33, 0, s[4:5]
	v_mov_b32_e32 v232, v32
	v_mov_b32_e32 v233, v33
	v_cvt_pk_bf16_f32 v64, v32, v33
	v_cmp_le_i32_e64 s[0:1], 8, v250
	v_cmp_le_i32_e64 s[4:5], 9, v250
	v_exp_f32_e32 v36, v36
	v_exp_f32_e32 v37, v37
	v_cndmask_b32_e64 v34, v34, 0, s[6:7]
	v_cndmask_b32_e64 v35, v35, 0, s[48:49]
	v_add_f32_e32 v232, v232, v34
	v_add_f32_e32 v233, v233, v35
	v_cvt_pk_bf16_f32 v65, v34, v35
	v_cmp_le_i32_e64 s[6:7], 10, v250
	v_cmp_le_i32_e64 s[48:49], 11, v250
	v_exp_f32_e32 v38, v38
	v_exp_f32_e32 v39, v39
	v_cndmask_b32_e64 v36, v36, 0, s[0:1]
	v_cndmask_b32_e64 v37, v37, 0, s[4:5]
	v_add_f32_e32 v232, v232, v36
	v_add_f32_e32 v233, v233, v37
	v_cvt_pk_bf16_f32 v66, v36, v37
	v_cndmask_b32_e64 v38, v38, 0, s[6:7]
	v_cndmask_b32_e64 v39, v39, 0, s[48:49]
	v_add_f32_e32 v232, v232, v38
	v_add_f32_e32 v233, v233, v39
	v_cvt_pk_bf16_f32 v67, v38, v39
	v_cmp_le_i32_e64 s[0:1], 16, v250
	v_cmp_le_i32_e64 s[4:5], 17, v250
	v_exp_f32_e32 v40, v40
	v_exp_f32_e32 v41, v41
	v_cmp_le_i32_e64 s[6:7], 18, v250
	v_cmp_le_i32_e64 s[48:49], 19, v250
	v_exp_f32_e32 v42, v42
	v_exp_f32_e32 v43, v43
	v_cndmask_b32_e64 v40, v40, 0, s[0:1]
	v_cndmask_b32_e64 v41, v41, 0, s[4:5]
	v_add_f32_e32 v232, v232, v40
	v_add_f32_e32 v233, v233, v41
	v_cvt_pk_bf16_f32 v68, v40, v41
	s_waitcnt lgkmcnt(3)
	v_mfma_f32_32x32x16_bf16 v[0:15], v[216:219], v[64:67], v[0:15]
	v_cmp_le_i32_e64 s[0:1], 24, v250
	v_cmp_le_i32_e64 s[4:5], 25, v250
	v_exp_f32_e32 v44, v44
	v_exp_f32_e32 v45, v45
	v_cndmask_b32_e64 v42, v42, 0, s[6:7]
	v_cndmask_b32_e64 v43, v43, 0, s[48:49]
	v_add_f32_e32 v232, v232, v42
	v_add_f32_e32 v233, v233, v43
	v_cvt_pk_bf16_f32 v69, v42, v43
	s_waitcnt lgkmcnt(2)
	v_mfma_f32_32x32x16_bf16 v[16:31], v[220:223], v[64:67], v[16:31]
	v_cmp_le_i32_e64 s[6:7], 26, v250
	v_cmp_le_i32_e64 s[48:49], 27, v250
	v_exp_f32_e32 v46, v46
	v_exp_f32_e32 v47, v47
	v_cndmask_b32_e64 v44, v44, 0, s[0:1]
	v_cndmask_b32_e64 v45, v45, 0, s[4:5]
	v_add_f32_e32 v232, v232, v44
	v_add_f32_e32 v233, v233, v45
	v_cvt_pk_bf16_f32 v70, v44, v45
	v_cndmask_b32_e64 v46, v46, 0, s[6:7]
	v_cndmask_b32_e64 v47, v47, 0, s[48:49]
	v_add_f32_e32 v232, v232, v46
	v_add_f32_e32 v233, v233, v47
	v_cvt_pk_bf16_f32 v71, v46, v47
	s_nop 1
	s_waitcnt lgkmcnt(1)
	v_mfma_f32_32x32x16_bf16 v[0:15], v[224:227], v[68:71], v[0:15]
	s_waitcnt lgkmcnt(0)
	v_mfma_f32_32x32x16_bf16 v[16:31], v[228:231], v[68:71], v[16:31]
	v_add_f32_e32 v232, v232, v233
	v_add_f32_e32 v112, v112, v232
	s_branch .Lt1_join
; __device__ __forceinline__ void phase4_attn(const Args& a, LAS unsigned char* lds) {
;     ...
;                     if (i == n_sel - 1 || i == n_all - 1) { const float lt = l_run + __shfl_xor(l_run, 32); const float sc = ((i == n_sel - 1) ? g1 : g2) / fmaxf(lt, 1e-20f);
;                         comb[hkv][0] += oacc[0] * sc; comb[hkv][1] += oacc[1] * sc; oacc[0] = zero16(); oacc[1] = zero16(); l_run = 0.f; }
;                     if (i + 1 < n_all) A_STAGE(bufo ^ 1);
;                     __syncthreads();
.Lt1_join:
	s_cmp_eq_u32 s89, s44
	s_cbranch_scc1 .Lt1_fin1
	s_cmp_eq_u32 s11, s44
	s_cbranch_scc1 .Lt1_fin2
.Lt1_stage:
	s_cmp_eq_u32 s45, 0
	s_cbranch_scc1 .Lt1_latch
	s_xor_b32 s0, s46, 1
	s_mul_i32 s1, s0, 0x4800
	s_mul_i32 s0, s0, 0x4200
	v_add_u32_e32 v251, s1, v246
	v_add_u32_e32 v252, s0, v247
	s_waitcnt vmcnt(3)
	ds_write_b128 v251, v[96:99]
	s_waitcnt vmcnt(2)
	ds_write_b128 v251, v[100:103] offset:9216
	s_waitcnt vmcnt(1)
	ds_write2_b64 v252, v[104:105], v[106:107] offset1:1
	s_waitcnt vmcnt(0)
	ds_write2_b64 v252, v[108:109], v[110:111] offset0:16 offset1:17
.Lt1_latch:
	s_add_i32 s44, s44, 1
	s_waitcnt lgkmcnt(0)
	s_barrier
	s_cmp_lg_u32 s44, s42
	s_cbranch_scc1 .Lt1_head
	s_branch .LBB0_794
.Lt1_fin1:
	v_mov_b32_e32 v76, v113
	s_branch .Lt1_fin
.Lt1_fin2:
	v_mov_b32_e32 v76, v114
.Lt1_fin:
	ds_bpermute_b32 v75, v193, v112
	s_waitcnt lgkmcnt(0)
	v_add_f32_e32 v75, v112, v75
	v_max_f32_e32 v75, 0x1e3ce508, v75
	v_div_scale_f32 v78, s[4:5], v75, v75, v76
	v_rcp_f32_e32 v79, v78
	v_div_scale_f32 v241, vcc, v76, v75, v76
	v_mov_b32_e32 v112, 0
	v_fma_f32 v242, -v78, v79, 1.0
	v_fmac_f32_e32 v79, v242, v79
	v_mul_f32_e32 v242, v241, v79
	v_fma_f32 v243, -v78, v242, v241
	v_fmac_f32_e32 v242, v243, v79
	v_fma_f32 v78, -v78, v242, v241
	v_div_fmas_f32 v78, v78, v79, v242
	v_div_fixup_f32 v76, v78, v75, v76
	v_pk_fma_f32 v[148:149], v[0:1], v[76:77], v[148:149] op_sel_hi:[1,0,1]
	v_pk_fma_f32 v[150:151], v[2:3], v[76:77], v[150:151] op_sel_hi:[1,0,1]
	v_pk_fma_f32 v[146:147], v[4:5], v[76:77], v[146:147] op_sel_hi:[1,0,1]
	v_pk_fma_f32 v[144:145], v[6:7], v[76:77], v[144:145] op_sel_hi:[1,0,1]
	v_pk_fma_f32 v[142:143], v[8:9], v[76:77], v[142:143] op_sel_hi:[1,0,1]
	v_pk_fma_f32 v[140:141], v[10:11], v[76:77], v[140:141] op_sel_hi:[1,0,1]
	v_pk_fma_f32 v[138:139], v[12:13], v[76:77], v[138:139] op_sel_hi:[1,0,1]
	v_pk_fma_f32 v[132:133], v[14:15], v[76:77], v[132:133] op_sel_hi:[1,0,1]
	v_pk_fma_f32 v[134:135], v[16:17], v[76:77], v[134:135] op_sel_hi:[1,0,1]
	v_pk_fma_f32 v[136:137], v[18:19], v[76:77], v[136:137] op_sel_hi:[1,0,1]
	v_pk_fma_f32 v[130:131], v[20:21], v[76:77], v[130:131] op_sel_hi:[1,0,1]
	v_pk_fma_f32 v[128:129], v[22:23], v[76:77], v[128:129] op_sel_hi:[1,0,1]
	v_pk_fma_f32 v[126:127], v[24:25], v[76:77], v[126:127] op_sel_hi:[1,0,1]
	v_pk_fma_f32 v[124:125], v[26:27], v[76:77], v[124:125] op_sel_hi:[1,0,1]
	v_pk_fma_f32 v[122:123], v[28:29], v[76:77], v[122:123] op_sel_hi:[1,0,1]
	v_pk_fma_f32 v[120:121], v[30:31], v[76:77], v[120:121] op_sel_hi:[1,0,1]
	v_mov_b32_e32 v0, 0
	v_mov_b32_e32 v1, 0
	v_mov_b32_e32 v2, 0
	v_mov_b32_e32 v3, 0
	v_mov_b32_e32 v4, 0
	v_mov_b32_e32 v5, 0
	v_mov_b32_e32 v6, 0
	v_mov_b32_e32 v7, 0
	v_mov_b32_e32 v8, 0
	v_mov_b32_e32 v9, 0
	v_mov_b32_e32 v10, 0
	v_mov_b32_e32 v11, 0
	v_mov_b32_e32 v12, 0
	v_mov_b32_e32 v13, 0
	v_mov_b32_e32 v14, 0
	v_mov_b32_e32 v15, 0
	v_mov_b32_e32 v16, 0
	v_mov_b32_e32 v17, 0
	v_mov_b32_e32 v18, 0
	v_mov_b32_e32 v19, 0
	v_mov_b32_e32 v20, 0
	v_mov_b32_e32 v21, 0
	v_mov_b32_e32 v22, 0
	v_mov_b32_e32 v23, 0
	v_mov_b32_e32 v24, 0
	v_mov_b32_e32 v25, 0
	v_mov_b32_e32 v26, 0
	v_mov_b32_e32 v27, 0
	v_mov_b32_e32 v28, 0
	v_mov_b32_e32 v29, 0
	v_mov_b32_e32 v30, 0
	v_mov_b32_e32 v31, 0
	s_branch .Lt1_stage

; #define LAS __attribute__((address_space(3)))
; __device__ __forceinline__ void phase4_attn(const Args& a, LAS unsigned char* lds) {
;     ...
; #pragma unroll 1
;                 for (int i = 0; i < n_all; ++i) {
;                     const int bufo = i & 1;
;                     if (i + 1 < n_all) A_ISSUE(i + 1);
;                     const LAS unsigned char* Kb = lds + A_KBUF + bufo * A_KT; const LAS unsigned char* Vb = lds + A_VBUF + bufo * A_VT;
;                     const bool issel = i < n_sel;
;                     const int st = issel ? i : wlo + (i - n_sel);
;                     const int dlt = 64 * t + ql - 128 * st - 4 * h;
;                     if (issel) {
;                         const bool b0 = (selw >> (2 * st)) & 1u, b1 = (selw >> (2 * st + 1)) & 1u;
;                         if (__ballot(b0 || b1) != 0ull) {
;                             if (2 * st + 1 < t) {
;                                 if (__ballot(b0 && b1) == ~0ull) attn_tile<2>(Kb, Vb, qf, oacc, l_run, r, h, dlt, dlt, (w & 4) != 0);
;                                 else attn_tile<3>(Kb, Vb, qf, oacc, l_run, r, h, __float_as_int(b0 ? 0.f : -1e30f), __float_as_int(b1 ? 0.f : -1e30f), (w & 4) != 0);
;                             } else attn_tile<0>(Kb, Vb, qf, oacc, l_run, r, h, b0 ? dlt : -1, b1 ? dlt : -1, (w & 4) != 0);
;                         }
;                     } else {
;                         if (2 * st > t - 8 && 2 * st + 1 < t) attn_tile<2>(Kb, Vb, qf, oacc, l_run, r, h, dlt, dlt, (w & 4) != 0);
;                         else attn_tile<1>(Kb, Vb, qf, oacc, l_run, r, h, dlt, dlt, (w & 4) != 0);
.LBB0_806:
	v_add_u32_e32 v244, v118, v153
	v_add_u32_e32 v245, v196, v197
	v_add_u32_e32 v245, 0x9000, v245
	v_ashrrev_i32_e32 v239, 3, v152
	v_lshlrev_b32_e32 v240, 4, v152
	v_and_b32_e32 v240, 0x70, v240
	v_mul_u32_u24_e32 v246, 0x90, v239
	v_add_u32_e32 v246, v246, v240
	v_mul_u32_u24_e32 v247, 0x108, v239
	v_add_u32_e32 v247, v247, v240
	v_add_u32_e32 v247, 0x9000, v247
	v_lshlrev_b32_e32 v248, 4, v152
	v_add_u32_e32 v249, 0x2000, v248
	v_and_b32_e32 v250, 31, v152
	v_sub_u32_e32 v250, v250, v195
	v_readfirstlane_b32 s50, v152
	s_bfe_u32 s50, s50, 0x10006
	s_lshl_b32 s0, s38, 1
	s_add_i32 s50, s50, s0
.Lt2_head:
	s_add_i32 s6, s44, 1
	s_add_i32 s7, s91, s44
	s_cmp_lt_i32 s44, s90
	s_cselect_b32 s45, 1, 0
	s_cbranch_scc0 .Lt2_noissue
	s_cmp_lt_u32 s44, s89
	s_cselect_b32 s0, s71, s75
	s_cselect_b32 s1, s72, s76
	s_cselect_b32 s4, s73, s77
	s_cselect_b32 s5, s74, s78
	s_cselect_b32 s6, s6, s7
	s_ashr_i32 s7, s6, 31
	s_lshl_b64 s[6:7], s[6:7], 14
	s_add_u32 s6, s6, s60
	s_addc_u32 s7, s7, s61
	s_add_u32 s0, s0, s6
	s_addc_u32 s1, s1, s7
	s_add_u32 s4, s4, s6
	s_addc_u32 s5, s5, s7
	global_load_dwordx4 v[96:99], v248, s[0:1]
	global_load_dwordx4 v[100:103], v249, s[0:1]
	global_load_dwordx4 v[104:107], v248, s[4:5]
	global_load_dwordx4 v[108:111], v249, s[4:5]
.Lt2_noissue:
	s_and_b32 s46, s44, 1
	s_mul_i32 s0, s46, 0x4800
	s_mul_i32 s1, s46, 0x4200
	v_add_u32_e32 v72, s0, v244
	v_add_u32_e32 v73, s1, v245
	v_add_u32_e32 v74, 0x2000, v73
	s_cmp_gt_u32 s44, s89
	s_cbranch_scc1 .Lt2_win
	s_lshl_b32 s0, s44, 2
	s_sub_i32 s49, s50, s0
	s_lshl_b32 s4, s44, 1
	v_lshrrev_b32_e32 v238, s4, v198
	v_and_b32_e32 v238, 3, v238
	v_cmp_ne_u32_e32 vcc, 0, v238
	s_cmp_eq_u64 vcc, 0
	s_cbranch_scc1 .Lt2_join
	s_cmp_le_i32 s49, 3
	s_cbranch_scc1 .Lt2_diag
	v_cmp_eq_u32_e32 vcc, 3, v238
	s_cmp_eq_u64 vcc, -1
	s_cbranch_scc1 .Lt2_full
	s_mov_b32 s49, s4
	s_branch .Lt2_bias

; #define LAS __attribute__((address_space(3)))
; #define MFMA32(a, b, c) __builtin_amdgcn_mfma_f32_32x32x16_bf16((a), (b), (c), 0, 0, 0)
; __device__ __forceinline__ float ex2(float x) { return __builtin_amdgcn_exp2f(x); }
; template <int MODE>
; __device__ __forceinline__ void attn_tile(const LAS unsigned char* Kb, const LAS unsigned char* Vb, const bf16x8_t (&qf)[4], f32x16 (&oacc)[2], float& l_run,
;                                           int r, int h, int dlt0, int dlt1, bool hiw) {
;     ...
;     for (int mt = 0; mt < 4; ++mt) {
;         if (mt == 0) { if (hiw) __builtin_amdgcn_s_setprio(1); else __builtin_amdgcn_s_setprio(0); }
;         if (mt == 2) { if (hiw) __builtin_amdgcn_s_setprio(0); else __builtin_amdgcn_s_setprio(1); }
;         const int dl = mt < 2 ? dlt0 : dlt1;
;         f32x16 sacc = zero16();
; #pragma unroll
;         for (int ks = 0; ks < 4; ++ks) { const bf16x8_t ka = *(const LAS bf16x8_t*)(Kb + (32 * mt + r) * A_KSTR + 32 * ks + 16 * h); sacc = MFMA32(ka, qf[ks], sacc); }
; #pragma unroll
;         for (int i = 0; i < 16; ++i) {
;             float p;
;             if (MODE == 2) p = ex2(sacc[i]);
;             else if (MODE == 3) p = ex2(sacc[i] + __int_as_float(dl));
;             else { const int ci = 32 * mt + (i & 3) + 8 * (i >> 2); p = ((unsigned)(dl - ci) < ulim) ? ex2(sacc[i]) : 0.f; }
;             sacc[i] = p; ls += p;
;         }
; #pragma unroll
;         for (int s = 0; s < 2; ++s) {
;             const bf16x8_t pf = pack8(sacc, 8 * s);
; #pragma unroll
;             for (int dt = 0; dt < 2; ++dt) {
;                 const LAS unsigned char* vp = Vb + (32 * dt + r) * A_CVSTR + (32 * mt + 16 * s + 4 * h) * 2;
;                 const s16x4_t lo = *(const LAS s16x4_t*)vp, hi = *(const LAS s16x4_t*)(vp + 16);
;                 oacc[dt] = MFMA32(__builtin_shufflevector(lo, hi, 0, 1, 2, 3, 4, 5, 6, 7), pf, oacc[dt]);
;             }
;         }
;     }
;     l_run += ls;
; __device__ __forceinline__ void phase4_attn(const Args& a, LAS unsigned char* lds) {
;     ...
;                                 else attn_tile<3>(Kb, Vb, qf, oacc, l_run, r, h, __float_as_int(b0 ? 0.f : -1e30f), __float_as_int(b1 ? 0.f : -1e30f), (w & 4) != 0);
.Lt2_bias:
	ds_read_b128 v[200:203], v72 offset:0
	ds_read_b128 v[204:207], v72 offset:32
	ds_read_b128 v[208:211], v72 offset:64
	ds_read_b128 v[212:215], v72 offset:96
	ds_read2_b64 v[216:219], v73 offset0:0 offset1:2
	ds_read2_b64 v[220:223], v74 offset0:32 offset1:34
	ds_read2_b64 v[224:227], v73 offset0:4 offset1:6
	ds_read2_b64 v[228:231], v74 offset0:36 offset1:38
	v_bfe_i32 v236, v198, s49, 1
	s_add_i32 s49, s49, 1
	v_bfe_i32 v237, v198, s49, 1
	s_waitcnt lgkmcnt(7)
	v_mfma_f32_32x32x16_bf16 v[32:47], v[200:203], v[80:83], 0
	ds_read_b128 v[200:203], v72 offset:4608
	s_waitcnt lgkmcnt(7)
	v_mfma_f32_32x32x16_bf16 v[32:47], v[204:207], v[84:87], v[32:47]
	ds_read_b128 v[204:207], v72 offset:4640
	s_waitcnt lgkmcnt(7)
	v_mfma_f32_32x32x16_bf16 v[32:47], v[208:211], v[88:91], v[32:47]
	ds_read_b128 v[208:211], v72 offset:4672
	s_waitcnt lgkmcnt(7)
	v_mfma_f32_32x32x16_bf16 v[32:47], v[212:215], v[92:95], v[32:47]
	ds_read_b128 v[212:215], v72 offset:4704
	s_nop 7
	s_nop 3
	s_waitcnt lgkmcnt(3)
	v_mfma_f32_32x32x16_bf16 v[48:63], v[200:203], v[80:83], 0
	ds_read_b128 v[200:203], v72 offset:9216
	v_exp_f32_e32 v32, v32
	v_exp_f32_e32 v33, v33
	s_waitcnt lgkmcnt(3)
	v_mfma_f32_32x32x16_bf16 v[48:63], v[204:207], v[84:87], v[48:63]
	ds_read_b128 v[204:207], v72 offset:9248
	v_exp_f32_e32 v34, v34
	v_exp_f32_e32 v35, v35
	v_mov_b32_e32 v232, v32
	v_mov_b32_e32 v233, v33
	v_cvt_pk_bf16_f32 v64, v32, v33
	v_and_b32_e32 v64, v236, v64
	v_exp_f32_e32 v36, v36
	v_exp_f32_e32 v37, v37
	v_add_f32_e32 v232, v232, v34
	v_add_f32_e32 v233, v233, v35
	v_cvt_pk_bf16_f32 v65, v34, v35
	v_and_b32_e32 v65, v236, v65
	v_exp_f32_e32 v38, v38
	v_exp_f32_e32 v39, v39
	v_add_f32_e32 v232, v232, v36
	v_add_f32_e32 v233, v233, v37
	v_cvt_pk_bf16_f32 v66, v36, v37
	v_and_b32_e32 v66, v236, v66
	v_add_f32_e32 v232, v232, v38
	v_add_f32_e32 v233, v233, v39
	v_cvt_pk_bf16_f32 v67, v38, v39
	v_and_b32_e32 v67, v236, v67
	s_waitcnt lgkmcnt(3)
	v_mfma_f32_32x32x16_bf16 v[48:63], v[208:211], v[88:91], v[48:63]
	ds_read_b128 v[208:211], v72 offset:9280
	v_exp_f32_e32 v40, v40
	v_exp_f32_e32 v41, v41
	s_waitcnt lgkmcnt(3)
	v_mfma_f32_32x32x16_bf16 v[48:63], v[212:215], v[92:95], v[48:63]
	ds_read_b128 v[212:215], v72 offset:9312
	v_exp_f32_e32 v42, v42
	v_exp_f32_e32 v43, v43
	v_add_f32_e32 v232, v232, v40
	v_add_f32_e32 v233, v233, v41
	v_cvt_pk_bf16_f32 v68, v40, v41
	v_and_b32_e32 v68, v236, v68
	s_waitcnt lgkmcnt(11)
	v_mfma_f32_32x32x16_bf16 v[0:15], v[216:219], v[64:67], v[0:15]
	ds_read2_b64 v[216:219], v73 offset0:8 offset1:10
	v_exp_f32_e32 v44, v44
	v_exp_f32_e32 v45, v45
	v_add_f32_e32 v232, v232, v42
	v_add_f32_e32 v233, v233, v43
	v_cvt_pk_bf16_f32 v69, v42, v43
	v_and_b32_e32 v69, v236, v69
	s_waitcnt lgkmcnt(11)
	v_mfma_f32_32x32x16_bf16 v[16:31], v[220:223], v[64:67], v[16:31]
	ds_read2_b64 v[220:223], v74 offset0:40 offset1:42
	v_exp_f32_e32 v46, v46
	v_exp_f32_e32 v47, v47
	v_add_f32_e32 v232, v232, v44
	v_add_f32_e32 v233, v233, v45
	v_cvt_pk_bf16_f32 v70, v44, v45
	v_and_b32_e32 v70, v236, v70
	v_add_f32_e32 v232, v232, v46
	v_add_f32_e32 v233, v233, v47
	v_cvt_pk_bf16_f32 v71, v46, v47
	v_and_b32_e32 v71, v236, v71
	s_waitcnt lgkmcnt(5)
	v_mfma_f32_32x32x16_bf16 v[32:47], v[200:203], v[80:83], 0
	ds_read_b128 v[200:203], v72 offset:13824
	v_exp_f32_e32 v48, v48
	v_exp_f32_e32 v49, v49
	s_waitcnt lgkmcnt(5)
	v_mfma_f32_32x32x16_bf16 v[32:47], v[204:207], v[84:87], v[32:47]
	ds_read_b128 v[204:207], v72 offset:13856
	v_exp_f32_e32 v50, v50
	v_exp_f32_e32 v51, v51
	v_add_f32_e32 v232, v232, v48
	v_add_f32_e32 v233, v233, v49
	v_cvt_pk_bf16_f32 v64, v48, v49
	v_and_b32_e32 v64, v236, v64
	s_waitcnt lgkmcnt(13)
	v_mfma_f32_32x32x16_bf16 v[0:15], v[224:227], v[68:71], v[0:15]
	ds_read2_b64 v[224:227], v73 offset0:12 offset1:14
	v_exp_f32_e32 v52, v52
	v_exp_f32_e32 v53, v53
	v_add_f32_e32 v232, v232, v50
	v_add_f32_e32 v233, v233, v51
	v_cvt_pk_bf16_f32 v65, v50, v51
	v_and_b32_e32 v65, v236, v65
	s_waitcnt lgkmcnt(13)
	v_mfma_f32_32x32x16_bf16 v[16:31], v[228:231], v[68:71], v[16:31]
	ds_read2_b64 v[228:231], v74 offset0:44 offset1:46
	v_exp_f32_e32 v54, v54
	v_exp_f32_e32 v55, v55
	v_add_f32_e32 v232, v232, v52
	v_add_f32_e32 v233, v233, v53
	v_cvt_pk_bf16_f32 v66, v52, v53
	v_and_b32_e32 v66, v236, v66
	v_add_f32_e32 v232, v232, v54
	v_add_f32_e32 v233, v233, v55
	v_cvt_pk_bf16_f32 v67, v54, v55
	v_and_b32_e32 v67, v236, v67
	s_waitcnt lgkmcnt(7)
	v_mfma_f32_32x32x16_bf16 v[32:47], v[208:211], v[88:91], v[32:47]
	ds_read_b128 v[208:211], v72 offset:13888
	v_exp_f32_e32 v56, v56
	v_exp_f32_e32 v57, v57
	s_waitcnt lgkmcnt(7)
	v_mfma_f32_32x32x16_bf16 v[32:47], v[212:215], v[92:95], v[32:47]
	ds_read_b128 v[212:215], v72 offset:13920
	v_exp_f32_e32 v58, v58
	v_exp_f32_e32 v59, v59
	v_add_f32_e32 v232, v232, v56
	v_add_f32_e32 v233, v233, v57
	v_cvt_pk_bf16_f32 v68, v56, v57
	v_and_b32_e32 v68, v236, v68
	s_waitcnt lgkmcnt(7)
	v_mfma_f32_32x32x16_bf16 v[0:15], v[216:219], v[64:67], v[0:15]
	ds_read2_b64 v[216:219], v73 offset0:16 offset1:18
	v_exp_f32_e32 v60, v60
	v_exp_f32_e32 v61, v61
	v_add_f32_e32 v232, v232, v58
	v_add_f32_e32 v233, v233, v59
	v_cvt_pk_bf16_f32 v69, v58, v59
	v_and_b32_e32 v69, v236, v69
	s_waitcnt lgkmcnt(7)
; #define LAS __attribute__((address_space(3)))
; #define MFMA32(a, b, c) __builtin_amdgcn_mfma_f32_32x32x16_bf16((a), (b), (c), 0, 0, 0)
; __device__ __forceinline__ float ex2(float x) { return __builtin_amdgcn_exp2f(x); }
; template <int MODE>
; __device__ __forceinline__ void attn_tile(const LAS unsigned char* Kb, const LAS unsigned char* Vb, const bf16x8_t (&qf)[4], f32x16 (&oacc)[2], float& l_run,
;                                           int r, int h, int dlt0, int dlt1, bool hiw) {
;     ...
;     for (int mt = 0; mt < 4; ++mt) {
;         if (mt == 0) { if (hiw) __builtin_amdgcn_s_setprio(1); else __builtin_amdgcn_s_setprio(0); }
;         if (mt == 2) { if (hiw) __builtin_amdgcn_s_setprio(0); else __builtin_amdgcn_s_setprio(1); }
;         const int dl = mt < 2 ? dlt0 : dlt1;
;         f32x16 sacc = zero16();
; #pragma unroll
;         for (int ks = 0; ks < 4; ++ks) { const bf16x8_t ka = *(const LAS bf16x8_t*)(Kb + (32 * mt + r) * A_KSTR + 32 * ks + 16 * h); sacc = MFMA32(ka, qf[ks], sacc); }
; #pragma unroll
;         for (int i = 0; i < 16; ++i) {
;             float p;
;             if (MODE == 2) p = ex2(sacc[i]);
;             else if (MODE == 3) p = ex2(sacc[i] + __int_as_float(dl));
;             else { const int ci = 32 * mt + (i & 3) + 8 * (i >> 2); p = ((unsigned)(dl - ci) < ulim) ? ex2(sacc[i]) : 0.f; }
;             sacc[i] = p; ls += p;
;         }
; #pragma unroll
;         for (int s = 0; s < 2; ++s) {
;             const bf16x8_t pf = pack8(sacc, 8 * s);
; #pragma unroll
;             for (int dt = 0; dt < 2; ++dt) {
;                 const LAS unsigned char* vp = Vb + (32 * dt + r) * A_CVSTR + (32 * mt + 16 * s + 4 * h) * 2;
;                 const s16x4_t lo = *(const LAS s16x4_t*)vp, hi = *(const LAS s16x4_t*)(vp + 16);
;                 oacc[dt] = MFMA32(__builtin_shufflevector(lo, hi, 0, 1, 2, 3, 4, 5, 6, 7), pf, oacc[dt]);
;             }
;         }
;     }
;     l_run += ls;
	v_mfma_f32_32x32x16_bf16 v[16:31], v[220:223], v[64:67], v[16:31]
	ds_read2_b64 v[220:223], v74 offset0:48 offset1:50
	v_exp_f32_e32 v62, v62
	v_exp_f32_e32 v63, v63
	v_add_f32_e32 v232, v232, v60
	v_add_f32_e32 v233, v233, v61
	v_cvt_pk_bf16_f32 v70, v60, v61
	v_and_b32_e32 v70, v236, v70
	v_add_f32_e32 v232, v232, v62
	v_add_f32_e32 v233, v233, v63
	v_cvt_pk_bf16_f32 v71, v62, v63
	v_and_b32_e32 v71, v236, v71
	s_waitcnt lgkmcnt(7)
	v_mfma_f32_32x32x16_bf16 v[48:63], v[200:203], v[80:83], 0
	v_exp_f32_e32 v32, v32
	v_exp_f32_e32 v33, v33
	s_waitcnt lgkmcnt(6)
	v_mfma_f32_32x32x16_bf16 v[48:63], v[204:207], v[84:87], v[48:63]
	v_exp_f32_e32 v34, v34
	v_exp_f32_e32 v35, v35
	v_mov_b32_e32 v234, v32
	v_mov_b32_e32 v235, v33
	v_cvt_pk_bf16_f32 v64, v32, v33
	v_and_b32_e32 v64, v237, v64
	s_waitcnt lgkmcnt(5)
	v_mfma_f32_32x32x16_bf16 v[0:15], v[224:227], v[68:71], v[0:15]
	ds_read2_b64 v[224:227], v73 offset0:20 offset1:22
	v_exp_f32_e32 v36, v36
	v_exp_f32_e32 v37, v37
	v_add_f32_e32 v234, v234, v34
	v_add_f32_e32 v235, v235, v35
	v_cvt_pk_bf16_f32 v65, v34, v35
	v_and_b32_e32 v65, v237, v65
	s_waitcnt lgkmcnt(5)
	v_mfma_f32_32x32x16_bf16 v[16:31], v[228:231], v[68:71], v[16:31]
	ds_read2_b64 v[228:231], v74 offset0:52 offset1:54
	v_exp_f32_e32 v38, v38
	v_exp_f32_e32 v39, v39
	v_add_f32_e32 v234, v234, v36
	v_add_f32_e32 v235, v235, v37
	v_cvt_pk_bf16_f32 v66, v36, v37
	v_and_b32_e32 v66, v237, v66
	v_add_f32_e32 v234, v234, v38
	v_add_f32_e32 v235, v235, v39
	v_cvt_pk_bf16_f32 v67, v38, v39
	v_and_b32_e32 v67, v237, v67
	s_waitcnt lgkmcnt(5)
	v_mfma_f32_32x32x16_bf16 v[48:63], v[208:211], v[88:91], v[48:63]
	v_exp_f32_e32 v40, v40
	v_exp_f32_e32 v41, v41
	s_waitcnt lgkmcnt(4)
	v_mfma_f32_32x32x16_bf16 v[48:63], v[212:215], v[92:95], v[48:63]
	v_exp_f32_e32 v42, v42
	v_exp_f32_e32 v43, v43
	v_add_f32_e32 v234, v234, v40
	v_add_f32_e32 v235, v235, v41
	v_cvt_pk_bf16_f32 v68, v40, v41
	v_and_b32_e32 v68, v237, v68
	s_waitcnt lgkmcnt(3)
	v_mfma_f32_32x32x16_bf16 v[0:15], v[216:219], v[64:67], v[0:15]
	ds_read2_b64 v[216:219], v73 offset0:24 offset1:26
	v_exp_f32_e32 v44, v44
	v_exp_f32_e32 v45, v45
	v_add_f32_e32 v234, v234, v42
	v_add_f32_e32 v235, v235, v43
	v_cvt_pk_bf16_f32 v69, v42, v43
	v_and_b32_e32 v69, v237, v69
	s_waitcnt lgkmcnt(3)
	v_mfma_f32_32x32x16_bf16 v[16:31], v[220:223], v[64:67], v[16:31]
	ds_read2_b64 v[220:223], v74 offset0:56 offset1:58
	v_exp_f32_e32 v46, v46
	v_exp_f32_e32 v47, v47
	v_add_f32_e32 v234, v234, v44
	v_add_f32_e32 v235, v235, v45
	v_cvt_pk_bf16_f32 v70, v44, v45
	v_and_b32_e32 v70, v237, v70
	v_add_f32_e32 v234, v234, v46
	v_add_f32_e32 v235, v235, v47
	v_cvt_pk_bf16_f32 v71, v46, v47
	v_and_b32_e32 v71, v237, v71
	v_exp_f32_e32 v48, v48
	v_exp_f32_e32 v49, v49
	v_exp_f32_e32 v50, v50
	v_exp_f32_e32 v51, v51
	v_add_f32_e32 v234, v234, v48
	v_add_f32_e32 v235, v235, v49
	v_cvt_pk_bf16_f32 v64, v48, v49
	v_and_b32_e32 v64, v237, v64
	s_waitcnt lgkmcnt(3)
	v_mfma_f32_32x32x16_bf16 v[0:15], v[224:227], v[68:71], v[0:15]
	ds_read2_b64 v[224:227], v73 offset0:28 offset1:30
	v_exp_f32_e32 v52, v52
	v_exp_f32_e32 v53, v53
	v_add_f32_e32 v234, v234, v50
	v_add_f32_e32 v235, v235, v51
	v_cvt_pk_bf16_f32 v65, v50, v51
	v_and_b32_e32 v65, v237, v65
	s_waitcnt lgkmcnt(3)
	v_mfma_f32_32x32x16_bf16 v[16:31], v[228:231], v[68:71], v[16:31]
	ds_read2_b64 v[228:231], v74 offset0:60 offset1:62
	v_exp_f32_e32 v54, v54
	v_exp_f32_e32 v55, v55
	v_add_f32_e32 v234, v234, v52
	v_add_f32_e32 v235, v235, v53
	v_cvt_pk_bf16_f32 v66, v52, v53
	v_and_b32_e32 v66, v237, v66
	v_add_f32_e32 v234, v234, v54
	v_add_f32_e32 v235, v235, v55
	v_cvt_pk_bf16_f32 v67, v54, v55
	v_and_b32_e32 v67, v237, v67
	v_exp_f32_e32 v56, v56
	v_exp_f32_e32 v57, v57
	v_exp_f32_e32 v58, v58
	v_exp_f32_e32 v59, v59
	v_add_f32_e32 v234, v234, v56
	v_add_f32_e32 v235, v235, v57
	v_cvt_pk_bf16_f32 v68, v56, v57
	v_and_b32_e32 v68, v237, v68
	s_waitcnt lgkmcnt(3)
	v_mfma_f32_32x32x16_bf16 v[0:15], v[216:219], v[64:67], v[0:15]
	v_exp_f32_e32 v60, v60
	v_exp_f32_e32 v61, v61
	v_add_f32_e32 v234, v234, v58
	v_add_f32_e32 v235, v235, v59
	v_cvt_pk_bf16_f32 v69, v58, v59
	v_and_b32_e32 v69, v237, v69
	s_waitcnt lgkmcnt(2)
	v_mfma_f32_32x32x16_bf16 v[16:31], v[220:223], v[64:67], v[16:31]
	v_exp_f32_e32 v62, v62
	v_exp_f32_e32 v63, v63
	v_add_f32_e32 v234, v234, v60
	v_add_f32_e32 v235, v235, v61
	v_cvt_pk_bf16_f32 v70, v60, v61
	v_and_b32_e32 v70, v237, v70
	v_add_f32_e32 v234, v234, v62
	v_add_f32_e32 v235, v235, v63
	v_cvt_pk_bf16_f32 v71, v62, v63
	v_and_b32_e32 v71, v237, v71
	s_nop 1
	s_waitcnt lgkmcnt(1)
	v_mfma_f32_32x32x16_bf16 v[0:15], v[224:227], v[68:71], v[0:15]
	s_waitcnt lgkmcnt(0)
	v_mfma_f32_32x32x16_bf16 v[16:31], v[228:231], v[68:71], v[16:31]
	v_add_f32_e32 v232, v232, v233
	v_add_f32_e32 v234, v234, v235
	v_and_b32_e32 v239, 1.0, v236
	v_and_b32_e32 v240, 1.0, v237
	v_fmac_f32_e32 v112, v232, v239
	v_fmac_f32_e32 v112, v234, v240
	s_branch .Lt2_join

; __device__ __forceinline__ void phase4_attn(const Args& a, LAS unsigned char* lds) {
;     ...
;                     __syncthreads();
;                 }
.Lt2_latch:
	s_add_i32 s44, s44, 1
	s_waitcnt lgkmcnt(0)
	s_barrier
	s_cmp_lg_u32 s44, s30
	s_cbranch_scc1 .Lt2_head
	s_branch .LBB0_873

; __device__ __forceinline__ void phase4_attn(const Args& a, LAS unsigned char* lds) {
;     ...
;                     if (i == n_sel - 1 || i == n_all - 1) { const float lt = l_run + __shfl_xor(l_run, 32); const float sc = ((i == n_sel - 1) ? g1 : g2) / fmaxf(lt, 1e-20f);
;                         comb[hkv][0] += oacc[0] * sc; comb[hkv][1] += oacc[1] * sc; oacc[0] = zero16(); oacc[1] = zero16(); l_run = 0.f; }
.Lt2_fin:
	ds_bpermute_b32 v75, v193, v112
	s_waitcnt lgkmcnt(0)
	v_add_f32_e32 v75, v112, v75
	v_max_f32_e32 v75, 0x1e3ce508, v75
	v_div_scale_f32 v78, s[4:5], v75, v75, v76
	v_rcp_f32_e32 v79, v78
	v_div_scale_f32 v241, vcc, v76, v75, v76
	v_mov_b32_e32 v112, 0
	v_fma_f32 v242, -v78, v79, 1.0
	v_fmac_f32_e32 v79, v242, v79
	v_mul_f32_e32 v242, v241, v79
	v_fma_f32 v243, -v78, v242, v241
	v_fmac_f32_e32 v242, v243, v79
	v_fma_f32 v78, -v78, v242, v241
	v_div_fmas_f32 v78, v78, v79, v242
	v_div_fixup_f32 v76, v78, v75, v76
	v_pk_fma_f32 v[182:183], v[0:1], v[76:77], v[182:183] op_sel_hi:[1,0,1]
	v_pk_fma_f32 v[186:187], v[2:3], v[76:77], v[186:187] op_sel_hi:[1,0,1]
	v_pk_fma_f32 v[180:181], v[4:5], v[76:77], v[180:181] op_sel_hi:[1,0,1]
	v_pk_fma_f32 v[178:179], v[6:7], v[76:77], v[178:179] op_sel_hi:[1,0,1]
	v_pk_fma_f32 v[176:177], v[8:9], v[76:77], v[176:177] op_sel_hi:[1,0,1]
	v_pk_fma_f32 v[174:175], v[10:11], v[76:77], v[174:175] op_sel_hi:[1,0,1]
	v_pk_fma_f32 v[172:173], v[12:13], v[76:77], v[172:173] op_sel_hi:[1,0,1]
	v_pk_fma_f32 v[166:167], v[14:15], v[76:77], v[166:167] op_sel_hi:[1,0,1]
	v_pk_fma_f32 v[168:169], v[16:17], v[76:77], v[168:169] op_sel_hi:[1,0,1]
	v_pk_fma_f32 v[170:171], v[18:19], v[76:77], v[170:171] op_sel_hi:[1,0,1]
	v_pk_fma_f32 v[164:165], v[20:21], v[76:77], v[164:165] op_sel_hi:[1,0,1]
	v_pk_fma_f32 v[162:163], v[22:23], v[76:77], v[162:163] op_sel_hi:[1,0,1]
	v_pk_fma_f32 v[160:161], v[24:25], v[76:77], v[160:161] op_sel_hi:[1,0,1]
	v_pk_fma_f32 v[158:159], v[26:27], v[76:77], v[158:159] op_sel_hi:[1,0,1]
	v_pk_fma_f32 v[156:157], v[28:29], v[76:77], v[156:157] op_sel_hi:[1,0,1]
	v_pk_fma_f32 v[154:155], v[30:31], v[76:77], v[154:155] op_sel_hi:[1,0,1]
	v_mov_b32_e32 v0, 0
	v_mov_b32_e32 v1, 0
	v_mov_b32_e32 v2, 0
	v_mov_b32_e32 v3, 0
	v_mov_b32_e32 v4, 0
	v_mov_b32_e32 v5, 0
	v_mov_b32_e32 v6, 0
	v_mov_b32_e32 v7, 0
	v_mov_b32_e32 v8, 0
	v_mov_b32_e32 v9, 0
	v_mov_b32_e32 v10, 0
	v_mov_b32_e32 v11, 0
	v_mov_b32_e32 v12, 0
	v_mov_b32_e32 v13, 0
	v_mov_b32_e32 v14, 0
	v_mov_b32_e32 v15, 0
	v_mov_b32_e32 v16, 0
	v_mov_b32_e32 v17, 0
	v_mov_b32_e32 v18, 0
	v_mov_b32_e32 v19, 0
	v_mov_b32_e32 v20, 0
	v_mov_b32_e32 v21, 0
	v_mov_b32_e32 v22, 0
	v_mov_b32_e32 v23, 0
	v_mov_b32_e32 v24, 0
	v_mov_b32_e32 v25, 0
	v_mov_b32_e32 v26, 0
	v_mov_b32_e32 v27, 0
	v_mov_b32_e32 v28, 0
	v_mov_b32_e32 v29, 0
	v_mov_b32_e32 v30, 0
	v_mov_b32_e32 v31, 0
	s_branch .Lt2_stage
